# GEMM K-loops: one static s_setprio 1 for waves 4-7 before the loop, per-MMA-block priority flips removed (asm guide 7.4)
# baseline (speedup 1.0000x reference)
; __device__ __forceinline__ void xcd_barrier(const XcdBarrier& b) {
;     asm volatile("s_waitcnt vmcnt(0)" ::: "memory");
;     __syncthreads();
;     if (threadIdx.x == 0) {
;         unsigned* bar = b.bar;
;         __builtin_amdgcn_s_waitcnt(0);
;         unsigned nloc = b.st[0], nx = b.st[1];
;         if (nloc == 0u) { xcd_barrier_complete(bar, b.x, nloc, nx); b.st[0] = nloc; b.st[1] = nx; }
.LBB9_81:
	s_cmp_gt_i32 s93, 1
	s_cselect_b64 s[0:1], -1, 0
	s_and_b64 s[2:3], s[4:5], s[0:1]
	s_andn2_b64 vcc, exec, s[2:3]
	s_cbranch_vccnz .LBB9_135
	s_waitcnt vmcnt(0)
	s_barrier
	s_setprio 0
	s_and_saveexec_b64 s[4:5], s[80:81]
	s_cbranch_execz .LBB9_134
	s_add_i32 s2, 0, 0x24000
	v_mov_b32_e32 v0, s2
	s_waitcnt vmcnt(0) expcnt(0) lgkmcnt(0)
	ds_read_b32 v2, v0
	s_add_i32 s2, 0, 0x24004
	v_mov_b32_e32 v0, s2
	ds_read_b32 v0, v0
	s_waitcnt lgkmcnt(1)
	v_cmp_ne_u32_e32 vcc, 0, v2
	s_cbranch_vccnz .LBB9_98
	s_add_u32 s8, s90, 0x1000
	s_addc_u32 s9, s91, 0
	s_add_u32 s10, s90, 0x1100
	s_addc_u32 s11, s91, 0
	s_add_u32 s12, s90, 0x1200
	s_addc_u32 s13, s91, 0
	s_mul_i32 s22, s95, s83
	s_add_u32 s16, s90, 0x1300
	s_mul_i32 s22, s22, s94
	s_addc_u32 s17, s91, 0
	s_mov_b32 s23, 1
	v_mov_b32_e32 v16, 0
	s_branch .LBB9_86

; #define PG8_STAGE(bufoff, gbase, voff) do { _Pragma("unroll") for (int _i = 0; _i < 2; ++_i) \
;         __builtin_amdgcn_global_load_lds((const unsigned*)((const char*)(gbase) + (voff)[_i]), (PG8_LAS unsigned*)(lds + (bufoff) + ldsw + _i * 8192), 16, 0, 0); } while (0)
; #define PG8_WAIT_V(n) asm volatile("s_waitcnt vmcnt(" #n ")" ::: "memory")
; #define PG8_BAR __builtin_amdgcn_s_barrier()
; template <class Epi, class Sched, bool ALIGN_EPI = false, bool SP2 = false>
; __device__ __forceinline__ void gemm_phase(PG8_LAS unsigned char* lds, const Gemm g, const Sched& S, const Epi& E) {
;     ...
;     const char* cA = PG8_UA(cur); const char* cB = PG8_UB(cur);
;     S.a_ready(cur);
;     if constexpr (SP2) {
;         PG8_STAGE(PG8_SB(0, 0), cB, voffB); PG8_STAGE(PG8_SB(0, 1), cB + hstep, voffB); PG8_STAGE(PG8_SA(0, 0), cA, voffA); PG8_STAGE(PG8_SA(0, 1), cA + hstep, voffA);
;         if (wr == 1) PG8_BAR;
;         PG8_WAIT_V(2); PG8_BAR;
;         PG8_STAGE(PG8_SB(1, 0), cB + kstep, voffB); PG8_STAGE(PG8_SA(1, 0), cA + kstep, voffA); PG8_STAGE(PG8_SB(1, 1), cB + hstep + kstep, voffB);
;         PG8_WAIT_V(6); PG8_BAR;
.LBB9_220:
	s_ashr_i32 s0, s3, 3
	s_add_u32 s42, s90, 0x2000000
	s_addc_u32 s43, s91, 0
	s_add_u32 s44, s90, 0x100000
	s_addc_u32 s45, s91, 0
	s_add_i32 s0, s4, s0
	s_ashr_i32 s4, s0, 31
	s_lshr_b32 s4, s4, 25
	s_add_i32 s4, s0, s4
	s_ashr_i32 s5, s4, 7
	s_and_b32 s4, s4, 0xffffff80
	s_sub_i32 s4, s0, s4
	s_bfe_i32 s0, s4, 0x80000
	v_lshlrev_b32_e32 v1, 1, v47
	s_bfe_u32 s0, s0, 0x3000c
	v_and_b32_e32 v1, 24, v1
	v_and_b32_e32 v2, 3, v47
	s_add_i32 s6, s4, s0
	v_and_b32_e32 v0, 32, v208
	s_waitcnt lgkmcnt(2)
	v_and_b32_e32 v10, 15, v47
	v_or3_b32 v1, v49, v2, v1
	v_lshrrev_b32_e32 v2, 3, v208
	s_movk_i32 s3, 0x70
	s_bfe_i32 s0, s6, 0x80000
	s_and_b32 s6, s6, 0xf8
	v_bitop3_b32 v8, v48, v0, 48 bitop3:0x6c
	v_and_b32_e32 v9, 64, v208
	v_and_or_b32 v3, v2, s3, v10
	s_movk_i32 s3, 0x60
	s_sub_i32 s4, s4, s6
	v_or_b32_e32 v0, v8, v9
	v_and_or_b32 v2, v2, s3, v1
	s_waitcnt lgkmcnt(1)
	v_add_u32_e32 v11, 0x2000, v48
	s_lshl_b32 s5, s5, 3
	s_sext_i32_i16 s0, s0
	s_sext_i32_i8 s4, s4
	s_lshr_b32 s1, s2, 6
	v_lshl_or_b32 v154, v2, 11, v0
	v_lshrrev_b32_e32 v2, 7, v11
	s_movk_i32 s3, 0xf0
	s_lshr_b32 s0, s0, 3
	s_add_i32 s30, s5, s4
	v_lshl_or_b32 v152, v3, 11, v0
	v_and_or_b32 v3, v2, s3, v10
	s_movk_i32 s3, 0xe0
	s_ashr_i32 s31, s30, 31
	s_bfe_i64 s[6:7], s[0:1], 0x100000
	v_and_or_b32 v1, v2, s3, v1
	s_lshr_b32 s3, s2, 8
	s_lshl_b32 s46, s1, 10
	s_lshl_b64 s[4:5], s[30:31], 19
	s_lshl_b64 s[6:7], s[6:7], 19
	s_add_u32 s36, s44, s6
	s_addc_u32 s37, s45, s7
	s_add_i32 s31, s46, 0
	s_add_i32 m0, s31, 0x10000
	v_lshl_or_b32 v158, v1, 11, v0
	global_load_lds_dwordx4 v154, s[36:37]
	s_add_i32 m0, s31, 0x12000
	s_add_u32 s6, s36, 0x40000
	global_load_lds_dwordx4 v158, s[36:37]
	s_addc_u32 s7, s37, 0
	s_add_i32 m0, s31, 0x14000
	v_lshl_or_b32 v156, v3, 11, v0
	global_load_lds_dwordx4 v154, s[6:7]
	s_add_i32 m0, s31, 0x16000
	s_add_u32 s34, s42, s4
	s_addc_u32 s35, s43, s5
	s_add_i32 s47, s31, 0x2000
	global_load_lds_dwordx4 v158, s[6:7]
	s_mov_b32 m0, s31
	s_add_u32 s4, s34, 0x40000
	global_load_lds_dwordx4 v152, s[34:35]
	s_mov_b32 m0, s47
	s_addc_u32 s5, s35, 0
	s_add_i32 s48, s31, 0x4000
	global_load_lds_dwordx4 v156, s[34:35]
	s_mov_b32 m0, s48
	s_add_i32 s49, s31, 0x6000
	global_load_lds_dwordx4 v152, s[4:5]
	s_mov_b32 m0, s49
	v_mov_b32_e32 v161, 0
	global_load_lds_dwordx4 v156, s[4:5]
	v_mov_b32_e32 v155, v161
	v_mov_b32_e32 v159, v161
	v_mov_b32_e32 v153, v161
	v_mov_b32_e32 v157, v161
	s_cmp_eq_u32 s3, 1
	s_mov_b32 s5, 0
	v_lshl_add_u64 v[6:7], s[36:37], 0, v[154:155]
	v_lshl_add_u64 v[4:5], s[36:37], 0, v[158:159]
	v_lshl_add_u64 v[0:1], s[34:35], 0, v[152:153]
	s_cselect_b64 s[6:7], -1, 0
	s_cmp_lg_u32 s3, 1
	v_lshl_add_u64 v[2:3], s[34:35], 0, v[156:157]
	s_cbranch_scc1 .LBB9_222
	s_barrier
	s_setprio 1

; #define PG8_STAGE(bufoff, gbase, voff) do { _Pragma("unroll") for (int _i = 0; _i < 2; ++_i) \
;         __builtin_amdgcn_global_load_lds((const unsigned*)((const char*)(gbase) + (voff)[_i]), (PG8_LAS unsigned*)(lds + (bufoff) + ldsw + _i * 8192), 16, 0, 0); } while (0)
; #define PG8_LDA(dst, b, h) do { _Pragma("unroll") for (int m = 0; m < 4; ++m) _Pragma("unroll") for (int k = 0; k < 2; ++k) dst[m][k] = *(const PG8_LAS bf16x8*)(lds + PG8_SA(b, h) + aoff + m * 2048 + k * 1024); } while (0)
; #define PG8_LDB(dst, b, h) do { _Pragma("unroll") for (int n = 0; n < 2; ++n) _Pragma("unroll") for (int k = 0; k < 2; ++k) dst[n][k] = *(const PG8_LAS bf16x8*)(lds + PG8_SB(b, h) + boff + n * 2048 + k * 1024); } while (0)
; #define PG8_MMA(ai, bj, At, Bt) do { __builtin_amdgcn_s_setprio(1); _Pragma("unroll") for (int m = 0; m < 4; ++m) _Pragma("unroll") for (int n = 0; n < 2; ++n) _Pragma("unroll") for (int k = 0; k < 2; ++k) \
;         acc[ai][bj][m][n] = __builtin_amdgcn_mfma_f32_16x16x32_bf16(Bt[n][k], At[m][k], acc[ai][bj][m][n], 0, 0, 0); __builtin_amdgcn_s_setprio(0); } while (0)
; #define PG8_BAR __builtin_amdgcn_s_barrier()
; template <class Epi, class Sched, bool ALIGN_EPI = false, bool SP2 = false>
; __device__ __forceinline__ void gemm_phase(PG8_LAS unsigned char* lds, const Gemm g, const Sched& S, const Epi& E) {
;     ...
;             if constexpr (SP2) {
;             PG8_LDB(B0, 0, 0); PG8_LDB(B1, 0, 1); PG8_SCHED; PG8_LDA(At, 0, 0); PG8_STAGE(PG8_SA(1, 1), a1 + hstep, voffA);
;             PG8_WAIT_V(8); PG8_WAIT_L(0); PG8_BAR; PG8_MMA(0, 0, At, B0); PG8_MMA(0, 1, At, B1); PG8_BAR; PG8_SCHED;
;             PG8_LDA(At, 0, 1); PG8_STAGE(PG8_SB(0, 0), b2, voffB); PG8_STAGE(PG8_SB(0, 1), b2 + hstep, voffB); PG8_STAGE(PG8_SA(0, 0), a2, voffA);
;             PG8_WAIT_V(8); PG8_WAIT_L(0); PG8_BAR; PG8_MMA(1, 0, At, B0); PG8_MMA(1, 1, At, B1); PG8_BAR; PG8_SCHED;
;             PG8_LDB(B0, 1, 0); PG8_LDB(B1, 1, 1); PG8_SCHED; PG8_LDA(At, 1, 0); PG8_STAGE(PG8_SA(0, 1), a2 + hstep, voffA);
;             PG8_WAIT_V(8); PG8_WAIT_L(0); PG8_BAR; PG8_MMA(0, 0, At, B0); PG8_MMA(0, 1, At, B1); PG8_BAR; PG8_SCHED;
;             PG8_LDA(At, 1, 1); PG8_STAGE(PG8_SB(1, 0), b3, voffB); PG8_STAGE(PG8_SB(1, 1), b3 + hstep, voffB); PG8_STAGE(PG8_SA(1, 0), a3, voffA);
;             PG8_WAIT_V(8); PG8_WAIT_L(0); PG8_BAR; PG8_MMA(1, 0, At, B0); PG8_MMA(1, 1, At, B1); PG8_BAR; PG8_SCHED;
.LBB9_232:
	ds_read_b128 v[128:131], v195
	ds_read_b128 v[132:135], v195 offset:1024
	ds_read_b128 v[136:139], v195 offset:2048
	ds_read_b128 v[140:143], v195 offset:3072
	ds_read_b128 v[144:147], v196
	ds_read_b128 v[148:151], v196 offset:1024
	ds_read_b128 v[176:179], v196 offset:2048
	ds_read_b128 v[202:205], v196 offset:3072
	s_add_u32 s36, s34, 0xfffc0080
	s_addc_u32 s37, s35, -1
	s_cmp_eq_u32 s66, 12
	s_cselect_b32 s39, s2, s37
	s_cselect_b32 s38, s3, s36
	s_cselect_b32 s37, s4, s65
	s_cselect_b32 s36, s23, s25
	v_lshl_add_u64 v[206:207], s[34:35], 0, v[164:165]
	s_add_i32 m0, s31, 0xc000
	ds_read_b128 v[210:213], v197
	ds_read_b128 v[214:217], v197 offset:1024
	ds_read_b128 v[218:221], v197 offset:2048
	ds_read_b128 v[222:225], v197 offset:3072
	ds_read_b128 v[226:229], v197 offset:4096
	ds_read_b128 v[230:233], v197 offset:5120
	ds_read_b128 v[234:237], v197 offset:6144
	ds_read_b128 v[238:241], v197 offset:7168
	global_load_lds_dwordx4 v[206:207], off
	v_lshl_add_u64 v[206:207], s[34:35], 0, v[166:167]
	s_add_i32 m0, s31, 0xe000
	s_nop 0
	global_load_lds_dwordx4 v[206:207], off
	s_waitcnt vmcnt(8)
	s_waitcnt lgkmcnt(0)
	s_barrier
	s_nop 0
	s_waitcnt lgkmcnt(0)
	v_mfma_f32_16x16x32_bf16 v[124:127], v[128:131], v[210:213], v[124:127]
	v_mfma_f32_16x16x32_bf16 v[120:123], v[136:139], v[210:213], v[120:123]
	v_mfma_f32_16x16x32_bf16 v[108:111], v[128:131], v[218:221], v[108:111]
	v_mfma_f32_16x16x32_bf16 v[104:107], v[136:139], v[218:221], v[104:107]
	v_mfma_f32_16x16x32_bf16 v[92:95], v[128:131], v[226:229], v[92:95]
	v_mfma_f32_16x16x32_bf16 v[88:91], v[136:139], v[226:229], v[88:91]
	v_mfma_f32_16x16x32_bf16 v[76:79], v[128:131], v[234:237], v[76:79]
	v_mfma_f32_16x16x32_bf16 v[72:75], v[136:139], v[234:237], v[72:75]
	v_mfma_f32_16x16x32_bf16 v[124:127], v[132:135], v[214:217], v[124:127]
	v_mfma_f32_16x16x32_bf16 v[120:123], v[140:143], v[214:217], v[120:123]
	v_mfma_f32_16x16x32_bf16 v[108:111], v[132:135], v[222:225], v[108:111]
	v_mfma_f32_16x16x32_bf16 v[104:107], v[140:143], v[222:225], v[104:107]
	v_mfma_f32_16x16x32_bf16 v[92:95], v[132:135], v[230:233], v[92:95]
	v_mfma_f32_16x16x32_bf16 v[88:91], v[140:143], v[230:233], v[88:91]
	v_mfma_f32_16x16x32_bf16 v[76:79], v[132:135], v[238:241], v[76:79]
	v_mfma_f32_16x16x32_bf16 v[72:75], v[140:143], v[238:241], v[72:75]
	s_nop 0
	s_nop 0
	v_mfma_f32_16x16x32_bf16 v[116:119], v[144:147], v[210:213], v[116:119]
	v_mfma_f32_16x16x32_bf16 v[112:115], v[176:179], v[210:213], v[112:115]
	v_mfma_f32_16x16x32_bf16 v[100:103], v[144:147], v[218:221], v[100:103]
	v_mfma_f32_16x16x32_bf16 v[96:99], v[176:179], v[218:221], v[96:99]
	v_mfma_f32_16x16x32_bf16 v[84:87], v[144:147], v[226:229], v[84:87]
	v_mfma_f32_16x16x32_bf16 v[80:83], v[176:179], v[226:229], v[80:83]
	v_mfma_f32_16x16x32_bf16 v[68:71], v[144:147], v[234:237], v[68:71]
	v_mfma_f32_16x16x32_bf16 v[64:67], v[176:179], v[234:237], v[64:67]
	v_mfma_f32_16x16x32_bf16 v[116:119], v[148:151], v[214:217], v[116:119]
	v_mfma_f32_16x16x32_bf16 v[112:115], v[202:205], v[214:217], v[112:115]
	v_mfma_f32_16x16x32_bf16 v[100:103], v[148:151], v[222:225], v[100:103]
	v_mfma_f32_16x16x32_bf16 v[96:99], v[202:205], v[222:225], v[96:99]
	v_mfma_f32_16x16x32_bf16 v[84:87], v[148:151], v[230:233], v[84:87]
	v_mfma_f32_16x16x32_bf16 v[80:83], v[202:205], v[230:233], v[80:83]
	v_mfma_f32_16x16x32_bf16 v[68:71], v[148:151], v[238:241], v[68:71]
	v_mfma_f32_16x16x32_bf16 v[64:67], v[202:205], v[238:241], v[64:67]
	s_nop 0
	s_barrier
	s_add_i32 s67, s62, s46
	v_lshl_add_u64 v[206:207], s[36:37], 0, v[154:155]
	s_mov_b32 m0, s67
	ds_read_b128 v[210:213], v197 offset:16384
	ds_read_b128 v[214:217], v197 offset:17408
	ds_read_b128 v[218:221], v197 offset:18432
	ds_read_b128 v[222:225], v197 offset:19456
	ds_read_b128 v[226:229], v197 offset:20480
	ds_read_b128 v[230:233], v197 offset:21504
	ds_read_b128 v[234:237], v197 offset:22528
	ds_read_b128 v[238:241], v197 offset:23552
	global_load_lds_dwordx4 v[206:207], off
	s_add_i32 m0, s67, 0x2000
	s_add_u32 s68, s36, 0x40000
	v_lshl_add_u64 v[242:243], s[36:37], 0, v[158:159]
	s_addc_u32 s69, s37, 0
	s_add_i32 s67, s63, s46
	global_load_lds_dwordx4 v[242:243], off
	v_lshl_add_u64 v[244:245], s[68:69], 0, v[154:155]
	s_mov_b32 m0, s67
	v_lshl_add_u64 v[246:247], s[38:39], 0, v[156:157]
	global_load_lds_dwordx4 v[244:245], off
	v_lshl_add_u64 v[244:245], s[68:69], 0, v[158:159]
	s_add_i32 m0, s67, 0x2000
	s_nop 0
	global_load_lds_dwordx4 v[244:245], off
	v_lshl_add_u64 v[244:245], s[38:39], 0, v[152:153]
	s_mov_b32 m0, s31
	s_nop 0
	global_load_lds_dwordx4 v[244:245], off
	s_mov_b32 m0, s47
	s_nop 0
	global_load_lds_dwordx4 v[246:247], off
	s_waitcnt vmcnt(8)
	s_waitcnt lgkmcnt(0)
	s_barrier
; #define PG8_STAGE(bufoff, gbase, voff) do { _Pragma("unroll") for (int _i = 0; _i < 2; ++_i) \
;         __builtin_amdgcn_global_load_lds((const unsigned*)((const char*)(gbase) + (voff)[_i]), (PG8_LAS unsigned*)(lds + (bufoff) + ldsw + _i * 8192), 16, 0, 0); } while (0)
; #define PG8_LDA(dst, b, h) do { _Pragma("unroll") for (int m = 0; m < 4; ++m) _Pragma("unroll") for (int k = 0; k < 2; ++k) dst[m][k] = *(const PG8_LAS bf16x8*)(lds + PG8_SA(b, h) + aoff + m * 2048 + k * 1024); } while (0)
; #define PG8_LDB(dst, b, h) do { _Pragma("unroll") for (int n = 0; n < 2; ++n) _Pragma("unroll") for (int k = 0; k < 2; ++k) dst[n][k] = *(const PG8_LAS bf16x8*)(lds + PG8_SB(b, h) + boff + n * 2048 + k * 1024); } while (0)
; #define PG8_MMA(ai, bj, At, Bt) do { __builtin_amdgcn_s_setprio(1); _Pragma("unroll") for (int m = 0; m < 4; ++m) _Pragma("unroll") for (int n = 0; n < 2; ++n) _Pragma("unroll") for (int k = 0; k < 2; ++k) \
;         acc[ai][bj][m][n] = __builtin_amdgcn_mfma_f32_16x16x32_bf16(Bt[n][k], At[m][k], acc[ai][bj][m][n], 0, 0, 0); __builtin_amdgcn_s_setprio(0); } while (0)
; #define PG8_BAR __builtin_amdgcn_s_barrier()
; template <class Epi, class Sched, bool ALIGN_EPI = false, bool SP2 = false>
; __device__ __forceinline__ void gemm_phase(PG8_LAS unsigned char* lds, const Gemm g, const Sched& S, const Epi& E) {
;     ...
;             if constexpr (SP2) {
;             PG8_LDB(B0, 0, 0); PG8_LDB(B1, 0, 1); PG8_SCHED; PG8_LDA(At, 0, 0); PG8_STAGE(PG8_SA(1, 1), a1 + hstep, voffA);
;             PG8_WAIT_V(8); PG8_WAIT_L(0); PG8_BAR; PG8_MMA(0, 0, At, B0); PG8_MMA(0, 1, At, B1); PG8_BAR; PG8_SCHED;
;             PG8_LDA(At, 0, 1); PG8_STAGE(PG8_SB(0, 0), b2, voffB); PG8_STAGE(PG8_SB(0, 1), b2 + hstep, voffB); PG8_STAGE(PG8_SA(0, 0), a2, voffA);
;             PG8_WAIT_V(8); PG8_WAIT_L(0); PG8_BAR; PG8_MMA(1, 0, At, B0); PG8_MMA(1, 1, At, B1); PG8_BAR; PG8_SCHED;
;             PG8_LDB(B0, 1, 0); PG8_LDB(B1, 1, 1); PG8_SCHED; PG8_LDA(At, 1, 0); PG8_STAGE(PG8_SA(0, 1), a2 + hstep, voffA);
;             PG8_WAIT_V(8); PG8_WAIT_L(0); PG8_BAR; PG8_MMA(0, 0, At, B0); PG8_MMA(0, 1, At, B1); PG8_BAR; PG8_SCHED;
;             PG8_LDA(At, 1, 1); PG8_STAGE(PG8_SB(1, 0), b3, voffB); PG8_STAGE(PG8_SB(1, 1), b3 + hstep, voffB); PG8_STAGE(PG8_SA(1, 0), a3, voffA);
;             PG8_WAIT_V(8); PG8_WAIT_L(0); PG8_BAR; PG8_MMA(1, 0, At, B0); PG8_MMA(1, 1, At, B1); PG8_BAR; PG8_SCHED;
	s_nop 0
	s_waitcnt lgkmcnt(0)
	v_mfma_f32_16x16x32_bf16 v[60:63], v[128:131], v[210:213], v[60:63]
	v_mfma_f32_16x16x32_bf16 v[56:59], v[136:139], v[210:213], v[56:59]
	v_mfma_f32_16x16x32_bf16 v[44:47], v[128:131], v[218:221], v[44:47]
	v_mfma_f32_16x16x32_bf16 v[40:43], v[136:139], v[218:221], v[40:43]
	v_mfma_f32_16x16x32_bf16 v[28:31], v[128:131], v[226:229], v[28:31]
	v_mfma_f32_16x16x32_bf16 v[24:27], v[136:139], v[226:229], v[24:27]
	v_mfma_f32_16x16x32_bf16 v[12:15], v[128:131], v[234:237], v[12:15]
	v_mfma_f32_16x16x32_bf16 v[8:11], v[136:139], v[234:237], v[8:11]
	v_mfma_f32_16x16x32_bf16 v[60:63], v[132:135], v[214:217], v[60:63]
	v_mfma_f32_16x16x32_bf16 v[56:59], v[140:143], v[214:217], v[56:59]
	v_mfma_f32_16x16x32_bf16 v[44:47], v[132:135], v[222:225], v[44:47]
	v_mfma_f32_16x16x32_bf16 v[40:43], v[140:143], v[222:225], v[40:43]
	v_mfma_f32_16x16x32_bf16 v[28:31], v[132:135], v[230:233], v[28:31]
	v_mfma_f32_16x16x32_bf16 v[24:27], v[140:143], v[230:233], v[24:27]
	v_mfma_f32_16x16x32_bf16 v[12:15], v[132:135], v[238:241], v[12:15]
	v_mfma_f32_16x16x32_bf16 v[8:11], v[140:143], v[238:241], v[8:11]
	s_nop 0
	s_nop 0
	v_mfma_f32_16x16x32_bf16 v[52:55], v[144:147], v[210:213], v[52:55]
	v_mfma_f32_16x16x32_bf16 v[48:51], v[176:179], v[210:213], v[48:51]
	v_mfma_f32_16x16x32_bf16 v[36:39], v[144:147], v[218:221], v[36:39]
	v_mfma_f32_16x16x32_bf16 v[32:35], v[176:179], v[218:221], v[32:35]
	v_mfma_f32_16x16x32_bf16 v[20:23], v[144:147], v[226:229], v[20:23]
	v_mfma_f32_16x16x32_bf16 v[16:19], v[176:179], v[226:229], v[16:19]
	v_mfma_f32_16x16x32_bf16 v[4:7], v[144:147], v[234:237], v[4:7]
	v_mfma_f32_16x16x32_bf16 v[0:3], v[176:179], v[234:237], v[0:3]
	v_mfma_f32_16x16x32_bf16 v[52:55], v[148:151], v[214:217], v[52:55]
	v_mfma_f32_16x16x32_bf16 v[48:51], v[202:205], v[214:217], v[48:51]
	v_mfma_f32_16x16x32_bf16 v[36:39], v[148:151], v[222:225], v[36:39]
	v_mfma_f32_16x16x32_bf16 v[32:35], v[202:205], v[222:225], v[32:35]
	v_mfma_f32_16x16x32_bf16 v[20:23], v[148:151], v[230:233], v[20:23]
	v_mfma_f32_16x16x32_bf16 v[16:19], v[202:205], v[230:233], v[16:19]
	v_mfma_f32_16x16x32_bf16 v[4:7], v[148:151], v[238:241], v[4:7]
	v_mfma_f32_16x16x32_bf16 v[0:3], v[202:205], v[238:241], v[0:3]
	s_nop 0
	s_barrier
	s_add_i32 s67, 0, 0x18000
	s_add_i32 s68, 0, 0x1c000
	v_add_u32_e32 v140, s67, v181
	v_add_u32_e32 v175, s68, v181
	ds_read_b128 v[128:131], v140
	ds_read_b128 v[132:135], v140 offset:1024
	ds_read_b128 v[136:139], v140 offset:2048
	ds_read_b128 v[140:143], v140 offset:3072
	ds_read_b128 v[144:147], v175
	ds_read_b128 v[148:151], v175 offset:1024
	ds_read_b128 v[176:179], v175 offset:2048
	ds_read_b128 v[202:205], v175 offset:3072
	s_add_u32 s38, s38, 0x40000
	s_addc_u32 s39, s39, 0
	s_mov_b32 m0, s48
	v_lshl_add_u64 v[248:249], s[38:39], 0, v[152:153]
	ds_read_b128 v[210:213], v197 offset:32768
	ds_read_b128 v[214:217], v197 offset:33792
	ds_read_b128 v[218:221], v197 offset:34816
	ds_read_b128 v[222:225], v197 offset:35840
	ds_read_b128 v[226:229], v197 offset:36864
	ds_read_b128 v[230:233], v197 offset:37888
	ds_read_b128 v[234:237], v197 offset:38912
	ds_read_b128 v[238:241], v197 offset:39936
	global_load_lds_dwordx4 v[248:249], off
	v_lshl_add_u64 v[248:249], s[38:39], 0, v[156:157]
	s_mov_b32 m0, s49
	s_nop 0
	global_load_lds_dwordx4 v[248:249], off
	s_waitcnt vmcnt(8)
	s_waitcnt lgkmcnt(0)
	s_barrier
	s_nop 0
	s_waitcnt lgkmcnt(0)
	v_mfma_f32_16x16x32_bf16 v[124:127], v[128:131], v[210:213], v[124:127]
	v_mfma_f32_16x16x32_bf16 v[120:123], v[136:139], v[210:213], v[120:123]
	v_mfma_f32_16x16x32_bf16 v[108:111], v[128:131], v[218:221], v[108:111]
	v_mfma_f32_16x16x32_bf16 v[104:107], v[136:139], v[218:221], v[104:107]
	v_mfma_f32_16x16x32_bf16 v[92:95], v[128:131], v[226:229], v[92:95]
	v_mfma_f32_16x16x32_bf16 v[88:91], v[136:139], v[226:229], v[88:91]
	v_mfma_f32_16x16x32_bf16 v[76:79], v[128:131], v[234:237], v[76:79]
	v_mfma_f32_16x16x32_bf16 v[72:75], v[136:139], v[234:237], v[72:75]
	v_mfma_f32_16x16x32_bf16 v[124:127], v[132:135], v[214:217], v[124:127]
	v_mfma_f32_16x16x32_bf16 v[120:123], v[140:143], v[214:217], v[120:123]
	v_mfma_f32_16x16x32_bf16 v[108:111], v[132:135], v[222:225], v[108:111]
	v_mfma_f32_16x16x32_bf16 v[104:107], v[140:143], v[222:225], v[104:107]
	v_mfma_f32_16x16x32_bf16 v[92:95], v[132:135], v[230:233], v[92:95]
	v_mfma_f32_16x16x32_bf16 v[88:91], v[140:143], v[230:233], v[88:91]
	v_mfma_f32_16x16x32_bf16 v[76:79], v[132:135], v[238:241], v[76:79]
	v_mfma_f32_16x16x32_bf16 v[72:75], v[140:143], v[238:241], v[72:75]
	s_nop 0
	s_nop 0
	v_mfma_f32_16x16x32_bf16 v[116:119], v[144:147], v[210:213], v[116:119]
	v_mfma_f32_16x16x32_bf16 v[112:115], v[176:179], v[210:213], v[112:115]
	v_mfma_f32_16x16x32_bf16 v[100:103], v[144:147], v[218:221], v[100:103]
	v_mfma_f32_16x16x32_bf16 v[96:99], v[176:179], v[218:221], v[96:99]
	v_mfma_f32_16x16x32_bf16 v[84:87], v[144:147], v[226:229], v[84:87]
	v_mfma_f32_16x16x32_bf16 v[80:83], v[176:179], v[226:229], v[80:83]
	v_mfma_f32_16x16x32_bf16 v[68:71], v[144:147], v[234:237], v[68:71]
	v_mfma_f32_16x16x32_bf16 v[64:67], v[176:179], v[234:237], v[64:67]
	v_mfma_f32_16x16x32_bf16 v[116:119], v[148:151], v[214:217], v[116:119]
	v_mfma_f32_16x16x32_bf16 v[112:115], v[202:205], v[214:217], v[112:115]
	v_mfma_f32_16x16x32_bf16 v[100:103], v[148:151], v[222:225], v[100:103]
	v_mfma_f32_16x16x32_bf16 v[96:99], v[202:205], v[222:225], v[96:99]
	v_mfma_f32_16x16x32_bf16 v[84:87], v[148:151], v[230:233], v[84:87]
	v_mfma_f32_16x16x32_bf16 v[80:83], v[202:205], v[230:233], v[80:83]
	v_mfma_f32_16x16x32_bf16 v[68:71], v[148:151], v[238:241], v[68:71]
	v_mfma_f32_16x16x32_bf16 v[64:67], v[202:205], v[238:241], v[64:67]
	s_nop 0
	s_barrier
; #define PG8_STAGE(bufoff, gbase, voff) do { _Pragma("unroll") for (int _i = 0; _i < 2; ++_i) \
;         __builtin_amdgcn_global_load_lds((const unsigned*)((const char*)(gbase) + (voff)[_i]), (PG8_LAS unsigned*)(lds + (bufoff) + ldsw + _i * 8192), 16, 0, 0); } while (0)
; #define PG8_LDA(dst, b, h) do { _Pragma("unroll") for (int m = 0; m < 4; ++m) _Pragma("unroll") for (int k = 0; k < 2; ++k) dst[m][k] = *(const PG8_LAS bf16x8*)(lds + PG8_SA(b, h) + aoff + m * 2048 + k * 1024); } while (0)
; #define PG8_LDB(dst, b, h) do { _Pragma("unroll") for (int n = 0; n < 2; ++n) _Pragma("unroll") for (int k = 0; k < 2; ++k) dst[n][k] = *(const PG8_LAS bf16x8*)(lds + PG8_SB(b, h) + boff + n * 2048 + k * 1024); } while (0)
; #define PG8_MMA(ai, bj, At, Bt) do { __builtin_amdgcn_s_setprio(1); _Pragma("unroll") for (int m = 0; m < 4; ++m) _Pragma("unroll") for (int n = 0; n < 2; ++n) _Pragma("unroll") for (int k = 0; k < 2; ++k) \
;         acc[ai][bj][m][n] = __builtin_amdgcn_mfma_f32_16x16x32_bf16(Bt[n][k], At[m][k], acc[ai][bj][m][n], 0, 0, 0); __builtin_amdgcn_s_setprio(0); } while (0)
; #define PG8_BAR __builtin_amdgcn_s_barrier()
; template <class Epi, class Sched, bool ALIGN_EPI = false, bool SP2 = false>
; __device__ __forceinline__ void gemm_phase(PG8_LAS unsigned char* lds, const Gemm g, const Sched& S, const Epi& E) {
;     ...
;             if constexpr (SP2) {
;             PG8_LDB(B0, 0, 0); PG8_LDB(B1, 0, 1); PG8_SCHED; PG8_LDA(At, 0, 0); PG8_STAGE(PG8_SA(1, 1), a1 + hstep, voffA);
;             PG8_WAIT_V(8); PG8_WAIT_L(0); PG8_BAR; PG8_MMA(0, 0, At, B0); PG8_MMA(0, 1, At, B1); PG8_BAR; PG8_SCHED;
;             PG8_LDA(At, 0, 1); PG8_STAGE(PG8_SB(0, 0), b2, voffB); PG8_STAGE(PG8_SB(0, 1), b2 + hstep, voffB); PG8_STAGE(PG8_SA(0, 0), a2, voffA);
;             PG8_WAIT_V(8); PG8_WAIT_L(0); PG8_BAR; PG8_MMA(1, 0, At, B0); PG8_MMA(1, 1, At, B1); PG8_BAR; PG8_SCHED;
;             PG8_LDB(B0, 1, 0); PG8_LDB(B1, 1, 1); PG8_SCHED; PG8_LDA(At, 1, 0); PG8_STAGE(PG8_SA(0, 1), a2 + hstep, voffA);
;             PG8_WAIT_V(8); PG8_WAIT_L(0); PG8_BAR; PG8_MMA(0, 0, At, B0); PG8_MMA(0, 1, At, B1); PG8_BAR; PG8_SCHED;
;             PG8_LDA(At, 1, 1); PG8_STAGE(PG8_SB(1, 0), b3, voffB); PG8_STAGE(PG8_SB(1, 1), b3 + hstep, voffB); PG8_STAGE(PG8_SA(1, 0), a3, voffA);
;             PG8_WAIT_V(8); PG8_WAIT_L(0); PG8_BAR; PG8_MMA(1, 0, At, B0); PG8_MMA(1, 1, At, B1); PG8_BAR; PG8_SCHED;
	s_add_i32 s38, s67, s46
	v_lshl_add_u64 v[206:207], v[206:207], 0, s[16:17]
	s_mov_b32 m0, s38
	ds_read_b128 v[210:213], v197 offset:49152
	ds_read_b128 v[214:217], v197 offset:50176
	ds_read_b128 v[218:221], v197 offset:51200
	ds_read_b128 v[222:225], v197 offset:52224
	ds_read_b128 v[226:229], v197 offset:53248
	ds_read_b128 v[230:233], v197 offset:54272
	ds_read_b128 v[234:237], v197 offset:55296
	ds_read_b128 v[238:241], v197 offset:56320
	global_load_lds_dwordx4 v[206:207], off
	s_add_i32 m0, s38, 0x2000
	s_add_u32 s36, s36, 0x40080
	v_lshl_add_u64 v[206:207], v[242:243], 0, s[16:17]
	s_addc_u32 s37, s37, 0
	s_add_i32 s38, s68, s46
	global_load_lds_dwordx4 v[206:207], off
	v_lshl_add_u64 v[206:207], s[36:37], 0, v[154:155]
	s_mov_b32 m0, s38
	s_nop 0
	global_load_lds_dwordx4 v[206:207], off
	v_lshl_add_u64 v[206:207], s[36:37], 0, v[158:159]
	s_add_i32 m0, s38, 0x2000
	s_nop 0
	global_load_lds_dwordx4 v[206:207], off
	v_lshl_add_u64 v[206:207], v[244:245], 0, s[16:17]
	s_mov_b32 m0, s54
	s_nop 0
	global_load_lds_dwordx4 v[206:207], off
	v_lshl_add_u64 v[206:207], v[246:247], 0, s[16:17]
	s_mov_b32 m0, s55
	s_nop 0
	global_load_lds_dwordx4 v[206:207], off
	s_waitcnt vmcnt(8)
	s_waitcnt lgkmcnt(0)
	s_barrier
	s_nop 0
	s_waitcnt lgkmcnt(0)
	v_mfma_f32_16x16x32_bf16 v[60:63], v[128:131], v[210:213], v[60:63]
	v_mfma_f32_16x16x32_bf16 v[56:59], v[136:139], v[210:213], v[56:59]
	v_mfma_f32_16x16x32_bf16 v[44:47], v[128:131], v[218:221], v[44:47]
	v_mfma_f32_16x16x32_bf16 v[40:43], v[136:139], v[218:221], v[40:43]
	v_mfma_f32_16x16x32_bf16 v[28:31], v[128:131], v[226:229], v[28:31]
	v_mfma_f32_16x16x32_bf16 v[24:27], v[136:139], v[226:229], v[24:27]
	v_mfma_f32_16x16x32_bf16 v[12:15], v[128:131], v[234:237], v[12:15]
	v_mfma_f32_16x16x32_bf16 v[8:11], v[136:139], v[234:237], v[8:11]
	v_mfma_f32_16x16x32_bf16 v[60:63], v[132:135], v[214:217], v[60:63]
	v_mfma_f32_16x16x32_bf16 v[56:59], v[140:143], v[214:217], v[56:59]
	v_mfma_f32_16x16x32_bf16 v[44:47], v[132:135], v[222:225], v[44:47]
	v_mfma_f32_16x16x32_bf16 v[40:43], v[140:143], v[222:225], v[40:43]
	v_mfma_f32_16x16x32_bf16 v[28:31], v[132:135], v[230:233], v[28:31]
	v_mfma_f32_16x16x32_bf16 v[24:27], v[140:143], v[230:233], v[24:27]
	v_mfma_f32_16x16x32_bf16 v[12:15], v[132:135], v[238:241], v[12:15]
	v_mfma_f32_16x16x32_bf16 v[8:11], v[140:143], v[238:241], v[8:11]
	s_nop 0
	s_nop 0
	v_mfma_f32_16x16x32_bf16 v[52:55], v[144:147], v[210:213], v[52:55]
	v_mfma_f32_16x16x32_bf16 v[48:51], v[176:179], v[210:213], v[48:51]
	v_mfma_f32_16x16x32_bf16 v[36:39], v[144:147], v[218:221], v[36:39]
	v_mfma_f32_16x16x32_bf16 v[32:35], v[176:179], v[218:221], v[32:35]
	v_mfma_f32_16x16x32_bf16 v[20:23], v[144:147], v[226:229], v[20:23]
	v_mfma_f32_16x16x32_bf16 v[16:19], v[176:179], v[226:229], v[16:19]
	v_mfma_f32_16x16x32_bf16 v[4:7], v[144:147], v[234:237], v[4:7]
	v_mfma_f32_16x16x32_bf16 v[0:3], v[176:179], v[234:237], v[0:3]
	v_mfma_f32_16x16x32_bf16 v[52:55], v[148:151], v[214:217], v[52:55]
	v_mfma_f32_16x16x32_bf16 v[48:51], v[202:205], v[214:217], v[48:51]
	v_mfma_f32_16x16x32_bf16 v[36:39], v[148:151], v[222:225], v[36:39]
	v_mfma_f32_16x16x32_bf16 v[32:35], v[202:205], v[222:225], v[32:35]
	v_mfma_f32_16x16x32_bf16 v[20:23], v[148:151], v[230:233], v[20:23]
	v_mfma_f32_16x16x32_bf16 v[16:19], v[202:205], v[230:233], v[16:19]
	v_mfma_f32_16x16x32_bf16 v[4:7], v[148:151], v[238:241], v[4:7]
	v_mfma_f32_16x16x32_bf16 v[0:3], v[202:205], v[238:241], v[0:3]
	s_nop 0
	s_barrier
	s_add_i32 s66, s66, 2
	s_add_u32 s34, s34, 0x100
	s_addc_u32 s35, s35, 0
	s_add_u32 s25, s25, 0x100
	s_addc_u32 s65, s65, 0
	s_cmp_gt_u32 s66, 13
	s_cbranch_scc0 .LBB9_232
	s_and_b64 vcc, exec, s[18:19]
	s_cbranch_vccnz .LBB9_237
	s_cmp_lt_i32 s33, 5
	s_mov_b64 s[2:3], -1
	s_cbranch_scc0 .LBB9_238

; __device__ __forceinline__ void xcd_barrier(const XcdBarrier& b) {
;     asm volatile("s_waitcnt vmcnt(0)" ::: "memory");
;     __syncthreads();
;     if (threadIdx.x == 0) {
;         unsigned* bar = b.bar;
;         __builtin_amdgcn_s_waitcnt(0);
;         unsigned nloc = b.st[0], nx = b.st[1];
;         if (nloc == 0u) { xcd_barrier_complete(bar, b.x, nloc, nx); b.st[0] = nloc; b.st[1] = nx; }
.LBB9_251:
	s_cmp_gt_i32 s93, 3
	s_cselect_b64 s[0:1], -1, 0
	s_and_b64 s[2:3], s[14:15], s[0:1]
	s_andn2_b64 vcc, exec, s[2:3]
	s_cbranch_vccnz .LBB9_305
	s_waitcnt vmcnt(0)
	s_waitcnt vmcnt(0) lgkmcnt(0)
	s_barrier
	s_setprio 0
	s_and_saveexec_b64 s[4:5], s[80:81]
	s_cbranch_execz .LBB9_304
	s_add_i32 s2, 0, 0x24000
	v_mov_b32_e32 v0, s2
	s_waitcnt vmcnt(0) expcnt(0) lgkmcnt(0)
	ds_read_b32 v2, v0
	s_add_i32 s2, 0, 0x24004
	v_mov_b32_e32 v0, s2
	ds_read_b32 v0, v0
	s_waitcnt lgkmcnt(1)
	v_cmp_ne_u32_e32 vcc, 0, v2
	s_cbranch_vccnz .LBB9_268
	s_add_u32 s6, s90, 0x1000
	s_addc_u32 s7, s91, 0
	s_add_u32 s8, s90, 0x1100
	s_addc_u32 s9, s91, 0
	s_add_u32 s10, s90, 0x1200
	s_addc_u32 s11, s91, 0
	s_mul_i32 s18, s95, s83
	s_add_u32 s12, s90, 0x1300
	s_mul_i32 s18, s18, s94
	s_addc_u32 s13, s91, 0
	s_mov_b32 s19, 1
	v_mov_b32_e32 v16, 0
	s_branch .LBB9_256

; __device__ __forceinline__ unsigned xb_add(unsigned* p, unsigned v) { return __hip_atomic_fetch_add(p, v, __ATOMIC_RELAXED, __HIP_MEMORY_SCOPE_AGENT); }
; __device__ __forceinline__ void xcd_barrier(const XcdBarrier& b) {
;     asm volatile("s_waitcnt vmcnt(0)" ::: "memory");
;     __syncthreads();
;     if (threadIdx.x == 0) {
;         unsigned* bar = b.bar;
;         __builtin_amdgcn_s_waitcnt(0);
;         unsigned nloc = b.st[0], nx = b.st[1];
;         if (nloc == 0u) { xcd_barrier_complete(bar, b.x, nloc, nx); b.st[0] = nloc; b.st[1] = nx; }
;         const unsigned old = xb_add(&bar[XB_XSUB(b.x)], 1u);
;         const unsigned gen = old / nloc;
;         if (old + 1u == (gen + 1u) * nloc) {
;             __builtin_amdgcn_fence(__ATOMIC_RELEASE, "agent");
.LBB9_444:
	v_readlane_b32 s97, v251, 39
	s_cmp_gt_i32 s93, 4
	s_cselect_b64 s[0:1], -1, 0
	s_and_b64 s[2:3], s[22:23], s[0:1]
	s_andn2_b64 vcc, exec, s[2:3]
	s_cbranch_vccnz .LBB9_498
	s_waitcnt vmcnt(0)
	s_waitcnt vmcnt(0) lgkmcnt(0)
	s_barrier
	s_setprio 0
	s_and_saveexec_b64 s[4:5], s[80:81]
	s_cbranch_execz .LBB9_497
	v_mov_b32_e32 v0, 0x24008
	ds_read_b32 v0, v0
	s_waitcnt lgkmcnt(0)
	v_readfirstlane_b32 s98, v0
	s_nop 3
	s_cmp_eq_u32 s98, 1
	s_cbranch_scc0 .Lgb3_orig
	s_cmpk_lg_i32 s94, 0x100
	s_cbranch_scc1 .Lgb3_orig
	s_and_b32 s98, s97, 63
	s_lshl_b32 s98, s98, 2
	s_add_i32 s98, s98, 0x3f00
	v_mov_b32_e32 v0, s98
	v_mov_b32_e32 v1, 1
	global_atomic_add v0, v1, s[90:91]
	buffer_inv sc1

; #define PG8_STAGE(bufoff, gbase, voff) do { _Pragma("unroll") for (int _i = 0; _i < 2; ++_i) \
;         __builtin_amdgcn_global_load_lds((const unsigned*)((const char*)(gbase) + (voff)[_i]), (PG8_LAS unsigned*)(lds + (bufoff) + ldsw + _i * 8192), 16, 0, 0); } while (0)
; #define PG8_WAIT_V(n) asm volatile("s_waitcnt vmcnt(" #n ")" ::: "memory")
; #define PG8_BAR __builtin_amdgcn_s_barrier()
; template <class Epi, class Sched, bool ALIGN_EPI = false, bool SP2 = false>
; __device__ __forceinline__ void gemm_phase(PG8_LAS unsigned char* lds, const Gemm g, const Sched& S, const Epi& E) {
;     ...
;     const char* cA = PG8_UA(cur); const char* cB = PG8_UB(cur);
;     S.a_ready(cur);
;     if constexpr (SP2) {
;         PG8_STAGE(PG8_SB(0, 0), cB, voffB); PG8_STAGE(PG8_SB(0, 1), cB + hstep, voffB); PG8_STAGE(PG8_SA(0, 0), cA, voffA); PG8_STAGE(PG8_SA(0, 1), cA + hstep, voffA);
;         if (wr == 1) PG8_BAR;
;         PG8_WAIT_V(2); PG8_BAR;
;         PG8_STAGE(PG8_SB(1, 0), cB + kstep, voffB); PG8_STAGE(PG8_SA(1, 0), cA + kstep, voffA); PG8_STAGE(PG8_SB(1, 1), cB + hstep + kstep, voffB);
;         PG8_WAIT_V(6); PG8_BAR;
.LBB9_505:
	s_andn2_b64 vcc, exec, s[0:1]
	s_cbranch_vccnz .LBB9_591
	v_lshrrev_b32_e32 v2, 1, v208
	s_waitcnt lgkmcnt(0)
	v_and_b32_e32 v11, 24, v2
	v_lshrrev_b32_e32 v2, 5, v208
	v_and_b32_e32 v2, 4, v2
	v_bfe_u32 v3, v208, 2, 2
	v_lshlrev_b32_e32 v0, 4, v208
	v_and_b32_e32 v1, 32, v208
	v_bfe_u32 v10, v208, 2, 4
	v_or3_b32 v2, v2, v3, v11
	v_lshrrev_b32_e32 v3, 3, v208
	s_movk_i32 s1, 0x70
	s_add_u32 s33, s90, 0xc300000
	v_bitop3_b32 v8, v0, v1, 48 bitop3:0x6c
	v_and_b32_e32 v9, 64, v208
	v_and_or_b32 v4, v3, s1, v10
	s_movk_i32 s1, 0x60
	v_add_u32_e32 v12, 0x2000, v0
	s_addc_u32 s38, s91, 0
	v_or_b32_e32 v1, v8, v9
	v_and_or_b32 v3, v3, s1, v2
	v_lshrrev_b32_e32 v0, 7, v12
	s_movk_i32 s1, 0xf0
	s_add_u32 s39, s90, 0xe500000
	v_lshl_or_b32 v130, v3, 11, v1
	v_and_or_b32 v3, v0, s1, v10
	s_movk_i32 s1, 0xe0
	s_addc_u32 s40, s91, 0
	v_and_or_b32 v0, v0, s1, v2
	s_lshr_b32 s1, s16, 6
	s_ashr_i32 s27, s26, 31
	s_ashr_i32 s5, s4, 31
	s_lshr_b32 s0, s16, 8
	s_lshl_b32 s41, s1, 10
	s_lshl_b64 s[2:3], s[26:27], 19
	s_lshl_b64 s[8:9], s[4:5], 19
	s_add_u32 s34, s39, s8
	s_addc_u32 s35, s40, s9
	s_add_i32 s27, s41, 0
	s_add_i32 m0, s27, 0x10000
	v_lshl_or_b32 v134, v0, 11, v1
	global_load_lds_dwordx4 v130, s[34:35]
	s_add_i32 m0, s27, 0x12000
	s_add_u32 s8, s34, 0x40000
	global_load_lds_dwordx4 v134, s[34:35]
	s_addc_u32 s9, s35, 0
	s_add_i32 m0, s27, 0x14000
	v_lshl_or_b32 v128, v4, 11, v1
	global_load_lds_dwordx4 v130, s[8:9]
	s_add_i32 m0, s27, 0x16000
	s_add_u32 s30, s33, s2
	s_addc_u32 s31, s38, s3
	s_add_i32 s42, s27, 0x2000
	global_load_lds_dwordx4 v134, s[8:9]
	s_mov_b32 m0, s27
	s_add_u32 s2, s30, 0x40000
	v_lshl_or_b32 v132, v3, 11, v1
	global_load_lds_dwordx4 v128, s[30:31]
	s_mov_b32 m0, s42
	s_addc_u32 s3, s31, 0
	s_add_i32 s43, s27, 0x4000
	global_load_lds_dwordx4 v132, s[30:31]
	s_mov_b32 m0, s43
	s_add_i32 s44, s27, 0x6000
	global_load_lds_dwordx4 v128, s[2:3]
	s_mov_b32 m0, s44
	v_mov_b32_e32 v131, 0
	global_load_lds_dwordx4 v132, s[2:3]
	v_mov_b32_e32 v135, v131
	v_mov_b32_e32 v129, v131
	v_mov_b32_e32 v133, v131
	s_cmp_eq_u32 s0, 1
	s_mov_b32 s36, 0
	v_lshl_add_u64 v[6:7], s[34:35], 0, v[130:131]
	v_lshl_add_u64 v[4:5], s[34:35], 0, v[134:135]
	v_lshl_add_u64 v[0:1], s[30:31], 0, v[128:129]
	s_cselect_b64 s[8:9], -1, 0
	s_cmp_lg_u32 s0, 1
	v_lshl_add_u64 v[2:3], s[30:31], 0, v[132:133]
	s_cbranch_scc1 .LBB9_508
	s_barrier
	s_setprio 1

; #define PG8_STAGE(bufoff, gbase, voff) do { _Pragma("unroll") for (int _i = 0; _i < 2; ++_i) \
;         __builtin_amdgcn_global_load_lds((const unsigned*)((const char*)(gbase) + (voff)[_i]), (PG8_LAS unsigned*)(lds + (bufoff) + ldsw + _i * 8192), 16, 0, 0); } while (0)
; #define PG8_LDA(dst, b, h) do { _Pragma("unroll") for (int m = 0; m < 4; ++m) _Pragma("unroll") for (int k = 0; k < 2; ++k) dst[m][k] = *(const PG8_LAS bf16x8*)(lds + PG8_SA(b, h) + aoff + m * 2048 + k * 1024); } while (0)
; #define PG8_LDB(dst, b, h) do { _Pragma("unroll") for (int n = 0; n < 2; ++n) _Pragma("unroll") for (int k = 0; k < 2; ++k) dst[n][k] = *(const PG8_LAS bf16x8*)(lds + PG8_SB(b, h) + boff + n * 2048 + k * 1024); } while (0)
; #define PG8_MMA(ai, bj, At, Bt) do { __builtin_amdgcn_s_setprio(1); _Pragma("unroll") for (int m = 0; m < 4; ++m) _Pragma("unroll") for (int n = 0; n < 2; ++n) _Pragma("unroll") for (int k = 0; k < 2; ++k) \
;         acc[ai][bj][m][n] = __builtin_amdgcn_mfma_f32_16x16x32_bf16(Bt[n][k], At[m][k], acc[ai][bj][m][n], 0, 0, 0); __builtin_amdgcn_s_setprio(0); } while (0)
; #define PG8_BAR __builtin_amdgcn_s_barrier()
; template <class Epi, class Sched, bool ALIGN_EPI = false, bool SP2 = false>
; __device__ __forceinline__ void gemm_phase(PG8_LAS unsigned char* lds, const Gemm g, const Sched& S, const Epi& E) {
;     ...
;             if constexpr (SP2) {
;             PG8_LDB(B0, 0, 0); PG8_LDB(B1, 0, 1); PG8_SCHED; PG8_LDA(At, 0, 0); PG8_STAGE(PG8_SA(1, 1), a1 + hstep, voffA);
;             PG8_WAIT_V(8); PG8_WAIT_L(0); PG8_BAR; PG8_MMA(0, 0, At, B0); PG8_MMA(0, 1, At, B1); PG8_BAR; PG8_SCHED;
;             PG8_LDA(At, 0, 1); PG8_STAGE(PG8_SB(0, 0), b2, voffB); PG8_STAGE(PG8_SB(0, 1), b2 + hstep, voffB); PG8_STAGE(PG8_SA(0, 0), a2, voffA);
;             PG8_WAIT_V(8); PG8_WAIT_L(0); PG8_BAR; PG8_MMA(1, 0, At, B0); PG8_MMA(1, 1, At, B1); PG8_BAR; PG8_SCHED;
;             PG8_LDB(B0, 1, 0); PG8_LDB(B1, 1, 1); PG8_SCHED; PG8_LDA(At, 1, 0); PG8_STAGE(PG8_SA(0, 1), a2 + hstep, voffA);
;             PG8_WAIT_V(8); PG8_WAIT_L(0); PG8_BAR; PG8_MMA(0, 0, At, B0); PG8_MMA(0, 1, At, B1); PG8_BAR; PG8_SCHED;
;             PG8_LDA(At, 1, 1); PG8_STAGE(PG8_SB(1, 0), b3, voffB); PG8_STAGE(PG8_SB(1, 1), b3 + hstep, voffB); PG8_STAGE(PG8_SA(1, 0), a3, voffA);
;             PG8_WAIT_V(8); PG8_WAIT_L(0); PG8_BAR; PG8_MMA(1, 0, At, B0); PG8_MMA(1, 1, At, B1); PG8_BAR; PG8_SCHED;
.LBB9_518:
	v_add_u32_e32 v148, s52, v151
	ds_read_b128 v[144:147], v148
	ds_read_b128 v[162:165], v148 offset:1024
	ds_read_b128 v[166:169], v148 offset:2048
	ds_read_b128 v[170:173], v148 offset:3072
	v_add_u32_e32 v148, s53, v151
	ds_read_b128 v[174:177], v148
	ds_read_b128 v[178:181], v148 offset:1024
	ds_read_b128 v[182:185], v148 offset:2048
	ds_read_b128 v[186:189], v148 offset:3072
	s_add_i32 s59, s37, 2
	s_add_u32 s34, s30, 0xfffc0080
	s_addc_u32 s35, s31, -1
	s_cmp_eq_u32 s56, s37
	s_cselect_b32 s37, s2, s35
	s_cselect_b32 s36, s3, s34
	s_cselect_b32 s35, s5, s58
	s_cselect_b32 s34, s19, s57
	v_lshl_add_u64 v[148:149], s[30:31], 0, v[136:137]
	s_add_i32 m0, s27, 0xc000
	ds_read_b128 v[190:193], v160
	ds_read_b128 v[194:197], v160 offset:1024
	ds_read_b128 v[198:201], v160 offset:2048
	ds_read_b128 v[202:205], v160 offset:3072
	ds_read_b128 v[210:213], v160 offset:4096
	ds_read_b128 v[214:217], v160 offset:5120
	ds_read_b128 v[218:221], v160 offset:6144
	ds_read_b128 v[222:225], v160 offset:7168
	global_load_lds_dwordx4 v[148:149], off
	v_lshl_add_u64 v[148:149], s[30:31], 0, v[138:139]
	s_add_i32 m0, s27, 0xe000
	s_nop 0
	global_load_lds_dwordx4 v[148:149], off
	s_waitcnt vmcnt(8)
	s_waitcnt lgkmcnt(0)
	s_barrier
	s_nop 0
	s_waitcnt lgkmcnt(0)
	v_mfma_f32_16x16x32_bf16 v[124:127], v[144:147], v[190:193], v[124:127]
	v_mfma_f32_16x16x32_bf16 v[120:123], v[166:169], v[190:193], v[120:123]
	v_mfma_f32_16x16x32_bf16 v[116:119], v[144:147], v[198:201], v[116:119]
	v_mfma_f32_16x16x32_bf16 v[112:115], v[166:169], v[198:201], v[112:115]
	v_mfma_f32_16x16x32_bf16 v[108:111], v[144:147], v[210:213], v[108:111]
	v_mfma_f32_16x16x32_bf16 v[104:107], v[166:169], v[210:213], v[104:107]
	v_mfma_f32_16x16x32_bf16 v[100:103], v[144:147], v[218:221], v[100:103]
	v_mfma_f32_16x16x32_bf16 v[96:99], v[166:169], v[218:221], v[96:99]
	v_mfma_f32_16x16x32_bf16 v[124:127], v[162:165], v[194:197], v[124:127]
	v_mfma_f32_16x16x32_bf16 v[120:123], v[170:173], v[194:197], v[120:123]
	v_mfma_f32_16x16x32_bf16 v[116:119], v[162:165], v[202:205], v[116:119]
	v_mfma_f32_16x16x32_bf16 v[112:115], v[170:173], v[202:205], v[112:115]
	v_mfma_f32_16x16x32_bf16 v[108:111], v[162:165], v[214:217], v[108:111]
	v_mfma_f32_16x16x32_bf16 v[104:107], v[170:173], v[214:217], v[104:107]
	v_mfma_f32_16x16x32_bf16 v[100:103], v[162:165], v[222:225], v[100:103]
	v_mfma_f32_16x16x32_bf16 v[96:99], v[170:173], v[222:225], v[96:99]
	s_nop 0
	s_nop 0
	v_mfma_f32_16x16x32_bf16 v[92:95], v[174:177], v[190:193], v[92:95]
	v_mfma_f32_16x16x32_bf16 v[88:91], v[182:185], v[190:193], v[88:91]
	v_mfma_f32_16x16x32_bf16 v[84:87], v[174:177], v[198:201], v[84:87]
	v_mfma_f32_16x16x32_bf16 v[80:83], v[182:185], v[198:201], v[80:83]
	v_mfma_f32_16x16x32_bf16 v[76:79], v[174:177], v[210:213], v[76:79]
	v_mfma_f32_16x16x32_bf16 v[72:75], v[182:185], v[210:213], v[72:75]
	v_mfma_f32_16x16x32_bf16 v[68:71], v[174:177], v[218:221], v[68:71]
	v_mfma_f32_16x16x32_bf16 v[64:67], v[182:185], v[218:221], v[64:67]
	v_mfma_f32_16x16x32_bf16 v[92:95], v[178:181], v[194:197], v[92:95]
	v_mfma_f32_16x16x32_bf16 v[88:91], v[186:189], v[194:197], v[88:91]
	v_mfma_f32_16x16x32_bf16 v[84:87], v[178:181], v[202:205], v[84:87]
	v_mfma_f32_16x16x32_bf16 v[80:83], v[186:189], v[202:205], v[80:83]
	v_mfma_f32_16x16x32_bf16 v[76:79], v[178:181], v[214:217], v[76:79]
	v_mfma_f32_16x16x32_bf16 v[72:75], v[186:189], v[214:217], v[72:75]
	v_mfma_f32_16x16x32_bf16 v[68:71], v[178:181], v[222:225], v[68:71]
	v_mfma_f32_16x16x32_bf16 v[64:67], v[186:189], v[222:225], v[64:67]
	s_nop 0
	s_barrier
	s_add_i32 s60, s52, s41
	v_lshl_add_u64 v[148:149], s[34:35], 0, v[130:131]
	s_mov_b32 m0, s60
	ds_read_b128 v[190:193], v160 offset:16384
	ds_read_b128 v[194:197], v160 offset:17408
	ds_read_b128 v[198:201], v160 offset:18432
	ds_read_b128 v[202:205], v160 offset:19456
	ds_read_b128 v[210:213], v160 offset:20480
	ds_read_b128 v[214:217], v160 offset:21504
	ds_read_b128 v[218:221], v160 offset:22528
	ds_read_b128 v[222:225], v160 offset:23552
	global_load_lds_dwordx4 v[148:149], off
	s_add_i32 m0, s60, 0x2000
	s_add_u32 s60, s34, 0x40000
	v_lshl_add_u64 v[206:207], s[34:35], 0, v[134:135]
	s_addc_u32 s61, s35, 0
	s_add_i32 s62, s53, s41
	global_load_lds_dwordx4 v[206:207], off
	v_lshl_add_u64 v[226:227], s[60:61], 0, v[130:131]
	s_mov_b32 m0, s62
	v_lshl_add_u64 v[228:229], s[36:37], 0, v[132:133]
	global_load_lds_dwordx4 v[226:227], off
	v_lshl_add_u64 v[226:227], s[60:61], 0, v[134:135]
	s_add_i32 m0, s62, 0x2000
	s_nop 0
	global_load_lds_dwordx4 v[226:227], off
	v_lshl_add_u64 v[226:227], s[36:37], 0, v[128:129]
	s_mov_b32 m0, s27
	s_nop 0
	global_load_lds_dwordx4 v[226:227], off
	s_mov_b32 m0, s42
	s_nop 0
	global_load_lds_dwordx4 v[228:229], off
	s_waitcnt vmcnt(8)
	s_waitcnt lgkmcnt(0)
	s_barrier
; #define PG8_STAGE(bufoff, gbase, voff) do { _Pragma("unroll") for (int _i = 0; _i < 2; ++_i) \
;         __builtin_amdgcn_global_load_lds((const unsigned*)((const char*)(gbase) + (voff)[_i]), (PG8_LAS unsigned*)(lds + (bufoff) + ldsw + _i * 8192), 16, 0, 0); } while (0)
; #define PG8_LDA(dst, b, h) do { _Pragma("unroll") for (int m = 0; m < 4; ++m) _Pragma("unroll") for (int k = 0; k < 2; ++k) dst[m][k] = *(const PG8_LAS bf16x8*)(lds + PG8_SA(b, h) + aoff + m * 2048 + k * 1024); } while (0)
; #define PG8_LDB(dst, b, h) do { _Pragma("unroll") for (int n = 0; n < 2; ++n) _Pragma("unroll") for (int k = 0; k < 2; ++k) dst[n][k] = *(const PG8_LAS bf16x8*)(lds + PG8_SB(b, h) + boff + n * 2048 + k * 1024); } while (0)
; #define PG8_MMA(ai, bj, At, Bt) do { __builtin_amdgcn_s_setprio(1); _Pragma("unroll") for (int m = 0; m < 4; ++m) _Pragma("unroll") for (int n = 0; n < 2; ++n) _Pragma("unroll") for (int k = 0; k < 2; ++k) \
;         acc[ai][bj][m][n] = __builtin_amdgcn_mfma_f32_16x16x32_bf16(Bt[n][k], At[m][k], acc[ai][bj][m][n], 0, 0, 0); __builtin_amdgcn_s_setprio(0); } while (0)
; #define PG8_BAR __builtin_amdgcn_s_barrier()
; template <class Epi, class Sched, bool ALIGN_EPI = false, bool SP2 = false>
; __device__ __forceinline__ void gemm_phase(PG8_LAS unsigned char* lds, const Gemm g, const Sched& S, const Epi& E) {
;     ...
;             if constexpr (SP2) {
;             PG8_LDB(B0, 0, 0); PG8_LDB(B1, 0, 1); PG8_SCHED; PG8_LDA(At, 0, 0); PG8_STAGE(PG8_SA(1, 1), a1 + hstep, voffA);
;             PG8_WAIT_V(8); PG8_WAIT_L(0); PG8_BAR; PG8_MMA(0, 0, At, B0); PG8_MMA(0, 1, At, B1); PG8_BAR; PG8_SCHED;
;             PG8_LDA(At, 0, 1); PG8_STAGE(PG8_SB(0, 0), b2, voffB); PG8_STAGE(PG8_SB(0, 1), b2 + hstep, voffB); PG8_STAGE(PG8_SA(0, 0), a2, voffA);
;             PG8_WAIT_V(8); PG8_WAIT_L(0); PG8_BAR; PG8_MMA(1, 0, At, B0); PG8_MMA(1, 1, At, B1); PG8_BAR; PG8_SCHED;
;             PG8_LDB(B0, 1, 0); PG8_LDB(B1, 1, 1); PG8_SCHED; PG8_LDA(At, 1, 0); PG8_STAGE(PG8_SA(0, 1), a2 + hstep, voffA);
;             PG8_WAIT_V(8); PG8_WAIT_L(0); PG8_BAR; PG8_MMA(0, 0, At, B0); PG8_MMA(0, 1, At, B1); PG8_BAR; PG8_SCHED;
;             PG8_LDA(At, 1, 1); PG8_STAGE(PG8_SB(1, 0), b3, voffB); PG8_STAGE(PG8_SB(1, 1), b3 + hstep, voffB); PG8_STAGE(PG8_SA(1, 0), a3, voffA);
;             PG8_WAIT_V(8); PG8_WAIT_L(0); PG8_BAR; PG8_MMA(1, 0, At, B0); PG8_MMA(1, 1, At, B1); PG8_BAR; PG8_SCHED;
	s_nop 0
	s_waitcnt lgkmcnt(0)
	v_mfma_f32_16x16x32_bf16 v[60:63], v[144:147], v[190:193], v[60:63]
	v_mfma_f32_16x16x32_bf16 v[56:59], v[166:169], v[190:193], v[56:59]
	v_mfma_f32_16x16x32_bf16 v[52:55], v[144:147], v[198:201], v[52:55]
	v_mfma_f32_16x16x32_bf16 v[48:51], v[166:169], v[198:201], v[48:51]
	v_mfma_f32_16x16x32_bf16 v[44:47], v[144:147], v[210:213], v[44:47]
	v_mfma_f32_16x16x32_bf16 v[40:43], v[166:169], v[210:213], v[40:43]
	v_mfma_f32_16x16x32_bf16 v[36:39], v[144:147], v[218:221], v[36:39]
	v_mfma_f32_16x16x32_bf16 v[32:35], v[166:169], v[218:221], v[32:35]
	v_mfma_f32_16x16x32_bf16 v[60:63], v[162:165], v[194:197], v[60:63]
	v_mfma_f32_16x16x32_bf16 v[56:59], v[170:173], v[194:197], v[56:59]
	v_mfma_f32_16x16x32_bf16 v[52:55], v[162:165], v[202:205], v[52:55]
	v_mfma_f32_16x16x32_bf16 v[48:51], v[170:173], v[202:205], v[48:51]
	v_mfma_f32_16x16x32_bf16 v[44:47], v[162:165], v[214:217], v[44:47]
	v_mfma_f32_16x16x32_bf16 v[40:43], v[170:173], v[214:217], v[40:43]
	v_mfma_f32_16x16x32_bf16 v[36:39], v[162:165], v[222:225], v[36:39]
	v_mfma_f32_16x16x32_bf16 v[32:35], v[170:173], v[222:225], v[32:35]
	s_nop 0
	s_nop 0
	v_mfma_f32_16x16x32_bf16 v[28:31], v[174:177], v[190:193], v[28:31]
	v_mfma_f32_16x16x32_bf16 v[24:27], v[182:185], v[190:193], v[24:27]
	v_mfma_f32_16x16x32_bf16 v[20:23], v[174:177], v[198:201], v[20:23]
	v_mfma_f32_16x16x32_bf16 v[16:19], v[182:185], v[198:201], v[16:19]
	v_mfma_f32_16x16x32_bf16 v[12:15], v[174:177], v[210:213], v[12:15]
	v_mfma_f32_16x16x32_bf16 v[8:11], v[182:185], v[210:213], v[8:11]
	v_mfma_f32_16x16x32_bf16 v[4:7], v[174:177], v[218:221], v[4:7]
	v_mfma_f32_16x16x32_bf16 v[0:3], v[182:185], v[218:221], v[0:3]
	v_mfma_f32_16x16x32_bf16 v[28:31], v[178:181], v[194:197], v[28:31]
	v_mfma_f32_16x16x32_bf16 v[24:27], v[186:189], v[194:197], v[24:27]
	v_mfma_f32_16x16x32_bf16 v[20:23], v[178:181], v[202:205], v[20:23]
	v_mfma_f32_16x16x32_bf16 v[16:19], v[186:189], v[202:205], v[16:19]
	v_mfma_f32_16x16x32_bf16 v[12:15], v[178:181], v[214:217], v[12:15]
	v_mfma_f32_16x16x32_bf16 v[8:11], v[186:189], v[214:217], v[8:11]
	v_mfma_f32_16x16x32_bf16 v[4:7], v[178:181], v[222:225], v[4:7]
	v_mfma_f32_16x16x32_bf16 v[0:3], v[186:189], v[222:225], v[0:3]
	s_nop 0
	s_barrier
	s_add_i32 s60, 0, 0x18000
	v_add_u32_e32 v161, s60, v151
	s_add_i32 s61, 0, 0x1c000
	ds_read_b128 v[144:147], v161
	ds_read_b128 v[162:165], v161 offset:1024
	ds_read_b128 v[166:169], v161 offset:2048
	ds_read_b128 v[170:173], v161 offset:3072
	v_add_u32_e32 v161, s61, v151
	ds_read_b128 v[174:177], v161
	ds_read_b128 v[178:181], v161 offset:1024
	ds_read_b128 v[182:185], v161 offset:2048
	ds_read_b128 v[186:189], v161 offset:3072
	s_add_u32 s36, s36, 0x40000
	s_addc_u32 s37, s37, 0
	s_mov_b32 m0, s43
	v_lshl_add_u64 v[230:231], s[36:37], 0, v[128:129]
	ds_read_b128 v[190:193], v160 offset:32768
	ds_read_b128 v[194:197], v160 offset:33792
	ds_read_b128 v[198:201], v160 offset:34816
	ds_read_b128 v[202:205], v160 offset:35840
	ds_read_b128 v[210:213], v160 offset:36864
	ds_read_b128 v[214:217], v160 offset:37888
	ds_read_b128 v[218:221], v160 offset:38912
	ds_read_b128 v[222:225], v160 offset:39936
	global_load_lds_dwordx4 v[230:231], off
	v_lshl_add_u64 v[230:231], s[36:37], 0, v[132:133]
	s_mov_b32 m0, s44
	s_nop 0
	global_load_lds_dwordx4 v[230:231], off
	s_waitcnt vmcnt(8)
	s_waitcnt lgkmcnt(0)
	s_barrier
	s_nop 0
	s_waitcnt lgkmcnt(0)
	v_mfma_f32_16x16x32_bf16 v[124:127], v[144:147], v[190:193], v[124:127]
	v_mfma_f32_16x16x32_bf16 v[120:123], v[166:169], v[190:193], v[120:123]
	v_mfma_f32_16x16x32_bf16 v[116:119], v[144:147], v[198:201], v[116:119]
	v_mfma_f32_16x16x32_bf16 v[112:115], v[166:169], v[198:201], v[112:115]
	v_mfma_f32_16x16x32_bf16 v[108:111], v[144:147], v[210:213], v[108:111]
	v_mfma_f32_16x16x32_bf16 v[104:107], v[166:169], v[210:213], v[104:107]
	v_mfma_f32_16x16x32_bf16 v[100:103], v[144:147], v[218:221], v[100:103]
	v_mfma_f32_16x16x32_bf16 v[96:99], v[166:169], v[218:221], v[96:99]
	v_mfma_f32_16x16x32_bf16 v[124:127], v[162:165], v[194:197], v[124:127]
	v_mfma_f32_16x16x32_bf16 v[120:123], v[170:173], v[194:197], v[120:123]
	v_mfma_f32_16x16x32_bf16 v[116:119], v[162:165], v[202:205], v[116:119]
	v_mfma_f32_16x16x32_bf16 v[112:115], v[170:173], v[202:205], v[112:115]
	v_mfma_f32_16x16x32_bf16 v[108:111], v[162:165], v[214:217], v[108:111]
	v_mfma_f32_16x16x32_bf16 v[104:107], v[170:173], v[214:217], v[104:107]
	v_mfma_f32_16x16x32_bf16 v[100:103], v[162:165], v[222:225], v[100:103]
	v_mfma_f32_16x16x32_bf16 v[96:99], v[170:173], v[222:225], v[96:99]
	s_nop 0
	s_nop 0
	v_mfma_f32_16x16x32_bf16 v[92:95], v[174:177], v[190:193], v[92:95]
	v_mfma_f32_16x16x32_bf16 v[88:91], v[182:185], v[190:193], v[88:91]
	v_mfma_f32_16x16x32_bf16 v[84:87], v[174:177], v[198:201], v[84:87]
	v_mfma_f32_16x16x32_bf16 v[80:83], v[182:185], v[198:201], v[80:83]
	v_mfma_f32_16x16x32_bf16 v[76:79], v[174:177], v[210:213], v[76:79]
	v_mfma_f32_16x16x32_bf16 v[72:75], v[182:185], v[210:213], v[72:75]
	v_mfma_f32_16x16x32_bf16 v[68:71], v[174:177], v[218:221], v[68:71]
	v_mfma_f32_16x16x32_bf16 v[64:67], v[182:185], v[218:221], v[64:67]
	v_mfma_f32_16x16x32_bf16 v[92:95], v[178:181], v[194:197], v[92:95]
	v_mfma_f32_16x16x32_bf16 v[88:91], v[186:189], v[194:197], v[88:91]
	v_mfma_f32_16x16x32_bf16 v[84:87], v[178:181], v[202:205], v[84:87]
	v_mfma_f32_16x16x32_bf16 v[80:83], v[186:189], v[202:205], v[80:83]
	v_mfma_f32_16x16x32_bf16 v[76:79], v[178:181], v[214:217], v[76:79]
	v_mfma_f32_16x16x32_bf16 v[72:75], v[186:189], v[214:217], v[72:75]
	v_mfma_f32_16x16x32_bf16 v[68:71], v[178:181], v[222:225], v[68:71]
	v_mfma_f32_16x16x32_bf16 v[64:67], v[186:189], v[222:225], v[64:67]
	s_nop 0
	s_barrier
; #define PG8_STAGE(bufoff, gbase, voff) do { _Pragma("unroll") for (int _i = 0; _i < 2; ++_i) \
;         __builtin_amdgcn_global_load_lds((const unsigned*)((const char*)(gbase) + (voff)[_i]), (PG8_LAS unsigned*)(lds + (bufoff) + ldsw + _i * 8192), 16, 0, 0); } while (0)
; #define PG8_LDA(dst, b, h) do { _Pragma("unroll") for (int m = 0; m < 4; ++m) _Pragma("unroll") for (int k = 0; k < 2; ++k) dst[m][k] = *(const PG8_LAS bf16x8*)(lds + PG8_SA(b, h) + aoff + m * 2048 + k * 1024); } while (0)
; #define PG8_LDB(dst, b, h) do { _Pragma("unroll") for (int n = 0; n < 2; ++n) _Pragma("unroll") for (int k = 0; k < 2; ++k) dst[n][k] = *(const PG8_LAS bf16x8*)(lds + PG8_SB(b, h) + boff + n * 2048 + k * 1024); } while (0)
; #define PG8_MMA(ai, bj, At, Bt) do { __builtin_amdgcn_s_setprio(1); _Pragma("unroll") for (int m = 0; m < 4; ++m) _Pragma("unroll") for (int n = 0; n < 2; ++n) _Pragma("unroll") for (int k = 0; k < 2; ++k) \
;         acc[ai][bj][m][n] = __builtin_amdgcn_mfma_f32_16x16x32_bf16(Bt[n][k], At[m][k], acc[ai][bj][m][n], 0, 0, 0); __builtin_amdgcn_s_setprio(0); } while (0)
; #define PG8_BAR __builtin_amdgcn_s_barrier()
; template <class Epi, class Sched, bool ALIGN_EPI = false, bool SP2 = false>
; __device__ __forceinline__ void gemm_phase(PG8_LAS unsigned char* lds, const Gemm g, const Sched& S, const Epi& E) {
;     ...
;             if constexpr (SP2) {
;             PG8_LDB(B0, 0, 0); PG8_LDB(B1, 0, 1); PG8_SCHED; PG8_LDA(At, 0, 0); PG8_STAGE(PG8_SA(1, 1), a1 + hstep, voffA);
;             PG8_WAIT_V(8); PG8_WAIT_L(0); PG8_BAR; PG8_MMA(0, 0, At, B0); PG8_MMA(0, 1, At, B1); PG8_BAR; PG8_SCHED;
;             PG8_LDA(At, 0, 1); PG8_STAGE(PG8_SB(0, 0), b2, voffB); PG8_STAGE(PG8_SB(0, 1), b2 + hstep, voffB); PG8_STAGE(PG8_SA(0, 0), a2, voffA);
;             PG8_WAIT_V(8); PG8_WAIT_L(0); PG8_BAR; PG8_MMA(1, 0, At, B0); PG8_MMA(1, 1, At, B1); PG8_BAR; PG8_SCHED;
;             PG8_LDB(B0, 1, 0); PG8_LDB(B1, 1, 1); PG8_SCHED; PG8_LDA(At, 1, 0); PG8_STAGE(PG8_SA(0, 1), a2 + hstep, voffA);
;             PG8_WAIT_V(8); PG8_WAIT_L(0); PG8_BAR; PG8_MMA(0, 0, At, B0); PG8_MMA(0, 1, At, B1); PG8_BAR; PG8_SCHED;
;             PG8_LDA(At, 1, 1); PG8_STAGE(PG8_SB(1, 0), b3, voffB); PG8_STAGE(PG8_SB(1, 1), b3 + hstep, voffB); PG8_STAGE(PG8_SA(1, 0), a3, voffA);
;             PG8_WAIT_V(8); PG8_WAIT_L(0); PG8_BAR; PG8_MMA(1, 0, At, B0); PG8_MMA(1, 1, At, B1); PG8_BAR; PG8_SCHED;
	s_add_i32 s36, s60, s41
	v_lshl_add_u64 v[148:149], v[148:149], 0, s[14:15]
	s_mov_b32 m0, s36
	ds_read_b128 v[190:193], v160 offset:49152
	ds_read_b128 v[194:197], v160 offset:50176
	ds_read_b128 v[198:201], v160 offset:51200
	ds_read_b128 v[202:205], v160 offset:52224
	ds_read_b128 v[210:213], v160 offset:53248
	ds_read_b128 v[214:217], v160 offset:54272
	ds_read_b128 v[218:221], v160 offset:55296
	ds_read_b128 v[222:225], v160 offset:56320
	global_load_lds_dwordx4 v[148:149], off
	s_add_i32 m0, s36, 0x2000
	s_add_u32 s34, s34, 0x40080
	v_lshl_add_u64 v[148:149], v[206:207], 0, s[14:15]
	s_addc_u32 s35, s35, 0
	s_add_i32 s36, s61, s41
	global_load_lds_dwordx4 v[148:149], off
	v_lshl_add_u64 v[148:149], s[34:35], 0, v[130:131]
	s_mov_b32 m0, s36
	s_nop 0
	global_load_lds_dwordx4 v[148:149], off
	v_lshl_add_u64 v[148:149], s[34:35], 0, v[134:135]
	s_add_i32 m0, s36, 0x2000
	s_nop 0
	global_load_lds_dwordx4 v[148:149], off
	v_lshl_add_u64 v[148:149], v[226:227], 0, s[14:15]
	s_mov_b32 m0, s49
	s_nop 0
	global_load_lds_dwordx4 v[148:149], off
	v_lshl_add_u64 v[148:149], v[228:229], 0, s[14:15]
	s_mov_b32 m0, s50
	s_nop 0
	global_load_lds_dwordx4 v[148:149], off
	s_waitcnt vmcnt(8)
	s_waitcnt lgkmcnt(0)
	s_barrier
	s_nop 0
	s_waitcnt lgkmcnt(0)
	v_mfma_f32_16x16x32_bf16 v[60:63], v[144:147], v[190:193], v[60:63]
	v_mfma_f32_16x16x32_bf16 v[56:59], v[166:169], v[190:193], v[56:59]
	v_mfma_f32_16x16x32_bf16 v[52:55], v[144:147], v[198:201], v[52:55]
	v_mfma_f32_16x16x32_bf16 v[48:51], v[166:169], v[198:201], v[48:51]
	v_mfma_f32_16x16x32_bf16 v[44:47], v[144:147], v[210:213], v[44:47]
	v_mfma_f32_16x16x32_bf16 v[40:43], v[166:169], v[210:213], v[40:43]
	v_mfma_f32_16x16x32_bf16 v[36:39], v[144:147], v[218:221], v[36:39]
	v_mfma_f32_16x16x32_bf16 v[32:35], v[166:169], v[218:221], v[32:35]
	v_mfma_f32_16x16x32_bf16 v[60:63], v[162:165], v[194:197], v[60:63]
	v_mfma_f32_16x16x32_bf16 v[56:59], v[170:173], v[194:197], v[56:59]
	v_mfma_f32_16x16x32_bf16 v[52:55], v[162:165], v[202:205], v[52:55]
	v_mfma_f32_16x16x32_bf16 v[48:51], v[170:173], v[202:205], v[48:51]
	v_mfma_f32_16x16x32_bf16 v[44:47], v[162:165], v[214:217], v[44:47]
	v_mfma_f32_16x16x32_bf16 v[40:43], v[170:173], v[214:217], v[40:43]
	v_mfma_f32_16x16x32_bf16 v[36:39], v[162:165], v[222:225], v[36:39]
	v_mfma_f32_16x16x32_bf16 v[32:35], v[170:173], v[222:225], v[32:35]
	s_nop 0
	s_nop 0
	v_mfma_f32_16x16x32_bf16 v[28:31], v[174:177], v[190:193], v[28:31]
	v_mfma_f32_16x16x32_bf16 v[24:27], v[182:185], v[190:193], v[24:27]
	v_mfma_f32_16x16x32_bf16 v[20:23], v[174:177], v[198:201], v[20:23]
	v_mfma_f32_16x16x32_bf16 v[16:19], v[182:185], v[198:201], v[16:19]
	v_mfma_f32_16x16x32_bf16 v[12:15], v[174:177], v[210:213], v[12:15]
	v_mfma_f32_16x16x32_bf16 v[8:11], v[182:185], v[210:213], v[8:11]
	v_mfma_f32_16x16x32_bf16 v[4:7], v[174:177], v[218:221], v[4:7]
	v_mfma_f32_16x16x32_bf16 v[0:3], v[182:185], v[218:221], v[0:3]
	v_mfma_f32_16x16x32_bf16 v[28:31], v[178:181], v[194:197], v[28:31]
	v_mfma_f32_16x16x32_bf16 v[24:27], v[186:189], v[194:197], v[24:27]
	v_mfma_f32_16x16x32_bf16 v[20:23], v[178:181], v[202:205], v[20:23]
	v_mfma_f32_16x16x32_bf16 v[16:19], v[186:189], v[202:205], v[16:19]
	v_mfma_f32_16x16x32_bf16 v[12:15], v[178:181], v[214:217], v[12:15]
	v_mfma_f32_16x16x32_bf16 v[8:11], v[186:189], v[214:217], v[8:11]
	v_mfma_f32_16x16x32_bf16 v[4:7], v[178:181], v[222:225], v[4:7]
	v_mfma_f32_16x16x32_bf16 v[0:3], v[186:189], v[222:225], v[0:3]
	s_nop 0
	s_barrier
	s_add_u32 s30, s30, 0x100
	s_addc_u32 s31, s31, 0
	s_add_u32 s57, s57, 0x100
	s_addc_u32 s58, s58, 0
	s_cmp_ge_u32 s59, s21
	s_mov_b32 s37, s59
	s_cbranch_scc0 .LBB9_518
	s_and_b64 vcc, exec, s[16:17]
	s_cbranch_vccz .LBB9_521
	s_barrier

; __device__ __forceinline__ unsigned xb_add(unsigned* p, unsigned v) { return __hip_atomic_fetch_add(p, v, __ATOMIC_RELAXED, __HIP_MEMORY_SCOPE_AGENT); }
; __device__ __forceinline__ void xcd_barrier(const XcdBarrier& b) {
;     asm volatile("s_waitcnt vmcnt(0)" ::: "memory");
;     __syncthreads();
;     if (threadIdx.x == 0) {
;         unsigned* bar = b.bar;
;         __builtin_amdgcn_s_waitcnt(0);
;         unsigned nloc = b.st[0], nx = b.st[1];
;         if (nloc == 0u) { xcd_barrier_complete(bar, b.x, nloc, nx); b.st[0] = nloc; b.st[1] = nx; }
;         const unsigned old = xb_add(&bar[XB_XSUB(b.x)], 1u);
;         const unsigned gen = old / nloc;
;         if (old + 1u == (gen + 1u) * nloc) {
;             __builtin_amdgcn_fence(__ATOMIC_RELEASE, "agent");
.LBB9_591:
	s_cmp_gt_i32 s93, 5
	s_cselect_b64 s[0:1], -1, 0
	s_and_b64 s[2:3], s[6:7], s[0:1]
	s_andn2_b64 vcc, exec, s[2:3]
	s_cbranch_vccnz .LBB9_645
	s_waitcnt vmcnt(0)
	s_waitcnt vmcnt(0) lgkmcnt(0)
	s_barrier
	s_setprio 0
	s_and_saveexec_b64 s[4:5], s[80:81]
	s_cbranch_execz .LBB9_644
	v_mov_b32_e32 v0, 0x24008
	ds_read_b32 v0, v0
	s_waitcnt lgkmcnt(0)
	v_readfirstlane_b32 s98, v0
	s_nop 3
	s_cmp_eq_u32 s98, 1
	s_cbranch_scc0 .Lgb4_orig
	s_and_b32 s98, s97, 63
	s_lshl_b32 s98, s98, 2
	s_add_i32 s98, s98, 0x3d00
	v_mov_b32_e32 v0, s98
	v_mov_b32_e32 v1, 1
	global_atomic_add v0, v1, s[90:91]
	buffer_inv sc1

; #define PG8_STAGE(bufoff, gbase, voff) do { _Pragma("unroll") for (int _i = 0; _i < 2; ++_i) \
;         __builtin_amdgcn_global_load_lds((const unsigned*)((const char*)(gbase) + (voff)[_i]), (PG8_LAS unsigned*)(lds + (bufoff) + ldsw + _i * 8192), 16, 0, 0); } while (0)
; #define PG8_WAIT_V(n) asm volatile("s_waitcnt vmcnt(" #n ")" ::: "memory")
; #define PG8_BAR __builtin_amdgcn_s_barrier()
; template <class Epi, class Sched, bool ALIGN_EPI = false, bool SP2 = false>
; __device__ __forceinline__ void gemm_phase(PG8_LAS unsigned char* lds, const Gemm g, const Sched& S, const Epi& E) {
;     ...
;     const char* cA = PG8_UA(cur); const char* cB = PG8_UB(cur);
;     S.a_ready(cur);
;     if constexpr (SP2) {
;         PG8_STAGE(PG8_SB(0, 0), cB, voffB); PG8_STAGE(PG8_SB(0, 1), cB + hstep, voffB); PG8_STAGE(PG8_SA(0, 0), cA, voffA); PG8_STAGE(PG8_SA(0, 1), cA + hstep, voffA);
;         if (wr == 1) PG8_BAR;
;         PG8_WAIT_V(2); PG8_BAR;
;         PG8_STAGE(PG8_SB(1, 0), cB + kstep, voffB); PG8_STAGE(PG8_SA(1, 0), cA + kstep, voffA); PG8_STAGE(PG8_SB(1, 1), cB + hstep + kstep, voffB);
;         PG8_WAIT_V(6); PG8_BAR;
.LBB9_652:
	s_andn2_b64 vcc, exec, s[0:1]
	s_cbranch_vccnz .LBB9_706
	v_lshrrev_b32_e32 v2, 1, v208
	v_lshrrev_b32_e32 v3, 5, v208
	v_and_b32_e32 v2, 24, v2
	v_and_b32_e32 v3, 4, v3
	v_bfe_u32 v4, v208, 2, 2
	s_add_u32 s33, s90, 0x4200000
	v_lshlrev_b32_e32 v0, 4, v208
	v_and_b32_e32 v1, 32, v208
	s_waitcnt lgkmcnt(0)
	v_bfe_u32 v10, v208, 2, 4
	v_or3_b32 v2, v3, v4, v2
	v_lshrrev_b32_e32 v3, 3, v208
	s_movk_i32 s0, 0x70
	s_addc_u32 s40, s91, 0
	v_bitop3_b32 v8, v0, v1, 48 bitop3:0x6c
	v_and_b32_e32 v9, 64, v208
	v_and_or_b32 v4, v3, s0, v10
	s_movk_i32 s0, 0x60
	v_add_u32_e32 v11, 0x2000, v0
	s_add_u32 s41, s90, 0xc00000
	v_or_b32_e32 v1, v8, v9
	v_and_or_b32 v3, v3, s0, v2
	v_lshrrev_b32_e32 v0, 7, v11
	s_movk_i32 s0, 0xf0
	s_addc_u32 s42, s91, 0
	s_lshr_b32 s1, s4, 6
	v_lshl_or_b32 v162, v3, 11, v1
	v_and_or_b32 v3, v0, s0, v10
	s_movk_i32 s0, 0xe0
	s_ashr_i32 s31, s30, 31
	s_ashr_i32 s11, s10, 31
	v_and_or_b32 v0, v0, s0, v2
	s_lshr_b32 s0, s4, 8
	s_lshl_b32 s43, s1, 10
	s_lshl_b64 s[2:3], s[30:31], 19
	s_lshl_b64 s[6:7], s[10:11], 19
	s_add_u32 s36, s41, s6
	s_addc_u32 s37, s42, s7
	s_add_i32 s31, s43, 0
	s_add_i32 m0, s31, 0x10000
	v_lshl_or_b32 v166, v0, 11, v1
	global_load_lds_dwordx4 v162, s[36:37]
	s_add_i32 m0, s31, 0x12000
	s_add_u32 s6, s36, 0x40000
	global_load_lds_dwordx4 v166, s[36:37]
	s_addc_u32 s7, s37, 0
	s_add_i32 m0, s31, 0x14000
	v_lshl_or_b32 v160, v4, 11, v1
	global_load_lds_dwordx4 v162, s[6:7]
	s_add_i32 m0, s31, 0x16000
	s_add_u32 s34, s33, s2
	s_addc_u32 s35, s40, s3
	s_add_i32 s44, s31, 0x2000
	global_load_lds_dwordx4 v166, s[6:7]
	s_mov_b32 m0, s31
	s_add_u32 s2, s34, 0x40000
	v_lshl_or_b32 v164, v3, 11, v1
	global_load_lds_dwordx4 v160, s[34:35]
	s_mov_b32 m0, s44
	s_addc_u32 s3, s35, 0
	s_add_i32 s45, s31, 0x4000
	global_load_lds_dwordx4 v164, s[34:35]
	s_mov_b32 m0, s45
	s_add_i32 s46, s31, 0x6000
	global_load_lds_dwordx4 v160, s[2:3]
	s_mov_b32 m0, s46
	v_mov_b32_e32 v163, 0
	global_load_lds_dwordx4 v164, s[2:3]
	v_mov_b32_e32 v167, v163
	v_mov_b32_e32 v161, v163
	v_mov_b32_e32 v165, v163
	s_cmp_eq_u32 s0, 1
	s_mov_b32 s47, 0
	v_lshl_add_u64 v[6:7], s[36:37], 0, v[162:163]
	v_lshl_add_u64 v[4:5], s[36:37], 0, v[166:167]
	v_lshl_add_u64 v[0:1], s[34:35], 0, v[160:161]
	s_cselect_b64 s[12:13], -1, 0
	s_cmp_lg_u32 s0, 1
	v_lshl_add_u64 v[2:3], s[34:35], 0, v[164:165]
	s_cbranch_scc1 .LBB9_655
	s_barrier
	s_setprio 1

; #define PG8_STAGE(bufoff, gbase, voff) do { _Pragma("unroll") for (int _i = 0; _i < 2; ++_i) \
;         __builtin_amdgcn_global_load_lds((const unsigned*)((const char*)(gbase) + (voff)[_i]), (PG8_LAS unsigned*)(lds + (bufoff) + ldsw + _i * 8192), 16, 0, 0); } while (0)
; #define PG8_LDA(dst, b, h) do { _Pragma("unroll") for (int m = 0; m < 4; ++m) _Pragma("unroll") for (int k = 0; k < 2; ++k) dst[m][k] = *(const PG8_LAS bf16x8*)(lds + PG8_SA(b, h) + aoff + m * 2048 + k * 1024); } while (0)
; #define PG8_LDB(dst, b, h) do { _Pragma("unroll") for (int n = 0; n < 2; ++n) _Pragma("unroll") for (int k = 0; k < 2; ++k) dst[n][k] = *(const PG8_LAS bf16x8*)(lds + PG8_SB(b, h) + boff + n * 2048 + k * 1024); } while (0)
; #define PG8_MMA(ai, bj, At, Bt) do { __builtin_amdgcn_s_setprio(1); _Pragma("unroll") for (int m = 0; m < 4; ++m) _Pragma("unroll") for (int n = 0; n < 2; ++n) _Pragma("unroll") for (int k = 0; k < 2; ++k) \
;         acc[ai][bj][m][n] = __builtin_amdgcn_mfma_f32_16x16x32_bf16(Bt[n][k], At[m][k], acc[ai][bj][m][n], 0, 0, 0); __builtin_amdgcn_s_setprio(0); } while (0)
; #define PG8_BAR __builtin_amdgcn_s_barrier()
; template <class Epi, class Sched, bool ALIGN_EPI = false, bool SP2 = false>
; __device__ __forceinline__ void gemm_phase(PG8_LAS unsigned char* lds, const Gemm g, const Sched& S, const Epi& E) {
;     ...
;             if constexpr (SP2) {
;             PG8_LDB(B0, 0, 0); PG8_LDB(B1, 0, 1); PG8_SCHED; PG8_LDA(At, 0, 0); PG8_STAGE(PG8_SA(1, 1), a1 + hstep, voffA);
;             PG8_WAIT_V(8); PG8_WAIT_L(0); PG8_BAR; PG8_MMA(0, 0, At, B0); PG8_MMA(0, 1, At, B1); PG8_BAR; PG8_SCHED;
;             PG8_LDA(At, 0, 1); PG8_STAGE(PG8_SB(0, 0), b2, voffB); PG8_STAGE(PG8_SB(0, 1), b2 + hstep, voffB); PG8_STAGE(PG8_SA(0, 0), a2, voffA);
;             PG8_WAIT_V(8); PG8_WAIT_L(0); PG8_BAR; PG8_MMA(1, 0, At, B0); PG8_MMA(1, 1, At, B1); PG8_BAR; PG8_SCHED;
;             PG8_LDB(B0, 1, 0); PG8_LDB(B1, 1, 1); PG8_SCHED; PG8_LDA(At, 1, 0); PG8_STAGE(PG8_SA(0, 1), a2 + hstep, voffA);
;             PG8_WAIT_V(8); PG8_WAIT_L(0); PG8_BAR; PG8_MMA(0, 0, At, B0); PG8_MMA(0, 1, At, B1); PG8_BAR; PG8_SCHED;
;             PG8_LDA(At, 1, 1); PG8_STAGE(PG8_SB(1, 0), b3, voffB); PG8_STAGE(PG8_SB(1, 1), b3 + hstep, voffB); PG8_STAGE(PG8_SA(1, 0), a3, voffA);
;             PG8_WAIT_V(8); PG8_WAIT_L(0); PG8_BAR; PG8_MMA(1, 0, At, B0); PG8_MMA(1, 1, At, B1); PG8_BAR; PG8_SCHED;
.LBB9_665:
	ds_read_b128 v[128:131], v214
	ds_read_b128 v[132:135], v214 offset:1024
	ds_read_b128 v[136:139], v214 offset:2048
	ds_read_b128 v[140:143], v214 offset:3072
	ds_read_b128 v[144:147], v215
	ds_read_b128 v[148:151], v215 offset:1024
	ds_read_b128 v[152:155], v215 offset:2048
	ds_read_b128 v[156:159], v215 offset:3072
	s_add_u32 s36, s34, 0xfffc0080
	s_addc_u32 s37, s35, -1
	s_cmp_eq_u32 s58, 12
	s_cselect_b32 s39, s2, s37
	s_cselect_b32 s38, s3, s36
	s_cselect_b32 s37, s11, s57
	s_cselect_b32 s36, s23, s25
	v_lshl_add_u64 v[218:219], s[34:35], 0, v[168:169]
	s_add_i32 m0, s31, 0xc000
	ds_read_b128 v[176:179], v216
	ds_read_b128 v[180:183], v216 offset:1024
	ds_read_b128 v[184:187], v216 offset:2048
	ds_read_b128 v[188:191], v216 offset:3072
	ds_read_b128 v[192:195], v216 offset:4096
	ds_read_b128 v[196:199], v216 offset:5120
	ds_read_b128 v[200:203], v216 offset:6144
	ds_read_b128 v[204:207], v216 offset:7168
	global_load_lds_dwordx4 v[218:219], off
	v_lshl_add_u64 v[218:219], s[34:35], 0, v[170:171]
	s_add_i32 m0, s31, 0xe000
	s_nop 0
	global_load_lds_dwordx4 v[218:219], off
	s_waitcnt vmcnt(8)
	s_waitcnt lgkmcnt(0)
	s_barrier
	s_nop 0
	s_waitcnt lgkmcnt(0)
	v_mfma_f32_16x16x32_bf16 v[124:127], v[128:131], v[176:179], v[124:127]
	v_mfma_f32_16x16x32_bf16 v[120:123], v[136:139], v[176:179], v[120:123]
	v_mfma_f32_16x16x32_bf16 v[116:119], v[128:131], v[184:187], v[116:119]
	v_mfma_f32_16x16x32_bf16 v[112:115], v[136:139], v[184:187], v[112:115]
	v_mfma_f32_16x16x32_bf16 v[108:111], v[128:131], v[192:195], v[108:111]
	v_mfma_f32_16x16x32_bf16 v[104:107], v[136:139], v[192:195], v[104:107]
	v_mfma_f32_16x16x32_bf16 v[100:103], v[128:131], v[200:203], v[100:103]
	v_mfma_f32_16x16x32_bf16 v[96:99], v[136:139], v[200:203], v[96:99]
	v_mfma_f32_16x16x32_bf16 v[124:127], v[132:135], v[180:183], v[124:127]
	v_mfma_f32_16x16x32_bf16 v[120:123], v[140:143], v[180:183], v[120:123]
	v_mfma_f32_16x16x32_bf16 v[116:119], v[132:135], v[188:191], v[116:119]
	v_mfma_f32_16x16x32_bf16 v[112:115], v[140:143], v[188:191], v[112:115]
	v_mfma_f32_16x16x32_bf16 v[108:111], v[132:135], v[196:199], v[108:111]
	v_mfma_f32_16x16x32_bf16 v[104:107], v[140:143], v[196:199], v[104:107]
	v_mfma_f32_16x16x32_bf16 v[100:103], v[132:135], v[204:207], v[100:103]
	v_mfma_f32_16x16x32_bf16 v[96:99], v[140:143], v[204:207], v[96:99]
	s_nop 0
	s_nop 0
	v_mfma_f32_16x16x32_bf16 v[60:63], v[144:147], v[176:179], v[60:63]
	v_mfma_f32_16x16x32_bf16 v[56:59], v[152:155], v[176:179], v[56:59]
	v_mfma_f32_16x16x32_bf16 v[52:55], v[144:147], v[184:187], v[52:55]
	v_mfma_f32_16x16x32_bf16 v[48:51], v[152:155], v[184:187], v[48:51]
	v_mfma_f32_16x16x32_bf16 v[44:47], v[144:147], v[192:195], v[44:47]
	v_mfma_f32_16x16x32_bf16 v[40:43], v[152:155], v[192:195], v[40:43]
	v_mfma_f32_16x16x32_bf16 v[36:39], v[144:147], v[200:203], v[36:39]
	v_mfma_f32_16x16x32_bf16 v[32:35], v[152:155], v[200:203], v[32:35]
	v_mfma_f32_16x16x32_bf16 v[60:63], v[148:151], v[180:183], v[60:63]
	v_mfma_f32_16x16x32_bf16 v[56:59], v[156:159], v[180:183], v[56:59]
	v_mfma_f32_16x16x32_bf16 v[52:55], v[148:151], v[188:191], v[52:55]
	v_mfma_f32_16x16x32_bf16 v[48:51], v[156:159], v[188:191], v[48:51]
	v_mfma_f32_16x16x32_bf16 v[44:47], v[148:151], v[196:199], v[44:47]
	v_mfma_f32_16x16x32_bf16 v[40:43], v[156:159], v[196:199], v[40:43]
	v_mfma_f32_16x16x32_bf16 v[36:39], v[148:151], v[204:207], v[36:39]
	v_mfma_f32_16x16x32_bf16 v[32:35], v[156:159], v[204:207], v[32:35]
	s_nop 0
	s_barrier
	s_add_i32 s59, s55, s43
	v_lshl_add_u64 v[218:219], s[36:37], 0, v[162:163]
	s_mov_b32 m0, s59
	ds_read_b128 v[176:179], v216 offset:16384
	ds_read_b128 v[180:183], v216 offset:17408
	ds_read_b128 v[184:187], v216 offset:18432
	ds_read_b128 v[188:191], v216 offset:19456
	ds_read_b128 v[192:195], v216 offset:20480
	ds_read_b128 v[196:199], v216 offset:21504
	ds_read_b128 v[200:203], v216 offset:22528
	ds_read_b128 v[204:207], v216 offset:23552
	global_load_lds_dwordx4 v[218:219], off
	s_add_i32 m0, s59, 0x2000
	s_add_u32 s60, s36, 0x40000
	v_lshl_add_u64 v[220:221], s[36:37], 0, v[166:167]
	s_addc_u32 s61, s37, 0
	s_add_i32 s59, s56, s43
	global_load_lds_dwordx4 v[220:221], off
	v_lshl_add_u64 v[222:223], s[60:61], 0, v[162:163]
	s_mov_b32 m0, s59
	v_lshl_add_u64 v[224:225], s[38:39], 0, v[164:165]
	global_load_lds_dwordx4 v[222:223], off
	v_lshl_add_u64 v[222:223], s[60:61], 0, v[166:167]
	s_add_i32 m0, s59, 0x2000
	s_nop 0
	global_load_lds_dwordx4 v[222:223], off
	v_lshl_add_u64 v[222:223], s[38:39], 0, v[160:161]
	s_mov_b32 m0, s31
	s_nop 0
	global_load_lds_dwordx4 v[222:223], off
	s_mov_b32 m0, s44
	s_nop 0
	global_load_lds_dwordx4 v[224:225], off
	s_waitcnt vmcnt(8)
	s_waitcnt lgkmcnt(0)
	s_barrier
; #define PG8_STAGE(bufoff, gbase, voff) do { _Pragma("unroll") for (int _i = 0; _i < 2; ++_i) \
;         __builtin_amdgcn_global_load_lds((const unsigned*)((const char*)(gbase) + (voff)[_i]), (PG8_LAS unsigned*)(lds + (bufoff) + ldsw + _i * 8192), 16, 0, 0); } while (0)
; #define PG8_LDA(dst, b, h) do { _Pragma("unroll") for (int m = 0; m < 4; ++m) _Pragma("unroll") for (int k = 0; k < 2; ++k) dst[m][k] = *(const PG8_LAS bf16x8*)(lds + PG8_SA(b, h) + aoff + m * 2048 + k * 1024); } while (0)
; #define PG8_LDB(dst, b, h) do { _Pragma("unroll") for (int n = 0; n < 2; ++n) _Pragma("unroll") for (int k = 0; k < 2; ++k) dst[n][k] = *(const PG8_LAS bf16x8*)(lds + PG8_SB(b, h) + boff + n * 2048 + k * 1024); } while (0)
; #define PG8_MMA(ai, bj, At, Bt) do { __builtin_amdgcn_s_setprio(1); _Pragma("unroll") for (int m = 0; m < 4; ++m) _Pragma("unroll") for (int n = 0; n < 2; ++n) _Pragma("unroll") for (int k = 0; k < 2; ++k) \
;         acc[ai][bj][m][n] = __builtin_amdgcn_mfma_f32_16x16x32_bf16(Bt[n][k], At[m][k], acc[ai][bj][m][n], 0, 0, 0); __builtin_amdgcn_s_setprio(0); } while (0)
; #define PG8_BAR __builtin_amdgcn_s_barrier()
; template <class Epi, class Sched, bool ALIGN_EPI = false, bool SP2 = false>
; __device__ __forceinline__ void gemm_phase(PG8_LAS unsigned char* lds, const Gemm g, const Sched& S, const Epi& E) {
;     ...
;             if constexpr (SP2) {
;             PG8_LDB(B0, 0, 0); PG8_LDB(B1, 0, 1); PG8_SCHED; PG8_LDA(At, 0, 0); PG8_STAGE(PG8_SA(1, 1), a1 + hstep, voffA);
;             PG8_WAIT_V(8); PG8_WAIT_L(0); PG8_BAR; PG8_MMA(0, 0, At, B0); PG8_MMA(0, 1, At, B1); PG8_BAR; PG8_SCHED;
;             PG8_LDA(At, 0, 1); PG8_STAGE(PG8_SB(0, 0), b2, voffB); PG8_STAGE(PG8_SB(0, 1), b2 + hstep, voffB); PG8_STAGE(PG8_SA(0, 0), a2, voffA);
;             PG8_WAIT_V(8); PG8_WAIT_L(0); PG8_BAR; PG8_MMA(1, 0, At, B0); PG8_MMA(1, 1, At, B1); PG8_BAR; PG8_SCHED;
;             PG8_LDB(B0, 1, 0); PG8_LDB(B1, 1, 1); PG8_SCHED; PG8_LDA(At, 1, 0); PG8_STAGE(PG8_SA(0, 1), a2 + hstep, voffA);
;             PG8_WAIT_V(8); PG8_WAIT_L(0); PG8_BAR; PG8_MMA(0, 0, At, B0); PG8_MMA(0, 1, At, B1); PG8_BAR; PG8_SCHED;
;             PG8_LDA(At, 1, 1); PG8_STAGE(PG8_SB(1, 0), b3, voffB); PG8_STAGE(PG8_SB(1, 1), b3 + hstep, voffB); PG8_STAGE(PG8_SA(1, 0), a3, voffA);
;             PG8_WAIT_V(8); PG8_WAIT_L(0); PG8_BAR; PG8_MMA(1, 0, At, B0); PG8_MMA(1, 1, At, B1); PG8_BAR; PG8_SCHED;
	s_nop 0
	s_waitcnt lgkmcnt(0)
	v_mfma_f32_16x16x32_bf16 v[92:95], v[128:131], v[176:179], v[92:95]
	v_mfma_f32_16x16x32_bf16 v[88:91], v[136:139], v[176:179], v[88:91]
	v_mfma_f32_16x16x32_bf16 v[84:87], v[128:131], v[184:187], v[84:87]
	v_mfma_f32_16x16x32_bf16 v[80:83], v[136:139], v[184:187], v[80:83]
	v_mfma_f32_16x16x32_bf16 v[76:79], v[128:131], v[192:195], v[76:79]
	v_mfma_f32_16x16x32_bf16 v[72:75], v[136:139], v[192:195], v[72:75]
	v_mfma_f32_16x16x32_bf16 v[68:71], v[128:131], v[200:203], v[68:71]
	v_mfma_f32_16x16x32_bf16 v[64:67], v[136:139], v[200:203], v[64:67]
	v_mfma_f32_16x16x32_bf16 v[92:95], v[132:135], v[180:183], v[92:95]
	v_mfma_f32_16x16x32_bf16 v[88:91], v[140:143], v[180:183], v[88:91]
	v_mfma_f32_16x16x32_bf16 v[84:87], v[132:135], v[188:191], v[84:87]
	v_mfma_f32_16x16x32_bf16 v[80:83], v[140:143], v[188:191], v[80:83]
	v_mfma_f32_16x16x32_bf16 v[76:79], v[132:135], v[196:199], v[76:79]
	v_mfma_f32_16x16x32_bf16 v[72:75], v[140:143], v[196:199], v[72:75]
	v_mfma_f32_16x16x32_bf16 v[68:71], v[132:135], v[204:207], v[68:71]
	v_mfma_f32_16x16x32_bf16 v[64:67], v[140:143], v[204:207], v[64:67]
	s_nop 0
	s_nop 0
	v_mfma_f32_16x16x32_bf16 v[28:31], v[144:147], v[176:179], v[28:31]
	v_mfma_f32_16x16x32_bf16 v[24:27], v[152:155], v[176:179], v[24:27]
	v_mfma_f32_16x16x32_bf16 v[20:23], v[144:147], v[184:187], v[20:23]
	v_mfma_f32_16x16x32_bf16 v[16:19], v[152:155], v[184:187], v[16:19]
	v_mfma_f32_16x16x32_bf16 v[12:15], v[144:147], v[192:195], v[12:15]
	v_mfma_f32_16x16x32_bf16 v[8:11], v[152:155], v[192:195], v[8:11]
	v_mfma_f32_16x16x32_bf16 v[4:7], v[144:147], v[200:203], v[4:7]
	v_mfma_f32_16x16x32_bf16 v[0:3], v[152:155], v[200:203], v[0:3]
	v_mfma_f32_16x16x32_bf16 v[28:31], v[148:151], v[180:183], v[28:31]
	v_mfma_f32_16x16x32_bf16 v[24:27], v[156:159], v[180:183], v[24:27]
	v_mfma_f32_16x16x32_bf16 v[20:23], v[148:151], v[188:191], v[20:23]
	v_mfma_f32_16x16x32_bf16 v[16:19], v[156:159], v[188:191], v[16:19]
	v_mfma_f32_16x16x32_bf16 v[12:15], v[148:151], v[196:199], v[12:15]
	v_mfma_f32_16x16x32_bf16 v[8:11], v[156:159], v[196:199], v[8:11]
	v_mfma_f32_16x16x32_bf16 v[4:7], v[148:151], v[204:207], v[4:7]
	v_mfma_f32_16x16x32_bf16 v[0:3], v[156:159], v[204:207], v[0:3]
	s_nop 0
	s_barrier
	s_add_i32 s59, 0, 0x18000
	s_add_i32 s60, 0, 0x1c000
	v_add_u32_e32 v140, s59, v210
	v_add_u32_e32 v156, s60, v210
	ds_read_b128 v[128:131], v140
	ds_read_b128 v[132:135], v140 offset:1024
	ds_read_b128 v[136:139], v140 offset:2048
	ds_read_b128 v[140:143], v140 offset:3072
	ds_read_b128 v[144:147], v156
	ds_read_b128 v[148:151], v156 offset:1024
	ds_read_b128 v[152:155], v156 offset:2048
	ds_read_b128 v[156:159], v156 offset:3072
	s_add_u32 s38, s38, 0x40000
	s_addc_u32 s39, s39, 0
	s_mov_b32 m0, s45
	v_lshl_add_u64 v[226:227], s[38:39], 0, v[160:161]
	ds_read_b128 v[176:179], v216 offset:32768
	ds_read_b128 v[180:183], v216 offset:33792
	ds_read_b128 v[184:187], v216 offset:34816
	ds_read_b128 v[188:191], v216 offset:35840
	ds_read_b128 v[192:195], v216 offset:36864
	ds_read_b128 v[196:199], v216 offset:37888
	ds_read_b128 v[200:203], v216 offset:38912
	ds_read_b128 v[204:207], v216 offset:39936
	global_load_lds_dwordx4 v[226:227], off
	v_lshl_add_u64 v[226:227], s[38:39], 0, v[164:165]
	s_mov_b32 m0, s46
	s_nop 0
	global_load_lds_dwordx4 v[226:227], off
	s_waitcnt vmcnt(8)
	s_waitcnt lgkmcnt(0)
	s_barrier
	s_nop 0
	s_waitcnt lgkmcnt(0)
	v_mfma_f32_16x16x32_bf16 v[124:127], v[128:131], v[176:179], v[124:127]
	v_mfma_f32_16x16x32_bf16 v[120:123], v[136:139], v[176:179], v[120:123]
	v_mfma_f32_16x16x32_bf16 v[116:119], v[128:131], v[184:187], v[116:119]
	v_mfma_f32_16x16x32_bf16 v[112:115], v[136:139], v[184:187], v[112:115]
	v_mfma_f32_16x16x32_bf16 v[108:111], v[128:131], v[192:195], v[108:111]
	v_mfma_f32_16x16x32_bf16 v[104:107], v[136:139], v[192:195], v[104:107]
	v_mfma_f32_16x16x32_bf16 v[100:103], v[128:131], v[200:203], v[100:103]
	v_mfma_f32_16x16x32_bf16 v[96:99], v[136:139], v[200:203], v[96:99]
	v_mfma_f32_16x16x32_bf16 v[124:127], v[132:135], v[180:183], v[124:127]
	v_mfma_f32_16x16x32_bf16 v[120:123], v[140:143], v[180:183], v[120:123]
	v_mfma_f32_16x16x32_bf16 v[116:119], v[132:135], v[188:191], v[116:119]
	v_mfma_f32_16x16x32_bf16 v[112:115], v[140:143], v[188:191], v[112:115]
	v_mfma_f32_16x16x32_bf16 v[108:111], v[132:135], v[196:199], v[108:111]
	v_mfma_f32_16x16x32_bf16 v[104:107], v[140:143], v[196:199], v[104:107]
	v_mfma_f32_16x16x32_bf16 v[100:103], v[132:135], v[204:207], v[100:103]
	v_mfma_f32_16x16x32_bf16 v[96:99], v[140:143], v[204:207], v[96:99]
	s_nop 0
	s_nop 0
	v_mfma_f32_16x16x32_bf16 v[60:63], v[144:147], v[176:179], v[60:63]
	v_mfma_f32_16x16x32_bf16 v[56:59], v[152:155], v[176:179], v[56:59]
	v_mfma_f32_16x16x32_bf16 v[52:55], v[144:147], v[184:187], v[52:55]
	v_mfma_f32_16x16x32_bf16 v[48:51], v[152:155], v[184:187], v[48:51]
	v_mfma_f32_16x16x32_bf16 v[44:47], v[144:147], v[192:195], v[44:47]
	v_mfma_f32_16x16x32_bf16 v[40:43], v[152:155], v[192:195], v[40:43]
	v_mfma_f32_16x16x32_bf16 v[36:39], v[144:147], v[200:203], v[36:39]
	v_mfma_f32_16x16x32_bf16 v[32:35], v[152:155], v[200:203], v[32:35]
	v_mfma_f32_16x16x32_bf16 v[60:63], v[148:151], v[180:183], v[60:63]
	v_mfma_f32_16x16x32_bf16 v[56:59], v[156:159], v[180:183], v[56:59]
	v_mfma_f32_16x16x32_bf16 v[52:55], v[148:151], v[188:191], v[52:55]
	v_mfma_f32_16x16x32_bf16 v[48:51], v[156:159], v[188:191], v[48:51]
	v_mfma_f32_16x16x32_bf16 v[44:47], v[148:151], v[196:199], v[44:47]
	v_mfma_f32_16x16x32_bf16 v[40:43], v[156:159], v[196:199], v[40:43]
	v_mfma_f32_16x16x32_bf16 v[36:39], v[148:151], v[204:207], v[36:39]
	v_mfma_f32_16x16x32_bf16 v[32:35], v[156:159], v[204:207], v[32:35]
	s_nop 0
	s_barrier
; #define PG8_STAGE(bufoff, gbase, voff) do { _Pragma("unroll") for (int _i = 0; _i < 2; ++_i) \
;         __builtin_amdgcn_global_load_lds((const unsigned*)((const char*)(gbase) + (voff)[_i]), (PG8_LAS unsigned*)(lds + (bufoff) + ldsw + _i * 8192), 16, 0, 0); } while (0)
; #define PG8_LDA(dst, b, h) do { _Pragma("unroll") for (int m = 0; m < 4; ++m) _Pragma("unroll") for (int k = 0; k < 2; ++k) dst[m][k] = *(const PG8_LAS bf16x8*)(lds + PG8_SA(b, h) + aoff + m * 2048 + k * 1024); } while (0)
; #define PG8_LDB(dst, b, h) do { _Pragma("unroll") for (int n = 0; n < 2; ++n) _Pragma("unroll") for (int k = 0; k < 2; ++k) dst[n][k] = *(const PG8_LAS bf16x8*)(lds + PG8_SB(b, h) + boff + n * 2048 + k * 1024); } while (0)
; #define PG8_MMA(ai, bj, At, Bt) do { __builtin_amdgcn_s_setprio(1); _Pragma("unroll") for (int m = 0; m < 4; ++m) _Pragma("unroll") for (int n = 0; n < 2; ++n) _Pragma("unroll") for (int k = 0; k < 2; ++k) \
;         acc[ai][bj][m][n] = __builtin_amdgcn_mfma_f32_16x16x32_bf16(Bt[n][k], At[m][k], acc[ai][bj][m][n], 0, 0, 0); __builtin_amdgcn_s_setprio(0); } while (0)
; #define PG8_BAR __builtin_amdgcn_s_barrier()
; template <class Epi, class Sched, bool ALIGN_EPI = false, bool SP2 = false>
; __device__ __forceinline__ void gemm_phase(PG8_LAS unsigned char* lds, const Gemm g, const Sched& S, const Epi& E) {
;     ...
;             if constexpr (SP2) {
;             PG8_LDB(B0, 0, 0); PG8_LDB(B1, 0, 1); PG8_SCHED; PG8_LDA(At, 0, 0); PG8_STAGE(PG8_SA(1, 1), a1 + hstep, voffA);
;             PG8_WAIT_V(8); PG8_WAIT_L(0); PG8_BAR; PG8_MMA(0, 0, At, B0); PG8_MMA(0, 1, At, B1); PG8_BAR; PG8_SCHED;
;             PG8_LDA(At, 0, 1); PG8_STAGE(PG8_SB(0, 0), b2, voffB); PG8_STAGE(PG8_SB(0, 1), b2 + hstep, voffB); PG8_STAGE(PG8_SA(0, 0), a2, voffA);
;             PG8_WAIT_V(8); PG8_WAIT_L(0); PG8_BAR; PG8_MMA(1, 0, At, B0); PG8_MMA(1, 1, At, B1); PG8_BAR; PG8_SCHED;
;             PG8_LDB(B0, 1, 0); PG8_LDB(B1, 1, 1); PG8_SCHED; PG8_LDA(At, 1, 0); PG8_STAGE(PG8_SA(0, 1), a2 + hstep, voffA);
;             PG8_WAIT_V(8); PG8_WAIT_L(0); PG8_BAR; PG8_MMA(0, 0, At, B0); PG8_MMA(0, 1, At, B1); PG8_BAR; PG8_SCHED;
;             PG8_LDA(At, 1, 1); PG8_STAGE(PG8_SB(1, 0), b3, voffB); PG8_STAGE(PG8_SB(1, 1), b3 + hstep, voffB); PG8_STAGE(PG8_SA(1, 0), a3, voffA);
;             PG8_WAIT_V(8); PG8_WAIT_L(0); PG8_BAR; PG8_MMA(1, 0, At, B0); PG8_MMA(1, 1, At, B1); PG8_BAR; PG8_SCHED;
	s_add_i32 s38, s59, s43
	v_lshl_add_u64 v[218:219], v[218:219], 0, s[18:19]
	s_mov_b32 m0, s38
	ds_read_b128 v[176:179], v216 offset:49152
	ds_read_b128 v[180:183], v216 offset:50176
	ds_read_b128 v[184:187], v216 offset:51200
	ds_read_b128 v[188:191], v216 offset:52224
	ds_read_b128 v[192:195], v216 offset:53248
	ds_read_b128 v[196:199], v216 offset:54272
	ds_read_b128 v[200:203], v216 offset:55296
	ds_read_b128 v[204:207], v216 offset:56320
	global_load_lds_dwordx4 v[218:219], off
	s_add_i32 m0, s38, 0x2000
	s_add_u32 s36, s36, 0x40080
	v_lshl_add_u64 v[218:219], v[220:221], 0, s[18:19]
	s_addc_u32 s37, s37, 0
	s_add_i32 s38, s60, s43
	global_load_lds_dwordx4 v[218:219], off
	v_lshl_add_u64 v[218:219], s[36:37], 0, v[162:163]
	s_mov_b32 m0, s38
	s_nop 0
	global_load_lds_dwordx4 v[218:219], off
	v_lshl_add_u64 v[218:219], s[36:37], 0, v[166:167]
	s_add_i32 m0, s38, 0x2000
	s_nop 0
	global_load_lds_dwordx4 v[218:219], off
	v_lshl_add_u64 v[218:219], v[222:223], 0, s[18:19]
	s_mov_b32 m0, s50
	s_nop 0
	global_load_lds_dwordx4 v[218:219], off
	v_lshl_add_u64 v[218:219], v[224:225], 0, s[18:19]
	s_mov_b32 m0, s51
	s_nop 0
	global_load_lds_dwordx4 v[218:219], off
	s_waitcnt vmcnt(8)
	s_waitcnt lgkmcnt(0)
	s_barrier
	s_nop 0
	s_waitcnt lgkmcnt(0)
	v_mfma_f32_16x16x32_bf16 v[92:95], v[128:131], v[176:179], v[92:95]
	v_mfma_f32_16x16x32_bf16 v[88:91], v[136:139], v[176:179], v[88:91]
	v_mfma_f32_16x16x32_bf16 v[84:87], v[128:131], v[184:187], v[84:87]
	v_mfma_f32_16x16x32_bf16 v[80:83], v[136:139], v[184:187], v[80:83]
	v_mfma_f32_16x16x32_bf16 v[76:79], v[128:131], v[192:195], v[76:79]
	v_mfma_f32_16x16x32_bf16 v[72:75], v[136:139], v[192:195], v[72:75]
	v_mfma_f32_16x16x32_bf16 v[68:71], v[128:131], v[200:203], v[68:71]
	v_mfma_f32_16x16x32_bf16 v[64:67], v[136:139], v[200:203], v[64:67]
	v_mfma_f32_16x16x32_bf16 v[92:95], v[132:135], v[180:183], v[92:95]
	v_mfma_f32_16x16x32_bf16 v[88:91], v[140:143], v[180:183], v[88:91]
	v_mfma_f32_16x16x32_bf16 v[84:87], v[132:135], v[188:191], v[84:87]
	v_mfma_f32_16x16x32_bf16 v[80:83], v[140:143], v[188:191], v[80:83]
	v_mfma_f32_16x16x32_bf16 v[76:79], v[132:135], v[196:199], v[76:79]
	v_mfma_f32_16x16x32_bf16 v[72:75], v[140:143], v[196:199], v[72:75]
	v_mfma_f32_16x16x32_bf16 v[68:71], v[132:135], v[204:207], v[68:71]
	v_mfma_f32_16x16x32_bf16 v[64:67], v[140:143], v[204:207], v[64:67]
	s_nop 0
	s_nop 0
	v_mfma_f32_16x16x32_bf16 v[28:31], v[144:147], v[176:179], v[28:31]
	v_mfma_f32_16x16x32_bf16 v[24:27], v[152:155], v[176:179], v[24:27]
	v_mfma_f32_16x16x32_bf16 v[20:23], v[144:147], v[184:187], v[20:23]
	v_mfma_f32_16x16x32_bf16 v[16:19], v[152:155], v[184:187], v[16:19]
	v_mfma_f32_16x16x32_bf16 v[12:15], v[144:147], v[192:195], v[12:15]
	v_mfma_f32_16x16x32_bf16 v[8:11], v[152:155], v[192:195], v[8:11]
	v_mfma_f32_16x16x32_bf16 v[4:7], v[144:147], v[200:203], v[4:7]
	v_mfma_f32_16x16x32_bf16 v[0:3], v[152:155], v[200:203], v[0:3]
	v_mfma_f32_16x16x32_bf16 v[28:31], v[148:151], v[180:183], v[28:31]
	v_mfma_f32_16x16x32_bf16 v[24:27], v[156:159], v[180:183], v[24:27]
	v_mfma_f32_16x16x32_bf16 v[20:23], v[148:151], v[188:191], v[20:23]
	v_mfma_f32_16x16x32_bf16 v[16:19], v[156:159], v[188:191], v[16:19]
	v_mfma_f32_16x16x32_bf16 v[12:15], v[148:151], v[196:199], v[12:15]
	v_mfma_f32_16x16x32_bf16 v[8:11], v[156:159], v[196:199], v[8:11]
	v_mfma_f32_16x16x32_bf16 v[4:7], v[148:151], v[204:207], v[4:7]
	v_mfma_f32_16x16x32_bf16 v[0:3], v[156:159], v[204:207], v[0:3]
	s_nop 0
	s_barrier
	s_add_i32 s58, s58, 2
	s_add_u32 s34, s34, 0x100
	s_addc_u32 s35, s35, 0
	s_add_u32 s25, s25, 0x100
	s_addc_u32 s57, s57, 0
	s_cmp_gt_u32 s58, 13
	s_cbranch_scc0 .LBB9_665
	s_and_b64 vcc, exec, s[20:21]
	s_cbranch_vccz .LBB9_668
	s_barrier

; __device__ __forceinline__ void xcd_barrier(const XcdBarrier& b) {
;     asm volatile("s_waitcnt vmcnt(0)" ::: "memory");
;     __syncthreads();
;     if (threadIdx.x == 0) {
;         unsigned* bar = b.bar;
;         __builtin_amdgcn_s_waitcnt(0);
;         unsigned nloc = b.st[0], nx = b.st[1];
;         if (nloc == 0u) { xcd_barrier_complete(bar, b.x, nloc, nx); b.st[0] = nloc; b.st[1] = nx; }
.LBB9_706:
	s_cmp_gt_i32 s93, 6
	s_cselect_b64 s[0:1], -1, 0
	s_and_b64 s[2:3], s[8:9], s[0:1]
	s_andn2_b64 vcc, exec, s[2:3]
	s_cbranch_vccnz .LBB9_760
	s_waitcnt vmcnt(0)
	s_waitcnt vmcnt(0) lgkmcnt(0)
	s_barrier
	s_setprio 0
	s_and_saveexec_b64 s[4:5], s[80:81]
	s_cbranch_execz .LBB9_759
	s_add_i32 s2, 0, 0x24000
	v_mov_b32_e32 v0, s2
	s_waitcnt vmcnt(0) expcnt(0) lgkmcnt(0)
	ds_read_b32 v2, v0
	s_add_i32 s2, 0, 0x24004
	v_mov_b32_e32 v0, s2
	ds_read_b32 v0, v0
	s_waitcnt lgkmcnt(1)
	v_cmp_ne_u32_e32 vcc, 0, v2
	s_cbranch_vccnz .LBB9_723
	s_add_u32 s6, s90, 0x1000
	s_addc_u32 s7, s91, 0
	s_add_u32 s8, s90, 0x1100
	s_addc_u32 s9, s91, 0
	s_add_u32 s10, s90, 0x1200
	s_addc_u32 s11, s91, 0
	s_mul_i32 s18, s95, s83
	s_add_u32 s12, s90, 0x1300
	s_mul_i32 s18, s18, s94
	s_addc_u32 s13, s91, 0
	s_mov_b32 s19, 1
	v_mov_b32_e32 v16, 0
	s_branch .LBB9_711

; #define PG8_STAGE(bufoff, gbase, voff) do { _Pragma("unroll") for (int _i = 0; _i < 2; ++_i) \
;         __builtin_amdgcn_global_load_lds((const unsigned*)((const char*)(gbase) + (voff)[_i]), (PG8_LAS unsigned*)(lds + (bufoff) + ldsw + _i * 8192), 16, 0, 0); } while (0)
; #define PG8_WAIT_V(n) asm volatile("s_waitcnt vmcnt(" #n ")" ::: "memory")
; #define PG8_BAR __builtin_amdgcn_s_barrier()
;     __device__ __forceinline__ bool next(int i, pg8::Unit& u) const { if (!pg8::StaticOrder::next(i >> 1, u)) return false; u.seg = i & 1; return true; }
;     __host__ __device__ bool next(int i, Unit& u) const {
;         const long L = (long)i * G + c; if (L >= nwg) return false;
;         int wgid = (int)L; { const int q = nwg / NXCD, r = nwg % NXCD, xcd = wgid % NXCD, off = wgid / NXCD; wgid = (xcd < r ? xcd * (q + 1) : r * (q + 1) + (xcd - r) * q) + off; }
;         const int nig = WGM * nN, gid = wgid / nig, fm = gid * WGM, gsz = (nM - fm) < WGM ? (nM - fm) : WGM;
;         u.pm = fm + ((wgid % nig) % gsz); u.pn = (wgid % nig) / gsz; u.seg = 0; return true;
; template <class Epi, class Sched, bool ALIGN_EPI = false, bool SP2 = false>
; __device__ __forceinline__ void gemm_phase(PG8_LAS unsigned char* lds, const Gemm g, const Sched& S, const Epi& E) {
;     ...
;     const char* cA = PG8_UA(cur); const char* cB = PG8_UB(cur);
;     S.a_ready(cur);
;     if constexpr (SP2) {
;         PG8_STAGE(PG8_SB(0, 0), cB, voffB); PG8_STAGE(PG8_SB(0, 1), cB + hstep, voffB); PG8_STAGE(PG8_SA(0, 0), cA, voffA); PG8_STAGE(PG8_SA(0, 1), cA + hstep, voffA);
;         if (wr == 1) PG8_BAR;
;         PG8_WAIT_V(2); PG8_BAR;
;         PG8_STAGE(PG8_SB(1, 0), cB + kstep, voffB); PG8_STAGE(PG8_SA(1, 0), cA + kstep, voffA); PG8_STAGE(PG8_SB(1, 1), cB + hstep + kstep, voffB);
;         PG8_WAIT_V(6); PG8_BAR;
.LBB9_760:
	s_cmp_lt_i32 s92, 7
	s_cselect_b64 s[2:3], -1, 0
	s_and_b64 s[4:5], s[2:3], s[0:1]
	s_andn2_b64 vcc, exec, s[4:5]
	s_cbranch_vccnz .LBB9_777
	s_cmpk_gt_i32 s97, 0x57f
	v_readfirstlane_b32 s1, v208
	s_cbranch_scc1 .LBB9_777
	v_lshrrev_b32_e32 v0, 5, v208
	s_waitcnt lgkmcnt(0)
	v_and_b32_e32 v1, 4, v0
	v_lshrrev_b32_e32 v0, 1, v208
	v_bfe_u32 v2, v208, 2, 2
	v_and_b32_e32 v0, 24, v0
	v_lshlrev_b32_e32 v3, 4, v208
	v_or3_b32 v2, v1, v2, v0
	v_add_u32_e32 v1, 0x2000, v3
	v_lshrrev_b32_e32 v4, 7, v1
	s_movk_i32 s0, 0xe0
	v_and_b32_e32 v6, 32, v208
	s_add_u32 s33, s90, 0x2000000
	v_and_or_b32 v5, v4, s0, v2
	v_bitop3_b32 v10, v3, v6, 48 bitop3:0x6c
	v_and_b32_e32 v11, 64, v208
	v_bfe_u32 v12, v208, 2, 4
	s_movk_i32 s0, 0xf0
	s_addc_u32 s34, s91, 0
	v_or_b32_e32 v3, v10, v11
	v_and_or_b32 v4, v4, s0, v12
	s_add_u32 s35, s90, 0xe00000
	v_lshl_or_b32 v146, v4, 11, v3
	v_lshrrev_b32_e32 v4, 3, v208
	s_movk_i32 s0, 0x60
	s_addc_u32 s36, s91, 0
	v_and_or_b32 v2, v4, s0, v2
	s_movk_i32 s0, 0x70
	s_ashr_i32 s38, s97, 31
	v_lshl_or_b32 v148, v2, 11, v3
	v_and_or_b32 v2, v4, s0, v12
	s_lshr_b32 s0, s38, 29
	s_add_i32 s0, s97, s0
	s_lshr_b32 s3, s1, 6
	s_ashr_i32 s6, s0, 3
	s_and_b32 s0, s0, -8
	s_lshr_b32 s2, s1, 8
	s_lshl_b32 s37, s3, 10
	s_sub_i32 s0, s97, s0
	s_cmp_lt_i32 s0, 0
	s_movk_i32 s39, 0xb1
	s_cselect_b32 s7, s39, 0xb0
	s_mul_i32 s0, s7, s0
	s_add_i32 s0, s0, s6
	s_mul_hi_i32 s6, s0, 0x2e8ba2e9
	s_lshr_b32 s7, s6, 31
	s_ashr_i32 s6, s6, 5
	s_add_i32 s6, s6, s7
	s_lshl_b32 s7, s6, 3
	s_mulk_i32 s6, 0xb0
	s_sub_i32 s6, s0, s6
	s_sext_i32_i16 s0, s6
	s_bfe_u32 s0, s0, 0x3001c
	s_add_i32 s8, s6, s0
	s_sext_i32_i16 s0, s8
	s_and_b32 s8, s8, 0xfff8
	s_sub_i32 s6, s6, s8
	s_sext_i32_i16 s6, s6
	s_lshr_b32 s0, s0, 3
	s_add_i32 s24, s7, s6
	s_ashr_i32 s25, s24, 31
	s_bfe_i64 s[8:9], s[0:1], 0x100000
	s_lshl_b64 s[6:7], s[24:25], 19
	s_lshl_b64 s[8:9], s[8:9], 19
	s_add_u32 s28, s35, s8
	s_addc_u32 s29, s36, s9
	s_add_i32 s25, s37, 0
	s_add_i32 m0, s25, 0x10000
	v_lshl_or_b32 v144, v5, 11, v3
	global_load_lds_dwordx4 v148, s[28:29]
	s_add_i32 m0, s25, 0x12000
	s_add_u32 s8, s28, 0x40000
	global_load_lds_dwordx4 v144, s[28:29]
	s_addc_u32 s9, s29, 0
	s_add_i32 m0, s25, 0x14000
	v_lshl_or_b32 v150, v2, 11, v3
	global_load_lds_dwordx4 v148, s[8:9]
	s_add_i32 m0, s25, 0x16000
	s_add_u32 s26, s33, s6
	s_addc_u32 s27, s34, s7
	s_add_i32 s40, s25, 0x2000
	global_load_lds_dwordx4 v144, s[8:9]
	s_mov_b32 m0, s25
	s_add_u32 s6, s26, 0x40000
	global_load_lds_dwordx4 v150, s[26:27]
	s_mov_b32 m0, s40
	s_addc_u32 s7, s27, 0
	s_add_i32 s41, s25, 0x4000
	global_load_lds_dwordx4 v146, s[26:27]
	s_mov_b32 m0, s41
	s_add_i32 s42, s25, 0x6000
	global_load_lds_dwordx4 v150, s[6:7]
	s_mov_b32 m0, s42
	v_mov_b32_e32 v149, 0
	global_load_lds_dwordx4 v146, s[6:7]
	v_mov_b32_e32 v145, v149
	v_mov_b32_e32 v151, v149
	v_mov_b32_e32 v147, v149
	s_cmp_eq_u32 s2, 1
	s_mov_b32 s43, 0
	v_lshl_add_u64 v[8:9], s[28:29], 0, v[148:149]
	v_lshl_add_u64 v[6:7], s[28:29], 0, v[144:145]
	v_lshl_add_u64 v[2:3], s[26:27], 0, v[150:151]
	s_cselect_b64 s[6:7], -1, 0
	s_cmp_lg_u32 s2, 1
	v_lshl_add_u64 v[4:5], s[26:27], 0, v[146:147]
	s_cbranch_scc1 .LBB9_764
	s_barrier
	s_setprio 1

; #define PG8_STAGE(bufoff, gbase, voff) do { _Pragma("unroll") for (int _i = 0; _i < 2; ++_i) \
;         __builtin_amdgcn_global_load_lds((const unsigned*)((const char*)(gbase) + (voff)[_i]), (PG8_LAS unsigned*)(lds + (bufoff) + ldsw + _i * 8192), 16, 0, 0); } while (0)
; #define PG8_LDA(dst, b, h) do { _Pragma("unroll") for (int m = 0; m < 4; ++m) _Pragma("unroll") for (int k = 0; k < 2; ++k) dst[m][k] = *(const PG8_LAS bf16x8*)(lds + PG8_SA(b, h) + aoff + m * 2048 + k * 1024); } while (0)
; #define PG8_LDB(dst, b, h) do { _Pragma("unroll") for (int n = 0; n < 2; ++n) _Pragma("unroll") for (int k = 0; k < 2; ++k) dst[n][k] = *(const PG8_LAS bf16x8*)(lds + PG8_SB(b, h) + boff + n * 2048 + k * 1024); } while (0)
; #define PG8_MMA(ai, bj, At, Bt) do { __builtin_amdgcn_s_setprio(1); _Pragma("unroll") for (int m = 0; m < 4; ++m) _Pragma("unroll") for (int n = 0; n < 2; ++n) _Pragma("unroll") for (int k = 0; k < 2; ++k) \
;         acc[ai][bj][m][n] = __builtin_amdgcn_mfma_f32_16x16x32_bf16(Bt[n][k], At[m][k], acc[ai][bj][m][n], 0, 0, 0); __builtin_amdgcn_s_setprio(0); } while (0)
; #define PG8_BAR __builtin_amdgcn_s_barrier()
; template <class Epi, class Sched, bool ALIGN_EPI = false, bool SP2 = false>
; __device__ __forceinline__ void gemm_phase(PG8_LAS unsigned char* lds, const Gemm g, const Sched& S, const Epi& E) {
;     ...
;             if constexpr (SP2) {
;             PG8_LDB(B0, 0, 0); PG8_LDB(B1, 0, 1); PG8_SCHED; PG8_LDA(At, 0, 0); PG8_STAGE(PG8_SA(1, 1), a1 + hstep, voffA);
;             PG8_WAIT_V(8); PG8_WAIT_L(0); PG8_BAR; PG8_MMA(0, 0, At, B0); PG8_MMA(0, 1, At, B1); PG8_BAR; PG8_SCHED;
;             PG8_LDA(At, 0, 1); PG8_STAGE(PG8_SB(0, 0), b2, voffB); PG8_STAGE(PG8_SB(0, 1), b2 + hstep, voffB); PG8_STAGE(PG8_SA(0, 0), a2, voffA);
;             PG8_WAIT_V(8); PG8_WAIT_L(0); PG8_BAR; PG8_MMA(1, 0, At, B0); PG8_MMA(1, 1, At, B1); PG8_BAR; PG8_SCHED;
;             PG8_LDB(B0, 1, 0); PG8_LDB(B1, 1, 1); PG8_SCHED; PG8_LDA(At, 1, 0); PG8_STAGE(PG8_SA(0, 1), a2 + hstep, voffA);
;             PG8_WAIT_V(8); PG8_WAIT_L(0); PG8_BAR; PG8_MMA(0, 0, At, B0); PG8_MMA(0, 1, At, B1); PG8_BAR; PG8_SCHED;
;             PG8_LDA(At, 1, 1); PG8_STAGE(PG8_SB(1, 0), b3, voffB); PG8_STAGE(PG8_SB(1, 1), b3 + hstep, voffB); PG8_STAGE(PG8_SA(1, 0), a3, voffA);
;             PG8_WAIT_V(8); PG8_WAIT_L(0); PG8_BAR; PG8_MMA(1, 0, At, B0); PG8_MMA(1, 1, At, B1); PG8_BAR; PG8_SCHED;
.LBB9_770:
	ds_read_b128 v[88:91], v169
	ds_read_b128 v[92:95], v169 offset:1024
	ds_read_b128 v[96:99], v169 offset:2048
	ds_read_b128 v[100:103], v169 offset:3072
	ds_read_b128 v[160:163], v170
	ds_read_b128 v[174:177], v170 offset:1024
	ds_read_b128 v[178:181], v170 offset:2048
	ds_read_b128 v[182:185], v170 offset:3072
	s_add_u32 s28, s26, 0xfffc0080
	s_addc_u32 s29, s27, -1
	s_cmp_eq_u32 s57, 12
	s_cselect_b32 s31, s2, s29
	s_cselect_b32 s30, s3, s28
	s_cselect_b32 s29, s17, s56
	s_cselect_b32 s28, s19, s55
	v_lshl_add_u64 v[164:165], s[26:27], 0, v[152:153]
	s_add_i32 m0, s25, 0xc000
	ds_read_b128 v[186:189], v171
	ds_read_b128 v[190:193], v171 offset:1024
	ds_read_b128 v[194:197], v171 offset:2048
	ds_read_b128 v[198:201], v171 offset:3072
	ds_read_b128 v[202:205], v171 offset:4096
	ds_read_b128 v[210:213], v171 offset:5120
	ds_read_b128 v[214:217], v171 offset:6144
	ds_read_b128 v[218:221], v171 offset:7168
	global_load_lds_dwordx4 v[164:165], off
	v_lshl_add_u64 v[164:165], s[26:27], 0, v[154:155]
	s_add_i32 m0, s25, 0xe000
	s_nop 0
	global_load_lds_dwordx4 v[164:165], off
	s_waitcnt vmcnt(8)
	s_waitcnt lgkmcnt(0)
	s_barrier
	s_nop 0
	s_waitcnt lgkmcnt(0)
	v_mfma_f32_16x16x32_bf16 v[140:143], v[88:91], v[186:189], v[140:143]
	v_mfma_f32_16x16x32_bf16 v[136:139], v[96:99], v[186:189], v[136:139]
	v_mfma_f32_16x16x32_bf16 v[124:127], v[88:91], v[194:197], v[124:127]
	v_mfma_f32_16x16x32_bf16 v[120:123], v[96:99], v[194:197], v[120:123]
	v_mfma_f32_16x16x32_bf16 v[108:111], v[88:91], v[202:205], v[108:111]
	v_mfma_f32_16x16x32_bf16 v[104:107], v[96:99], v[202:205], v[104:107]
	v_mfma_f32_16x16x32_bf16 v[76:79], v[88:91], v[214:217], v[76:79]
	v_mfma_f32_16x16x32_bf16 v[72:75], v[96:99], v[214:217], v[72:75]
	v_mfma_f32_16x16x32_bf16 v[140:143], v[92:95], v[190:193], v[140:143]
	v_mfma_f32_16x16x32_bf16 v[136:139], v[100:103], v[190:193], v[136:139]
	v_mfma_f32_16x16x32_bf16 v[124:127], v[92:95], v[198:201], v[124:127]
	v_mfma_f32_16x16x32_bf16 v[120:123], v[100:103], v[198:201], v[120:123]
	v_mfma_f32_16x16x32_bf16 v[108:111], v[92:95], v[210:213], v[108:111]
	v_mfma_f32_16x16x32_bf16 v[104:107], v[100:103], v[210:213], v[104:107]
	v_mfma_f32_16x16x32_bf16 v[76:79], v[92:95], v[218:221], v[76:79]
	v_mfma_f32_16x16x32_bf16 v[72:75], v[100:103], v[218:221], v[72:75]
	s_nop 0
	s_nop 0
	v_mfma_f32_16x16x32_bf16 v[132:135], v[160:163], v[186:189], v[132:135]
	v_mfma_f32_16x16x32_bf16 v[128:131], v[178:181], v[186:189], v[128:131]
	v_mfma_f32_16x16x32_bf16 v[116:119], v[160:163], v[194:197], v[116:119]
	v_mfma_f32_16x16x32_bf16 v[112:115], v[178:181], v[194:197], v[112:115]
	v_mfma_f32_16x16x32_bf16 v[84:87], v[160:163], v[202:205], v[84:87]
	v_mfma_f32_16x16x32_bf16 v[80:83], v[178:181], v[202:205], v[80:83]
	v_mfma_f32_16x16x32_bf16 v[68:71], v[160:163], v[214:217], v[68:71]
	v_mfma_f32_16x16x32_bf16 v[64:67], v[178:181], v[214:217], v[64:67]
	v_mfma_f32_16x16x32_bf16 v[132:135], v[174:177], v[190:193], v[132:135]
	v_mfma_f32_16x16x32_bf16 v[128:131], v[182:185], v[190:193], v[128:131]
	v_mfma_f32_16x16x32_bf16 v[116:119], v[174:177], v[198:201], v[116:119]
	v_mfma_f32_16x16x32_bf16 v[112:115], v[182:185], v[198:201], v[112:115]
	v_mfma_f32_16x16x32_bf16 v[84:87], v[174:177], v[210:213], v[84:87]
	v_mfma_f32_16x16x32_bf16 v[80:83], v[182:185], v[210:213], v[80:83]
	v_mfma_f32_16x16x32_bf16 v[68:71], v[174:177], v[218:221], v[68:71]
	v_mfma_f32_16x16x32_bf16 v[64:67], v[182:185], v[218:221], v[64:67]
	s_nop 0
	s_barrier
	s_add_i32 s58, s50, s37
	v_lshl_add_u64 v[164:165], s[28:29], 0, v[148:149]
	s_mov_b32 m0, s58
	ds_read_b128 v[186:189], v171 offset:16384
	ds_read_b128 v[190:193], v171 offset:17408
	ds_read_b128 v[194:197], v171 offset:18432
	ds_read_b128 v[198:201], v171 offset:19456
	ds_read_b128 v[202:205], v171 offset:20480
	ds_read_b128 v[210:213], v171 offset:21504
	ds_read_b128 v[214:217], v171 offset:22528
	ds_read_b128 v[218:221], v171 offset:23552
	global_load_lds_dwordx4 v[164:165], off
	s_add_i32 m0, s58, 0x2000
	s_add_u32 s58, s28, 0x40000
	v_lshl_add_u64 v[206:207], s[28:29], 0, v[144:145]
	s_addc_u32 s59, s29, 0
	s_add_i32 s60, s51, s37
	global_load_lds_dwordx4 v[206:207], off
	v_lshl_add_u64 v[222:223], s[58:59], 0, v[148:149]
	s_mov_b32 m0, s60
	v_lshl_add_u64 v[224:225], s[30:31], 0, v[146:147]
	global_load_lds_dwordx4 v[222:223], off
	v_lshl_add_u64 v[222:223], s[58:59], 0, v[144:145]
	s_add_i32 m0, s60, 0x2000
	s_nop 0
	global_load_lds_dwordx4 v[222:223], off
	v_lshl_add_u64 v[222:223], s[30:31], 0, v[150:151]
	s_mov_b32 m0, s25
	s_nop 0
	global_load_lds_dwordx4 v[222:223], off
	s_mov_b32 m0, s40
	s_nop 0
	global_load_lds_dwordx4 v[224:225], off
	s_waitcnt vmcnt(8)
	s_waitcnt lgkmcnt(0)
	s_barrier
; #define PG8_STAGE(bufoff, gbase, voff) do { _Pragma("unroll") for (int _i = 0; _i < 2; ++_i) \
;         __builtin_amdgcn_global_load_lds((const unsigned*)((const char*)(gbase) + (voff)[_i]), (PG8_LAS unsigned*)(lds + (bufoff) + ldsw + _i * 8192), 16, 0, 0); } while (0)
; #define PG8_LDA(dst, b, h) do { _Pragma("unroll") for (int m = 0; m < 4; ++m) _Pragma("unroll") for (int k = 0; k < 2; ++k) dst[m][k] = *(const PG8_LAS bf16x8*)(lds + PG8_SA(b, h) + aoff + m * 2048 + k * 1024); } while (0)
; #define PG8_LDB(dst, b, h) do { _Pragma("unroll") for (int n = 0; n < 2; ++n) _Pragma("unroll") for (int k = 0; k < 2; ++k) dst[n][k] = *(const PG8_LAS bf16x8*)(lds + PG8_SB(b, h) + boff + n * 2048 + k * 1024); } while (0)
; #define PG8_MMA(ai, bj, At, Bt) do { __builtin_amdgcn_s_setprio(1); _Pragma("unroll") for (int m = 0; m < 4; ++m) _Pragma("unroll") for (int n = 0; n < 2; ++n) _Pragma("unroll") for (int k = 0; k < 2; ++k) \
;         acc[ai][bj][m][n] = __builtin_amdgcn_mfma_f32_16x16x32_bf16(Bt[n][k], At[m][k], acc[ai][bj][m][n], 0, 0, 0); __builtin_amdgcn_s_setprio(0); } while (0)
; #define PG8_BAR __builtin_amdgcn_s_barrier()
; template <class Epi, class Sched, bool ALIGN_EPI = false, bool SP2 = false>
; __device__ __forceinline__ void gemm_phase(PG8_LAS unsigned char* lds, const Gemm g, const Sched& S, const Epi& E) {
;     ...
;             if constexpr (SP2) {
;             PG8_LDB(B0, 0, 0); PG8_LDB(B1, 0, 1); PG8_SCHED; PG8_LDA(At, 0, 0); PG8_STAGE(PG8_SA(1, 1), a1 + hstep, voffA);
;             PG8_WAIT_V(8); PG8_WAIT_L(0); PG8_BAR; PG8_MMA(0, 0, At, B0); PG8_MMA(0, 1, At, B1); PG8_BAR; PG8_SCHED;
;             PG8_LDA(At, 0, 1); PG8_STAGE(PG8_SB(0, 0), b2, voffB); PG8_STAGE(PG8_SB(0, 1), b2 + hstep, voffB); PG8_STAGE(PG8_SA(0, 0), a2, voffA);
;             PG8_WAIT_V(8); PG8_WAIT_L(0); PG8_BAR; PG8_MMA(1, 0, At, B0); PG8_MMA(1, 1, At, B1); PG8_BAR; PG8_SCHED;
;             PG8_LDB(B0, 1, 0); PG8_LDB(B1, 1, 1); PG8_SCHED; PG8_LDA(At, 1, 0); PG8_STAGE(PG8_SA(0, 1), a2 + hstep, voffA);
;             PG8_WAIT_V(8); PG8_WAIT_L(0); PG8_BAR; PG8_MMA(0, 0, At, B0); PG8_MMA(0, 1, At, B1); PG8_BAR; PG8_SCHED;
;             PG8_LDA(At, 1, 1); PG8_STAGE(PG8_SB(1, 0), b3, voffB); PG8_STAGE(PG8_SB(1, 1), b3 + hstep, voffB); PG8_STAGE(PG8_SA(1, 0), a3, voffA);
;             PG8_WAIT_V(8); PG8_WAIT_L(0); PG8_BAR; PG8_MMA(1, 0, At, B0); PG8_MMA(1, 1, At, B1); PG8_BAR; PG8_SCHED;
	s_nop 0
	s_waitcnt lgkmcnt(0)
	v_mfma_f32_16x16x32_bf16 v[60:63], v[88:91], v[186:189], v[60:63]
	v_mfma_f32_16x16x32_bf16 v[56:59], v[96:99], v[186:189], v[56:59]
	v_mfma_f32_16x16x32_bf16 v[44:47], v[88:91], v[194:197], v[44:47]
	v_mfma_f32_16x16x32_bf16 v[40:43], v[96:99], v[194:197], v[40:43]
	v_mfma_f32_16x16x32_bf16 v[28:31], v[88:91], v[202:205], v[28:31]
	v_mfma_f32_16x16x32_bf16 v[24:27], v[96:99], v[202:205], v[24:27]
	v_mfma_f32_16x16x32_bf16 v[12:15], v[88:91], v[214:217], v[12:15]
	v_mfma_f32_16x16x32_bf16 v[8:11], v[96:99], v[214:217], v[8:11]
	v_mfma_f32_16x16x32_bf16 v[60:63], v[92:95], v[190:193], v[60:63]
	v_mfma_f32_16x16x32_bf16 v[56:59], v[100:103], v[190:193], v[56:59]
	v_mfma_f32_16x16x32_bf16 v[44:47], v[92:95], v[198:201], v[44:47]
	v_mfma_f32_16x16x32_bf16 v[40:43], v[100:103], v[198:201], v[40:43]
	v_mfma_f32_16x16x32_bf16 v[28:31], v[92:95], v[210:213], v[28:31]
	v_mfma_f32_16x16x32_bf16 v[24:27], v[100:103], v[210:213], v[24:27]
	v_mfma_f32_16x16x32_bf16 v[12:15], v[92:95], v[218:221], v[12:15]
	v_mfma_f32_16x16x32_bf16 v[8:11], v[100:103], v[218:221], v[8:11]
	s_nop 0
	s_nop 0
	v_mfma_f32_16x16x32_bf16 v[52:55], v[160:163], v[186:189], v[52:55]
	v_mfma_f32_16x16x32_bf16 v[48:51], v[178:181], v[186:189], v[48:51]
	v_mfma_f32_16x16x32_bf16 v[36:39], v[160:163], v[194:197], v[36:39]
	v_mfma_f32_16x16x32_bf16 v[32:35], v[178:181], v[194:197], v[32:35]
	v_mfma_f32_16x16x32_bf16 v[20:23], v[160:163], v[202:205], v[20:23]
	v_mfma_f32_16x16x32_bf16 v[16:19], v[178:181], v[202:205], v[16:19]
	v_mfma_f32_16x16x32_bf16 v[4:7], v[160:163], v[214:217], v[4:7]
	v_mfma_f32_16x16x32_bf16 v[0:3], v[178:181], v[214:217], v[0:3]
	v_mfma_f32_16x16x32_bf16 v[52:55], v[174:177], v[190:193], v[52:55]
	v_mfma_f32_16x16x32_bf16 v[48:51], v[182:185], v[190:193], v[48:51]
	v_mfma_f32_16x16x32_bf16 v[36:39], v[174:177], v[198:201], v[36:39]
	v_mfma_f32_16x16x32_bf16 v[32:35], v[182:185], v[198:201], v[32:35]
	v_mfma_f32_16x16x32_bf16 v[20:23], v[174:177], v[210:213], v[20:23]
	v_mfma_f32_16x16x32_bf16 v[16:19], v[182:185], v[210:213], v[16:19]
	v_mfma_f32_16x16x32_bf16 v[4:7], v[174:177], v[218:221], v[4:7]
	v_mfma_f32_16x16x32_bf16 v[0:3], v[182:185], v[218:221], v[0:3]
	s_nop 0
	s_barrier
	s_add_i32 s58, 0, 0x18000
	s_add_i32 s59, 0, 0x1c000
	v_add_u32_e32 v100, s58, v167
	v_add_u32_e32 v182, s59, v167
	ds_read_b128 v[88:91], v100
	ds_read_b128 v[92:95], v100 offset:1024
	ds_read_b128 v[96:99], v100 offset:2048
	ds_read_b128 v[100:103], v100 offset:3072
	ds_read_b128 v[160:163], v182
	ds_read_b128 v[174:177], v182 offset:1024
	ds_read_b128 v[178:181], v182 offset:2048
	ds_read_b128 v[182:185], v182 offset:3072
	s_add_u32 s30, s30, 0x40000
	s_addc_u32 s31, s31, 0
	s_mov_b32 m0, s41
	v_lshl_add_u64 v[226:227], s[30:31], 0, v[150:151]
	ds_read_b128 v[186:189], v171 offset:32768
	ds_read_b128 v[190:193], v171 offset:33792
	ds_read_b128 v[194:197], v171 offset:34816
	ds_read_b128 v[198:201], v171 offset:35840
	ds_read_b128 v[202:205], v171 offset:36864
	ds_read_b128 v[210:213], v171 offset:37888
	ds_read_b128 v[214:217], v171 offset:38912
	ds_read_b128 v[218:221], v171 offset:39936
	global_load_lds_dwordx4 v[226:227], off
	v_lshl_add_u64 v[226:227], s[30:31], 0, v[146:147]
	s_mov_b32 m0, s42
	s_nop 0
	global_load_lds_dwordx4 v[226:227], off
	s_waitcnt vmcnt(8)
	s_waitcnt lgkmcnt(0)
	s_barrier
	s_nop 0
	s_waitcnt lgkmcnt(0)
	v_mfma_f32_16x16x32_bf16 v[140:143], v[88:91], v[186:189], v[140:143]
	v_mfma_f32_16x16x32_bf16 v[136:139], v[96:99], v[186:189], v[136:139]
	v_mfma_f32_16x16x32_bf16 v[124:127], v[88:91], v[194:197], v[124:127]
	v_mfma_f32_16x16x32_bf16 v[120:123], v[96:99], v[194:197], v[120:123]
	v_mfma_f32_16x16x32_bf16 v[108:111], v[88:91], v[202:205], v[108:111]
	v_mfma_f32_16x16x32_bf16 v[104:107], v[96:99], v[202:205], v[104:107]
	v_mfma_f32_16x16x32_bf16 v[76:79], v[88:91], v[214:217], v[76:79]
	v_mfma_f32_16x16x32_bf16 v[72:75], v[96:99], v[214:217], v[72:75]
	v_mfma_f32_16x16x32_bf16 v[140:143], v[92:95], v[190:193], v[140:143]
	v_mfma_f32_16x16x32_bf16 v[136:139], v[100:103], v[190:193], v[136:139]
	v_mfma_f32_16x16x32_bf16 v[124:127], v[92:95], v[198:201], v[124:127]
	v_mfma_f32_16x16x32_bf16 v[120:123], v[100:103], v[198:201], v[120:123]
	v_mfma_f32_16x16x32_bf16 v[108:111], v[92:95], v[210:213], v[108:111]
	v_mfma_f32_16x16x32_bf16 v[104:107], v[100:103], v[210:213], v[104:107]
	v_mfma_f32_16x16x32_bf16 v[76:79], v[92:95], v[218:221], v[76:79]
	v_mfma_f32_16x16x32_bf16 v[72:75], v[100:103], v[218:221], v[72:75]
	s_nop 0
	s_nop 0
	v_mfma_f32_16x16x32_bf16 v[132:135], v[160:163], v[186:189], v[132:135]
	v_mfma_f32_16x16x32_bf16 v[128:131], v[178:181], v[186:189], v[128:131]
	v_mfma_f32_16x16x32_bf16 v[116:119], v[160:163], v[194:197], v[116:119]
	v_mfma_f32_16x16x32_bf16 v[112:115], v[178:181], v[194:197], v[112:115]
	v_mfma_f32_16x16x32_bf16 v[84:87], v[160:163], v[202:205], v[84:87]
	v_mfma_f32_16x16x32_bf16 v[80:83], v[178:181], v[202:205], v[80:83]
	v_mfma_f32_16x16x32_bf16 v[68:71], v[160:163], v[214:217], v[68:71]
	v_mfma_f32_16x16x32_bf16 v[64:67], v[178:181], v[214:217], v[64:67]
	v_mfma_f32_16x16x32_bf16 v[132:135], v[174:177], v[190:193], v[132:135]
	v_mfma_f32_16x16x32_bf16 v[128:131], v[182:185], v[190:193], v[128:131]
	v_mfma_f32_16x16x32_bf16 v[116:119], v[174:177], v[198:201], v[116:119]
	v_mfma_f32_16x16x32_bf16 v[112:115], v[182:185], v[198:201], v[112:115]
	v_mfma_f32_16x16x32_bf16 v[84:87], v[174:177], v[210:213], v[84:87]
	v_mfma_f32_16x16x32_bf16 v[80:83], v[182:185], v[210:213], v[80:83]
	v_mfma_f32_16x16x32_bf16 v[68:71], v[174:177], v[218:221], v[68:71]
	v_mfma_f32_16x16x32_bf16 v[64:67], v[182:185], v[218:221], v[64:67]
	s_nop 0
	s_barrier
; #define PG8_STAGE(bufoff, gbase, voff) do { _Pragma("unroll") for (int _i = 0; _i < 2; ++_i) \
;         __builtin_amdgcn_global_load_lds((const unsigned*)((const char*)(gbase) + (voff)[_i]), (PG8_LAS unsigned*)(lds + (bufoff) + ldsw + _i * 8192), 16, 0, 0); } while (0)
; #define PG8_LDA(dst, b, h) do { _Pragma("unroll") for (int m = 0; m < 4; ++m) _Pragma("unroll") for (int k = 0; k < 2; ++k) dst[m][k] = *(const PG8_LAS bf16x8*)(lds + PG8_SA(b, h) + aoff + m * 2048 + k * 1024); } while (0)
; #define PG8_LDB(dst, b, h) do { _Pragma("unroll") for (int n = 0; n < 2; ++n) _Pragma("unroll") for (int k = 0; k < 2; ++k) dst[n][k] = *(const PG8_LAS bf16x8*)(lds + PG8_SB(b, h) + boff + n * 2048 + k * 1024); } while (0)
; #define PG8_MMA(ai, bj, At, Bt) do { __builtin_amdgcn_s_setprio(1); _Pragma("unroll") for (int m = 0; m < 4; ++m) _Pragma("unroll") for (int n = 0; n < 2; ++n) _Pragma("unroll") for (int k = 0; k < 2; ++k) \
;         acc[ai][bj][m][n] = __builtin_amdgcn_mfma_f32_16x16x32_bf16(Bt[n][k], At[m][k], acc[ai][bj][m][n], 0, 0, 0); __builtin_amdgcn_s_setprio(0); } while (0)
; #define PG8_BAR __builtin_amdgcn_s_barrier()
; template <class Epi, class Sched, bool ALIGN_EPI = false, bool SP2 = false>
; __device__ __forceinline__ void gemm_phase(PG8_LAS unsigned char* lds, const Gemm g, const Sched& S, const Epi& E) {
;     ...
;             if constexpr (SP2) {
;             PG8_LDB(B0, 0, 0); PG8_LDB(B1, 0, 1); PG8_SCHED; PG8_LDA(At, 0, 0); PG8_STAGE(PG8_SA(1, 1), a1 + hstep, voffA);
;             PG8_WAIT_V(8); PG8_WAIT_L(0); PG8_BAR; PG8_MMA(0, 0, At, B0); PG8_MMA(0, 1, At, B1); PG8_BAR; PG8_SCHED;
;             PG8_LDA(At, 0, 1); PG8_STAGE(PG8_SB(0, 0), b2, voffB); PG8_STAGE(PG8_SB(0, 1), b2 + hstep, voffB); PG8_STAGE(PG8_SA(0, 0), a2, voffA);
;             PG8_WAIT_V(8); PG8_WAIT_L(0); PG8_BAR; PG8_MMA(1, 0, At, B0); PG8_MMA(1, 1, At, B1); PG8_BAR; PG8_SCHED;
;             PG8_LDB(B0, 1, 0); PG8_LDB(B1, 1, 1); PG8_SCHED; PG8_LDA(At, 1, 0); PG8_STAGE(PG8_SA(0, 1), a2 + hstep, voffA);
;             PG8_WAIT_V(8); PG8_WAIT_L(0); PG8_BAR; PG8_MMA(0, 0, At, B0); PG8_MMA(0, 1, At, B1); PG8_BAR; PG8_SCHED;
;             PG8_LDA(At, 1, 1); PG8_STAGE(PG8_SB(1, 0), b3, voffB); PG8_STAGE(PG8_SB(1, 1), b3 + hstep, voffB); PG8_STAGE(PG8_SA(1, 0), a3, voffA);
;             PG8_WAIT_V(8); PG8_WAIT_L(0); PG8_BAR; PG8_MMA(1, 0, At, B0); PG8_MMA(1, 1, At, B1); PG8_BAR; PG8_SCHED;
	s_add_i32 s30, s58, s37
	v_lshl_add_u64 v[164:165], v[164:165], 0, s[12:13]
	s_mov_b32 m0, s30
	ds_read_b128 v[186:189], v171 offset:49152
	ds_read_b128 v[190:193], v171 offset:50176
	ds_read_b128 v[194:197], v171 offset:51200
	ds_read_b128 v[198:201], v171 offset:52224
	ds_read_b128 v[202:205], v171 offset:53248
	ds_read_b128 v[210:213], v171 offset:54272
	ds_read_b128 v[214:217], v171 offset:55296
	ds_read_b128 v[218:221], v171 offset:56320
	global_load_lds_dwordx4 v[164:165], off
	s_add_i32 m0, s30, 0x2000
	s_add_u32 s28, s28, 0x40080
	v_lshl_add_u64 v[164:165], v[206:207], 0, s[12:13]
	s_addc_u32 s29, s29, 0
	s_add_i32 s30, s59, s37
	global_load_lds_dwordx4 v[164:165], off
	v_lshl_add_u64 v[164:165], s[28:29], 0, v[148:149]
	s_mov_b32 m0, s30
	s_nop 0
	global_load_lds_dwordx4 v[164:165], off
	v_lshl_add_u64 v[164:165], s[28:29], 0, v[144:145]
	s_add_i32 m0, s30, 0x2000
	s_nop 0
	global_load_lds_dwordx4 v[164:165], off
	v_lshl_add_u64 v[164:165], v[222:223], 0, s[12:13]
	s_mov_b32 m0, s46
	s_nop 0
	global_load_lds_dwordx4 v[164:165], off
	v_lshl_add_u64 v[164:165], v[224:225], 0, s[12:13]
	s_mov_b32 m0, s47
	s_nop 0
	global_load_lds_dwordx4 v[164:165], off
	s_waitcnt vmcnt(8)
	s_waitcnt lgkmcnt(0)
	s_barrier
	s_nop 0
	s_waitcnt lgkmcnt(0)
	v_mfma_f32_16x16x32_bf16 v[60:63], v[88:91], v[186:189], v[60:63]
	v_mfma_f32_16x16x32_bf16 v[56:59], v[96:99], v[186:189], v[56:59]
	v_mfma_f32_16x16x32_bf16 v[44:47], v[88:91], v[194:197], v[44:47]
	v_mfma_f32_16x16x32_bf16 v[40:43], v[96:99], v[194:197], v[40:43]
	v_mfma_f32_16x16x32_bf16 v[28:31], v[88:91], v[202:205], v[28:31]
	v_mfma_f32_16x16x32_bf16 v[24:27], v[96:99], v[202:205], v[24:27]
	v_mfma_f32_16x16x32_bf16 v[12:15], v[88:91], v[214:217], v[12:15]
	v_mfma_f32_16x16x32_bf16 v[8:11], v[96:99], v[214:217], v[8:11]
	v_mfma_f32_16x16x32_bf16 v[60:63], v[92:95], v[190:193], v[60:63]
	v_mfma_f32_16x16x32_bf16 v[56:59], v[100:103], v[190:193], v[56:59]
	v_mfma_f32_16x16x32_bf16 v[44:47], v[92:95], v[198:201], v[44:47]
	v_mfma_f32_16x16x32_bf16 v[40:43], v[100:103], v[198:201], v[40:43]
	v_mfma_f32_16x16x32_bf16 v[28:31], v[92:95], v[210:213], v[28:31]
	v_mfma_f32_16x16x32_bf16 v[24:27], v[100:103], v[210:213], v[24:27]
	v_mfma_f32_16x16x32_bf16 v[12:15], v[92:95], v[218:221], v[12:15]
	v_mfma_f32_16x16x32_bf16 v[8:11], v[100:103], v[218:221], v[8:11]
	s_nop 0
	s_nop 0
	v_mfma_f32_16x16x32_bf16 v[52:55], v[160:163], v[186:189], v[52:55]
	v_mfma_f32_16x16x32_bf16 v[48:51], v[178:181], v[186:189], v[48:51]
	v_mfma_f32_16x16x32_bf16 v[36:39], v[160:163], v[194:197], v[36:39]
	v_mfma_f32_16x16x32_bf16 v[32:35], v[178:181], v[194:197], v[32:35]
	v_mfma_f32_16x16x32_bf16 v[20:23], v[160:163], v[202:205], v[20:23]
	v_mfma_f32_16x16x32_bf16 v[16:19], v[178:181], v[202:205], v[16:19]
	v_mfma_f32_16x16x32_bf16 v[4:7], v[160:163], v[214:217], v[4:7]
	v_mfma_f32_16x16x32_bf16 v[0:3], v[178:181], v[214:217], v[0:3]
	v_mfma_f32_16x16x32_bf16 v[52:55], v[174:177], v[190:193], v[52:55]
	v_mfma_f32_16x16x32_bf16 v[48:51], v[182:185], v[190:193], v[48:51]
	v_mfma_f32_16x16x32_bf16 v[36:39], v[174:177], v[198:201], v[36:39]
	v_mfma_f32_16x16x32_bf16 v[32:35], v[182:185], v[198:201], v[32:35]
	v_mfma_f32_16x16x32_bf16 v[20:23], v[174:177], v[210:213], v[20:23]
	v_mfma_f32_16x16x32_bf16 v[16:19], v[182:185], v[210:213], v[16:19]
	v_mfma_f32_16x16x32_bf16 v[4:7], v[174:177], v[218:221], v[4:7]
	v_mfma_f32_16x16x32_bf16 v[0:3], v[182:185], v[218:221], v[0:3]
	s_nop 0
	s_barrier
	s_add_i32 s57, s57, 2
	s_add_u32 s26, s26, 0x100
	s_addc_u32 s27, s27, 0
	s_add_u32 s55, s55, 0x100
	s_addc_u32 s56, s56, 0
	s_cmp_gt_u32 s57, 13
	s_cbranch_scc0 .LBB9_770
	s_and_b64 vcc, exec, s[14:15]
	s_cbranch_vccz .LBB9_773
	s_barrier

; __device__ __forceinline__ unsigned xb_add(unsigned* p, unsigned v) { return __hip_atomic_fetch_add(p, v, __ATOMIC_RELAXED, __HIP_MEMORY_SCOPE_AGENT); }
; __device__ __forceinline__ void xcd_barrier(const XcdBarrier& b) {
;     asm volatile("s_waitcnt vmcnt(0)" ::: "memory");
;     __syncthreads();
;     if (threadIdx.x == 0) {
;         unsigned* bar = b.bar;
;         __builtin_amdgcn_s_waitcnt(0);
;         unsigned nloc = b.st[0], nx = b.st[1];
;         if (nloc == 0u) { xcd_barrier_complete(bar, b.x, nloc, nx); b.st[0] = nloc; b.st[1] = nx; }
;         const unsigned old = xb_add(&bar[XB_XSUB(b.x)], 1u);
;         const unsigned gen = old / nloc;
;         if (old + 1u == (gen + 1u) * nloc) {
;             __builtin_amdgcn_fence(__ATOMIC_RELEASE, "agent");
.LBB9_777:
	s_cmp_gt_i32 s93, 7
	s_cselect_b64 s[0:1], -1, 0
	s_and_b64 s[2:3], s[4:5], s[0:1]
	s_andn2_b64 vcc, exec, s[2:3]
	s_cbranch_vccnz .LBB9_831
	s_waitcnt vmcnt(0)
	s_waitcnt vmcnt(0) lgkmcnt(0)
	s_barrier
	s_setprio 0
	s_and_saveexec_b64 s[4:5], s[80:81]
	s_cbranch_execz .LBB9_830
	v_mov_b32_e32 v0, 0x24008
	ds_read_b32 v0, v0
	s_waitcnt lgkmcnt(0)
	v_readfirstlane_b32 s98, v0
	s_nop 3
	s_cmp_eq_u32 s98, 1
	s_cbranch_scc0 .Lgb6_orig
	s_and_b32 s98, s97, 63
	s_lshl_b32 s98, s98, 2
	s_add_i32 s98, s98, 0x3e00
	v_mov_b32_e32 v0, s98
	v_mov_b32_e32 v1, 1
	global_atomic_add v0, v1, s[90:91]
	buffer_inv sc1

; #define PG8_STAGE(bufoff, gbase, voff) do { _Pragma("unroll") for (int _i = 0; _i < 2; ++_i) \
;         __builtin_amdgcn_global_load_lds((const unsigned*)((const char*)(gbase) + (voff)[_i]), (PG8_LAS unsigned*)(lds + (bufoff) + ldsw + _i * 8192), 16, 0, 0); } while (0)
; #define PG8_WAIT_V(n) asm volatile("s_waitcnt vmcnt(" #n ")" ::: "memory")
; #define PG8_BAR __builtin_amdgcn_s_barrier()
; template <class Epi, class Sched, bool ALIGN_EPI = false, bool SP2 = false>
; __device__ __forceinline__ void gemm_phase(PG8_LAS unsigned char* lds, const Gemm g, const Sched& S, const Epi& E) {
;     ...
;     const char* cA = PG8_UA(cur); const char* cB = PG8_UB(cur);
;     S.a_ready(cur);
;     if constexpr (SP2) {
;         PG8_STAGE(PG8_SB(0, 0), cB, voffB); PG8_STAGE(PG8_SB(0, 1), cB + hstep, voffB); PG8_STAGE(PG8_SA(0, 0), cA, voffA); PG8_STAGE(PG8_SA(0, 1), cA + hstep, voffA);
;         if (wr == 1) PG8_BAR;
;         PG8_WAIT_V(2); PG8_BAR;
;         PG8_STAGE(PG8_SB(1, 0), cB + kstep, voffB); PG8_STAGE(PG8_SA(1, 0), cA + kstep, voffA); PG8_STAGE(PG8_SB(1, 1), cB + hstep + kstep, voffB);
;         PG8_WAIT_V(6); PG8_BAR;
.LBB9_837:
	s_add_u32 s3, s90, 0x4200000
	s_addc_u32 s20, s91, 0
	s_add_u32 s21, s90, 0x1900000
	s_addc_u32 s22, s91, 0
	s_add_i32 s1, s6, s1
	s_ashr_i32 s6, s1, 31
	s_lshr_b32 s6, s6, 27
	s_add_i32 s6, s1, s6
	s_ashr_i32 s7, s6, 5
	s_and_b32 s6, s6, 0xffe0
	v_lshrrev_b32_e32 v3, 1, v208
	s_sub_i32 s6, s1, s6
	s_waitcnt lgkmcnt(0)
	v_and_b32_e32 v10, 24, v3
	v_lshrrev_b32_e32 v3, 5, v208
	s_bfe_i32 s1, s6, 0x80000
	v_and_b32_e32 v3, 4, v3
	v_bfe_u32 v4, v208, 2, 2
	s_bfe_u32 s1, s1, 0x3000c
	v_lshlrev_b32_e32 v0, 4, v208
	v_and_b32_e32 v1, 32, v208
	v_bfe_u32 v2, v208, 2, 4
	v_or3_b32 v3, v3, v4, v10
	v_lshrrev_b32_e32 v4, 3, v208
	s_movk_i32 s5, 0x70
	s_add_i32 s8, s6, s1
	v_bitop3_b32 v8, v0, v1, 48 bitop3:0x6c
	v_and_or_b32 v5, v4, s5, v2
	s_movk_i32 s5, 0x60
	v_add_u32_e32 v0, 0x2000, v0
	s_bfe_i32 s1, s8, 0x80000
	s_and_b32 s8, s8, 0xf8
	v_and_or_b32 v4, v4, s5, v3
	v_lshrrev_b32_e32 v0, 7, v0
	s_movk_i32 s5, 0xf0
	s_sub_i32 s6, s6, s8
	v_and_or_b32 v2, v0, s5, v2
	s_movk_i32 s5, 0xe0
	s_lshl_b32 s7, s7, 3
	s_sext_i32_i16 s9, s1
	s_sext_i32_i8 s6, s6
	v_and_b32_e32 v9, 64, v208
	v_and_or_b32 v0, v0, s5, v3
	s_lshr_b32 s5, s4, 6
	s_add_i32 s37, s7, s6
	s_ashr_i32 s6, s9, 3
	s_lshr_b32 s0, s4, 8
	v_or_b32_e32 v1, v8, v9
	s_lshl_b32 s23, s5, 10
	s_lshr_b32 s1, s9, 3
	s_mul_hi_i32 s7, s6, 0x160000
	s_mul_i32 s6, s6, 0x160000
	v_lshrrev_b32_e32 v1, 1, v1
	v_mul_u32_u24_e32 v4, 0xb00, v4
	s_add_u32 s16, s21, s6
	v_or_b32_e32 v4, v4, v1
	s_addc_u32 s17, s22, s7
	s_add_i32 s24, s23, 0
	v_lshlrev_b32_e32 v138, 1, v4
	v_mul_u32_u24_e32 v0, 0xb00, v0
	s_add_i32 m0, s24, 0x10000
	v_or_b32_e32 v0, v0, v1
	global_load_lds_dwordx4 v138, s[16:17]
	s_add_i32 m0, s24, 0x12000
	v_lshlrev_b32_e32 v142, 1, v0
	s_add_u32 s6, s16, 0xb0000
	global_load_lds_dwordx4 v142, s[16:17]
	s_addc_u32 s7, s17, 0
	s_add_i32 m0, s24, 0x14000
	s_mul_i32 s10, s37, 0x160000
	global_load_lds_dwordx4 v138, s[6:7]
	s_add_i32 m0, s24, 0x16000
	v_mul_u32_u24_e32 v11, 0xb00, v5
	s_mul_hi_i32 s8, s37, 0x160000
	s_add_u32 s14, s3, s10
	v_or_b32_e32 v5, v1, v11
	v_mul_u32_u24_e32 v12, 0xb00, v2
	s_addc_u32 s15, s20, s8
	s_add_i32 s25, s24, 0x2000
	v_lshlrev_b32_e32 v136, 1, v5
	v_or_b32_e32 v2, v12, v1
	global_load_lds_dwordx4 v142, s[6:7]
	s_mov_b32 m0, s24
	s_add_u32 s6, s14, 0xb0000
	v_lshlrev_b32_e32 v140, 1, v2
	global_load_lds_dwordx4 v136, s[14:15]
	s_mov_b32 m0, s25
	s_addc_u32 s7, s15, 0
	s_add_i32 s26, s24, 0x4000
	global_load_lds_dwordx4 v140, s[14:15]
	s_mov_b32 m0, s26
	s_add_i32 s27, s24, 0x6000
	global_load_lds_dwordx4 v136, s[6:7]
	s_mov_b32 m0, s27
	v_mov_b32_e32 v139, 0
	global_load_lds_dwordx4 v140, s[6:7]
	v_mov_b32_e32 v143, v139
	v_mov_b32_e32 v137, v139
	v_mov_b32_e32 v141, v139
	s_cmp_eq_u32 s0, 1
	s_mov_b32 s28, 0
	v_lshl_add_u64 v[6:7], s[16:17], 0, v[138:139]
	v_lshl_add_u64 v[4:5], s[16:17], 0, v[142:143]
	v_lshl_add_u64 v[0:1], s[14:15], 0, v[136:137]
	s_cselect_b64 s[6:7], -1, 0
	s_cmp_lg_u32 s0, 1
	v_lshl_add_u64 v[2:3], s[14:15], 0, v[140:141]
	s_cbranch_scc1 .LBB9_839
	s_barrier
	s_setprio 1

; #define PG8_STAGE(bufoff, gbase, voff) do { _Pragma("unroll") for (int _i = 0; _i < 2; ++_i) \
;         __builtin_amdgcn_global_load_lds((const unsigned*)((const char*)(gbase) + (voff)[_i]), (PG8_LAS unsigned*)(lds + (bufoff) + ldsw + _i * 8192), 16, 0, 0); } while (0)
; #define PG8_LDA(dst, b, h) do { _Pragma("unroll") for (int m = 0; m < 4; ++m) _Pragma("unroll") for (int k = 0; k < 2; ++k) dst[m][k] = *(const PG8_LAS bf16x8*)(lds + PG8_SA(b, h) + aoff + m * 2048 + k * 1024); } while (0)
; #define PG8_LDB(dst, b, h) do { _Pragma("unroll") for (int n = 0; n < 2; ++n) _Pragma("unroll") for (int k = 0; k < 2; ++k) dst[n][k] = *(const PG8_LAS bf16x8*)(lds + PG8_SB(b, h) + boff + n * 2048 + k * 1024); } while (0)
; #define PG8_MMA(ai, bj, At, Bt) do { __builtin_amdgcn_s_setprio(1); _Pragma("unroll") for (int m = 0; m < 4; ++m) _Pragma("unroll") for (int n = 0; n < 2; ++n) _Pragma("unroll") for (int k = 0; k < 2; ++k) \
;         acc[ai][bj][m][n] = __builtin_amdgcn_mfma_f32_16x16x32_bf16(Bt[n][k], At[m][k], acc[ai][bj][m][n], 0, 0, 0); __builtin_amdgcn_s_setprio(0); } while (0)
; #define PG8_BAR __builtin_amdgcn_s_barrier()
; template <class Epi, class Sched, bool ALIGN_EPI = false, bool SP2 = false>
; __device__ __forceinline__ void gemm_phase(PG8_LAS unsigned char* lds, const Gemm g, const Sched& S, const Epi& E) {
;     ...
;             if constexpr (SP2) {
;             PG8_LDB(B0, 0, 0); PG8_LDB(B1, 0, 1); PG8_SCHED; PG8_LDA(At, 0, 0); PG8_STAGE(PG8_SA(1, 1), a1 + hstep, voffA);
;             PG8_WAIT_V(8); PG8_WAIT_L(0); PG8_BAR; PG8_MMA(0, 0, At, B0); PG8_MMA(0, 1, At, B1); PG8_BAR; PG8_SCHED;
;             PG8_LDA(At, 0, 1); PG8_STAGE(PG8_SB(0, 0), b2, voffB); PG8_STAGE(PG8_SB(0, 1), b2 + hstep, voffB); PG8_STAGE(PG8_SA(0, 0), a2, voffA);
;             PG8_WAIT_V(8); PG8_WAIT_L(0); PG8_BAR; PG8_MMA(1, 0, At, B0); PG8_MMA(1, 1, At, B1); PG8_BAR; PG8_SCHED;
;             PG8_LDB(B0, 1, 0); PG8_LDB(B1, 1, 1); PG8_SCHED; PG8_LDA(At, 1, 0); PG8_STAGE(PG8_SA(0, 1), a2 + hstep, voffA);
;             PG8_WAIT_V(8); PG8_WAIT_L(0); PG8_BAR; PG8_MMA(0, 0, At, B0); PG8_MMA(0, 1, At, B1); PG8_BAR; PG8_SCHED;
;             PG8_LDA(At, 1, 1); PG8_STAGE(PG8_SB(1, 0), b3, voffB); PG8_STAGE(PG8_SB(1, 1), b3 + hstep, voffB); PG8_STAGE(PG8_SA(1, 0), a3, voffA);
;             PG8_WAIT_V(8); PG8_WAIT_L(0); PG8_BAR; PG8_MMA(1, 0, At, B0); PG8_MMA(1, 1, At, B1); PG8_BAR; PG8_SCHED;
.LBB9_853:
	ds_read_b128 v[128:131], v173
	ds_read_b128 v[132:135], v173 offset:1024
	ds_read_b128 v[152:155], v173 offset:2048
	ds_read_b128 v[156:159], v173 offset:3072
	ds_read_b128 v[160:163], v174
	ds_read_b128 v[164:167], v174 offset:1024
	ds_read_b128 v[176:179], v174 offset:2048
	ds_read_b128 v[180:183], v174 offset:3072
	s_add_u32 s16, s14, 0xfff50080
	s_addc_u32 s17, s15, -1
	s_cmp_eq_u32 s41, 40
	s_cselect_b32 s19, s5, s17
	s_cselect_b32 s18, s4, s16
	s_cselect_b32 s17, s13, s40
	s_cselect_b32 s16, s12, s39
	v_lshl_add_u64 v[168:169], s[14:15], 0, v[144:145]
	s_add_i32 m0, s24, 0xc000
	ds_read_b128 v[184:187], v175
	ds_read_b128 v[188:191], v175 offset:1024
	ds_read_b128 v[192:195], v175 offset:2048
	ds_read_b128 v[196:199], v175 offset:3072
	ds_read_b128 v[200:203], v175 offset:4096
	ds_read_b128 v[204:207], v175 offset:5120
	ds_read_b128 v[208:211], v175 offset:6144
	ds_read_b128 v[212:215], v175 offset:7168
	global_load_lds_dwordx4 v[168:169], off
	v_lshl_add_u64 v[168:169], s[14:15], 0, v[146:147]
	s_add_i32 m0, s24, 0xe000
	s_nop 0
	global_load_lds_dwordx4 v[168:169], off
	s_waitcnt vmcnt(8)
	s_waitcnt lgkmcnt(0)
	s_barrier
	s_nop 0
	s_waitcnt lgkmcnt(0)
	v_mfma_f32_16x16x32_bf16 v[124:127], v[128:131], v[184:187], v[124:127]
	v_mfma_f32_16x16x32_bf16 v[120:123], v[152:155], v[184:187], v[120:123]
	v_mfma_f32_16x16x32_bf16 v[116:119], v[128:131], v[192:195], v[116:119]
	v_mfma_f32_16x16x32_bf16 v[112:115], v[152:155], v[192:195], v[112:115]
	v_mfma_f32_16x16x32_bf16 v[108:111], v[128:131], v[200:203], v[108:111]
	v_mfma_f32_16x16x32_bf16 v[104:107], v[152:155], v[200:203], v[104:107]
	v_mfma_f32_16x16x32_bf16 v[100:103], v[128:131], v[208:211], v[100:103]
	v_mfma_f32_16x16x32_bf16 v[96:99], v[152:155], v[208:211], v[96:99]
	v_mfma_f32_16x16x32_bf16 v[124:127], v[132:135], v[188:191], v[124:127]
	v_mfma_f32_16x16x32_bf16 v[120:123], v[156:159], v[188:191], v[120:123]
	v_mfma_f32_16x16x32_bf16 v[116:119], v[132:135], v[196:199], v[116:119]
	v_mfma_f32_16x16x32_bf16 v[112:115], v[156:159], v[196:199], v[112:115]
	v_mfma_f32_16x16x32_bf16 v[108:111], v[132:135], v[204:207], v[108:111]
	v_mfma_f32_16x16x32_bf16 v[104:107], v[156:159], v[204:207], v[104:107]
	v_mfma_f32_16x16x32_bf16 v[100:103], v[132:135], v[212:215], v[100:103]
	v_mfma_f32_16x16x32_bf16 v[96:99], v[156:159], v[212:215], v[96:99]
	s_nop 0
	s_nop 0
	v_mfma_f32_16x16x32_bf16 v[60:63], v[160:163], v[184:187], v[60:63]
	v_mfma_f32_16x16x32_bf16 v[56:59], v[176:179], v[184:187], v[56:59]
	v_mfma_f32_16x16x32_bf16 v[52:55], v[160:163], v[192:195], v[52:55]
	v_mfma_f32_16x16x32_bf16 v[48:51], v[176:179], v[192:195], v[48:51]
	v_mfma_f32_16x16x32_bf16 v[44:47], v[160:163], v[200:203], v[44:47]
	v_mfma_f32_16x16x32_bf16 v[40:43], v[176:179], v[200:203], v[40:43]
	v_mfma_f32_16x16x32_bf16 v[36:39], v[160:163], v[208:211], v[36:39]
	v_mfma_f32_16x16x32_bf16 v[32:35], v[176:179], v[208:211], v[32:35]
	v_mfma_f32_16x16x32_bf16 v[60:63], v[164:167], v[188:191], v[60:63]
	v_mfma_f32_16x16x32_bf16 v[56:59], v[180:183], v[188:191], v[56:59]
	v_mfma_f32_16x16x32_bf16 v[52:55], v[164:167], v[196:199], v[52:55]
	v_mfma_f32_16x16x32_bf16 v[48:51], v[180:183], v[196:199], v[48:51]
	v_mfma_f32_16x16x32_bf16 v[44:47], v[164:167], v[204:207], v[44:47]
	v_mfma_f32_16x16x32_bf16 v[40:43], v[180:183], v[204:207], v[40:43]
	v_mfma_f32_16x16x32_bf16 v[36:39], v[164:167], v[212:215], v[36:39]
	v_mfma_f32_16x16x32_bf16 v[32:35], v[180:183], v[212:215], v[32:35]
	s_nop 0
	s_barrier
	s_add_i32 s42, s33, s23
	v_lshl_add_u64 v[168:169], s[16:17], 0, v[138:139]
	s_mov_b32 m0, s42
	ds_read_b128 v[184:187], v175 offset:16384
	ds_read_b128 v[188:191], v175 offset:17408
	ds_read_b128 v[192:195], v175 offset:18432
	ds_read_b128 v[196:199], v175 offset:19456
	ds_read_b128 v[200:203], v175 offset:20480
	ds_read_b128 v[204:207], v175 offset:21504
	ds_read_b128 v[208:211], v175 offset:22528
	ds_read_b128 v[212:215], v175 offset:23552
	global_load_lds_dwordx4 v[168:169], off
	s_add_i32 m0, s42, 0x2000
	s_add_u32 s42, s16, 0xb0000
	v_lshl_add_u64 v[216:217], s[16:17], 0, v[142:143]
	s_addc_u32 s43, s17, 0
	s_add_i32 s44, s34, s23
	global_load_lds_dwordx4 v[216:217], off
	v_lshl_add_u64 v[218:219], s[42:43], 0, v[138:139]
	s_mov_b32 m0, s44
	v_lshl_add_u64 v[220:221], s[18:19], 0, v[140:141]
	global_load_lds_dwordx4 v[218:219], off
	v_lshl_add_u64 v[218:219], s[42:43], 0, v[142:143]
	s_add_i32 m0, s44, 0x2000
	s_nop 0
	global_load_lds_dwordx4 v[218:219], off
	v_lshl_add_u64 v[218:219], s[18:19], 0, v[136:137]
	s_mov_b32 m0, s24
	s_nop 0
	global_load_lds_dwordx4 v[218:219], off
	s_mov_b32 m0, s25
	s_nop 0
	global_load_lds_dwordx4 v[220:221], off
	s_waitcnt vmcnt(8)
	s_waitcnt lgkmcnt(0)
	s_barrier
; #define PG8_STAGE(bufoff, gbase, voff) do { _Pragma("unroll") for (int _i = 0; _i < 2; ++_i) \
;         __builtin_amdgcn_global_load_lds((const unsigned*)((const char*)(gbase) + (voff)[_i]), (PG8_LAS unsigned*)(lds + (bufoff) + ldsw + _i * 8192), 16, 0, 0); } while (0)
; #define PG8_LDA(dst, b, h) do { _Pragma("unroll") for (int m = 0; m < 4; ++m) _Pragma("unroll") for (int k = 0; k < 2; ++k) dst[m][k] = *(const PG8_LAS bf16x8*)(lds + PG8_SA(b, h) + aoff + m * 2048 + k * 1024); } while (0)
; #define PG8_LDB(dst, b, h) do { _Pragma("unroll") for (int n = 0; n < 2; ++n) _Pragma("unroll") for (int k = 0; k < 2; ++k) dst[n][k] = *(const PG8_LAS bf16x8*)(lds + PG8_SB(b, h) + boff + n * 2048 + k * 1024); } while (0)
; #define PG8_MMA(ai, bj, At, Bt) do { __builtin_amdgcn_s_setprio(1); _Pragma("unroll") for (int m = 0; m < 4; ++m) _Pragma("unroll") for (int n = 0; n < 2; ++n) _Pragma("unroll") for (int k = 0; k < 2; ++k) \
;         acc[ai][bj][m][n] = __builtin_amdgcn_mfma_f32_16x16x32_bf16(Bt[n][k], At[m][k], acc[ai][bj][m][n], 0, 0, 0); __builtin_amdgcn_s_setprio(0); } while (0)
; #define PG8_BAR __builtin_amdgcn_s_barrier()
; template <class Epi, class Sched, bool ALIGN_EPI = false, bool SP2 = false>
; __device__ __forceinline__ void gemm_phase(PG8_LAS unsigned char* lds, const Gemm g, const Sched& S, const Epi& E) {
;     ...
;             if constexpr (SP2) {
;             PG8_LDB(B0, 0, 0); PG8_LDB(B1, 0, 1); PG8_SCHED; PG8_LDA(At, 0, 0); PG8_STAGE(PG8_SA(1, 1), a1 + hstep, voffA);
;             PG8_WAIT_V(8); PG8_WAIT_L(0); PG8_BAR; PG8_MMA(0, 0, At, B0); PG8_MMA(0, 1, At, B1); PG8_BAR; PG8_SCHED;
;             PG8_LDA(At, 0, 1); PG8_STAGE(PG8_SB(0, 0), b2, voffB); PG8_STAGE(PG8_SB(0, 1), b2 + hstep, voffB); PG8_STAGE(PG8_SA(0, 0), a2, voffA);
;             PG8_WAIT_V(8); PG8_WAIT_L(0); PG8_BAR; PG8_MMA(1, 0, At, B0); PG8_MMA(1, 1, At, B1); PG8_BAR; PG8_SCHED;
;             PG8_LDB(B0, 1, 0); PG8_LDB(B1, 1, 1); PG8_SCHED; PG8_LDA(At, 1, 0); PG8_STAGE(PG8_SA(0, 1), a2 + hstep, voffA);
;             PG8_WAIT_V(8); PG8_WAIT_L(0); PG8_BAR; PG8_MMA(0, 0, At, B0); PG8_MMA(0, 1, At, B1); PG8_BAR; PG8_SCHED;
;             PG8_LDA(At, 1, 1); PG8_STAGE(PG8_SB(1, 0), b3, voffB); PG8_STAGE(PG8_SB(1, 1), b3 + hstep, voffB); PG8_STAGE(PG8_SA(1, 0), a3, voffA);
;             PG8_WAIT_V(8); PG8_WAIT_L(0); PG8_BAR; PG8_MMA(1, 0, At, B0); PG8_MMA(1, 1, At, B1); PG8_BAR; PG8_SCHED;
	s_nop 0
	s_waitcnt lgkmcnt(0)
	v_mfma_f32_16x16x32_bf16 v[92:95], v[128:131], v[184:187], v[92:95]
	v_mfma_f32_16x16x32_bf16 v[88:91], v[152:155], v[184:187], v[88:91]
	v_mfma_f32_16x16x32_bf16 v[84:87], v[128:131], v[192:195], v[84:87]
	v_mfma_f32_16x16x32_bf16 v[80:83], v[152:155], v[192:195], v[80:83]
	v_mfma_f32_16x16x32_bf16 v[76:79], v[128:131], v[200:203], v[76:79]
	v_mfma_f32_16x16x32_bf16 v[72:75], v[152:155], v[200:203], v[72:75]
	v_mfma_f32_16x16x32_bf16 v[68:71], v[128:131], v[208:211], v[68:71]
	v_mfma_f32_16x16x32_bf16 v[64:67], v[152:155], v[208:211], v[64:67]
	v_mfma_f32_16x16x32_bf16 v[92:95], v[132:135], v[188:191], v[92:95]
	v_mfma_f32_16x16x32_bf16 v[88:91], v[156:159], v[188:191], v[88:91]
	v_mfma_f32_16x16x32_bf16 v[84:87], v[132:135], v[196:199], v[84:87]
	v_mfma_f32_16x16x32_bf16 v[80:83], v[156:159], v[196:199], v[80:83]
	v_mfma_f32_16x16x32_bf16 v[76:79], v[132:135], v[204:207], v[76:79]
	v_mfma_f32_16x16x32_bf16 v[72:75], v[156:159], v[204:207], v[72:75]
	v_mfma_f32_16x16x32_bf16 v[68:71], v[132:135], v[212:215], v[68:71]
	v_mfma_f32_16x16x32_bf16 v[64:67], v[156:159], v[212:215], v[64:67]
	s_nop 0
	s_nop 0
	v_mfma_f32_16x16x32_bf16 v[28:31], v[160:163], v[184:187], v[28:31]
	v_mfma_f32_16x16x32_bf16 v[24:27], v[176:179], v[184:187], v[24:27]
	v_mfma_f32_16x16x32_bf16 v[20:23], v[160:163], v[192:195], v[20:23]
	v_mfma_f32_16x16x32_bf16 v[16:19], v[176:179], v[192:195], v[16:19]
	v_mfma_f32_16x16x32_bf16 v[12:15], v[160:163], v[200:203], v[12:15]
	v_mfma_f32_16x16x32_bf16 v[8:11], v[176:179], v[200:203], v[8:11]
	v_mfma_f32_16x16x32_bf16 v[4:7], v[160:163], v[208:211], v[4:7]
	v_mfma_f32_16x16x32_bf16 v[0:3], v[176:179], v[208:211], v[0:3]
	v_mfma_f32_16x16x32_bf16 v[28:31], v[164:167], v[188:191], v[28:31]
	v_mfma_f32_16x16x32_bf16 v[24:27], v[180:183], v[188:191], v[24:27]
	v_mfma_f32_16x16x32_bf16 v[20:23], v[164:167], v[196:199], v[20:23]
	v_mfma_f32_16x16x32_bf16 v[16:19], v[180:183], v[196:199], v[16:19]
	v_mfma_f32_16x16x32_bf16 v[12:15], v[164:167], v[204:207], v[12:15]
	v_mfma_f32_16x16x32_bf16 v[8:11], v[180:183], v[204:207], v[8:11]
	v_mfma_f32_16x16x32_bf16 v[4:7], v[164:167], v[212:215], v[4:7]
	v_mfma_f32_16x16x32_bf16 v[0:3], v[180:183], v[212:215], v[0:3]
	s_nop 0
	s_barrier
	s_add_i32 s42, 0, 0x18000
	s_add_i32 s43, 0, 0x1c000
	v_add_u32_e32 v156, s42, v171
	v_add_u32_e32 v180, s43, v171
	ds_read_b128 v[128:131], v156
	ds_read_b128 v[132:135], v156 offset:1024
	ds_read_b128 v[152:155], v156 offset:2048
	ds_read_b128 v[156:159], v156 offset:3072
	ds_read_b128 v[160:163], v180
	ds_read_b128 v[164:167], v180 offset:1024
	ds_read_b128 v[176:179], v180 offset:2048
	ds_read_b128 v[180:183], v180 offset:3072
	s_add_u32 s18, s18, 0xb0000
	s_addc_u32 s19, s19, 0
	s_mov_b32 m0, s26
	v_lshl_add_u64 v[222:223], s[18:19], 0, v[136:137]
	ds_read_b128 v[184:187], v175 offset:32768
	ds_read_b128 v[188:191], v175 offset:33792
	ds_read_b128 v[192:195], v175 offset:34816
	ds_read_b128 v[196:199], v175 offset:35840
	ds_read_b128 v[200:203], v175 offset:36864
	ds_read_b128 v[204:207], v175 offset:37888
	ds_read_b128 v[208:211], v175 offset:38912
	ds_read_b128 v[212:215], v175 offset:39936
	global_load_lds_dwordx4 v[222:223], off
	v_lshl_add_u64 v[222:223], s[18:19], 0, v[140:141]
	s_mov_b32 m0, s27
	s_nop 0
	global_load_lds_dwordx4 v[222:223], off
	s_waitcnt vmcnt(8)
	s_waitcnt lgkmcnt(0)
	s_barrier
	s_nop 0
	s_waitcnt lgkmcnt(0)
	v_mfma_f32_16x16x32_bf16 v[124:127], v[128:131], v[184:187], v[124:127]
	v_mfma_f32_16x16x32_bf16 v[120:123], v[152:155], v[184:187], v[120:123]
	v_mfma_f32_16x16x32_bf16 v[116:119], v[128:131], v[192:195], v[116:119]
	v_mfma_f32_16x16x32_bf16 v[112:115], v[152:155], v[192:195], v[112:115]
	v_mfma_f32_16x16x32_bf16 v[108:111], v[128:131], v[200:203], v[108:111]
	v_mfma_f32_16x16x32_bf16 v[104:107], v[152:155], v[200:203], v[104:107]
	v_mfma_f32_16x16x32_bf16 v[100:103], v[128:131], v[208:211], v[100:103]
	v_mfma_f32_16x16x32_bf16 v[96:99], v[152:155], v[208:211], v[96:99]
	v_mfma_f32_16x16x32_bf16 v[124:127], v[132:135], v[188:191], v[124:127]
	v_mfma_f32_16x16x32_bf16 v[120:123], v[156:159], v[188:191], v[120:123]
	v_mfma_f32_16x16x32_bf16 v[116:119], v[132:135], v[196:199], v[116:119]
	v_mfma_f32_16x16x32_bf16 v[112:115], v[156:159], v[196:199], v[112:115]
	v_mfma_f32_16x16x32_bf16 v[108:111], v[132:135], v[204:207], v[108:111]
	v_mfma_f32_16x16x32_bf16 v[104:107], v[156:159], v[204:207], v[104:107]
	v_mfma_f32_16x16x32_bf16 v[100:103], v[132:135], v[212:215], v[100:103]
	v_mfma_f32_16x16x32_bf16 v[96:99], v[156:159], v[212:215], v[96:99]
	s_nop 0
	s_nop 0
	v_mfma_f32_16x16x32_bf16 v[60:63], v[160:163], v[184:187], v[60:63]
	v_mfma_f32_16x16x32_bf16 v[56:59], v[176:179], v[184:187], v[56:59]
	v_mfma_f32_16x16x32_bf16 v[52:55], v[160:163], v[192:195], v[52:55]
	v_mfma_f32_16x16x32_bf16 v[48:51], v[176:179], v[192:195], v[48:51]
	v_mfma_f32_16x16x32_bf16 v[44:47], v[160:163], v[200:203], v[44:47]
	v_mfma_f32_16x16x32_bf16 v[40:43], v[176:179], v[200:203], v[40:43]
	v_mfma_f32_16x16x32_bf16 v[36:39], v[160:163], v[208:211], v[36:39]
	v_mfma_f32_16x16x32_bf16 v[32:35], v[176:179], v[208:211], v[32:35]
	v_mfma_f32_16x16x32_bf16 v[60:63], v[164:167], v[188:191], v[60:63]
	v_mfma_f32_16x16x32_bf16 v[56:59], v[180:183], v[188:191], v[56:59]
	v_mfma_f32_16x16x32_bf16 v[52:55], v[164:167], v[196:199], v[52:55]
	v_mfma_f32_16x16x32_bf16 v[48:51], v[180:183], v[196:199], v[48:51]
	v_mfma_f32_16x16x32_bf16 v[44:47], v[164:167], v[204:207], v[44:47]
	v_mfma_f32_16x16x32_bf16 v[40:43], v[180:183], v[204:207], v[40:43]
	v_mfma_f32_16x16x32_bf16 v[36:39], v[164:167], v[212:215], v[36:39]
	v_mfma_f32_16x16x32_bf16 v[32:35], v[180:183], v[212:215], v[32:35]
	s_nop 0
	s_barrier
; #define PG8_STAGE(bufoff, gbase, voff) do { _Pragma("unroll") for (int _i = 0; _i < 2; ++_i) \
;         __builtin_amdgcn_global_load_lds((const unsigned*)((const char*)(gbase) + (voff)[_i]), (PG8_LAS unsigned*)(lds + (bufoff) + ldsw + _i * 8192), 16, 0, 0); } while (0)
; #define PG8_LDA(dst, b, h) do { _Pragma("unroll") for (int m = 0; m < 4; ++m) _Pragma("unroll") for (int k = 0; k < 2; ++k) dst[m][k] = *(const PG8_LAS bf16x8*)(lds + PG8_SA(b, h) + aoff + m * 2048 + k * 1024); } while (0)
; #define PG8_LDB(dst, b, h) do { _Pragma("unroll") for (int n = 0; n < 2; ++n) _Pragma("unroll") for (int k = 0; k < 2; ++k) dst[n][k] = *(const PG8_LAS bf16x8*)(lds + PG8_SB(b, h) + boff + n * 2048 + k * 1024); } while (0)
; #define PG8_MMA(ai, bj, At, Bt) do { __builtin_amdgcn_s_setprio(1); _Pragma("unroll") for (int m = 0; m < 4; ++m) _Pragma("unroll") for (int n = 0; n < 2; ++n) _Pragma("unroll") for (int k = 0; k < 2; ++k) \
;         acc[ai][bj][m][n] = __builtin_amdgcn_mfma_f32_16x16x32_bf16(Bt[n][k], At[m][k], acc[ai][bj][m][n], 0, 0, 0); __builtin_amdgcn_s_setprio(0); } while (0)
; #define PG8_BAR __builtin_amdgcn_s_barrier()
; template <class Epi, class Sched, bool ALIGN_EPI = false, bool SP2 = false>
; __device__ __forceinline__ void gemm_phase(PG8_LAS unsigned char* lds, const Gemm g, const Sched& S, const Epi& E) {
;     ...
;             if constexpr (SP2) {
;             PG8_LDB(B0, 0, 0); PG8_LDB(B1, 0, 1); PG8_SCHED; PG8_LDA(At, 0, 0); PG8_STAGE(PG8_SA(1, 1), a1 + hstep, voffA);
;             PG8_WAIT_V(8); PG8_WAIT_L(0); PG8_BAR; PG8_MMA(0, 0, At, B0); PG8_MMA(0, 1, At, B1); PG8_BAR; PG8_SCHED;
;             PG8_LDA(At, 0, 1); PG8_STAGE(PG8_SB(0, 0), b2, voffB); PG8_STAGE(PG8_SB(0, 1), b2 + hstep, voffB); PG8_STAGE(PG8_SA(0, 0), a2, voffA);
;             PG8_WAIT_V(8); PG8_WAIT_L(0); PG8_BAR; PG8_MMA(1, 0, At, B0); PG8_MMA(1, 1, At, B1); PG8_BAR; PG8_SCHED;
;             PG8_LDB(B0, 1, 0); PG8_LDB(B1, 1, 1); PG8_SCHED; PG8_LDA(At, 1, 0); PG8_STAGE(PG8_SA(0, 1), a2 + hstep, voffA);
;             PG8_WAIT_V(8); PG8_WAIT_L(0); PG8_BAR; PG8_MMA(0, 0, At, B0); PG8_MMA(0, 1, At, B1); PG8_BAR; PG8_SCHED;
;             PG8_LDA(At, 1, 1); PG8_STAGE(PG8_SB(1, 0), b3, voffB); PG8_STAGE(PG8_SB(1, 1), b3 + hstep, voffB); PG8_STAGE(PG8_SA(1, 0), a3, voffA);
;             PG8_WAIT_V(8); PG8_WAIT_L(0); PG8_BAR; PG8_MMA(1, 0, At, B0); PG8_MMA(1, 1, At, B1); PG8_BAR; PG8_SCHED;
	s_add_i32 s18, s42, s23
	v_lshl_add_u64 v[168:169], v[168:169], 0, s[8:9]
	s_mov_b32 m0, s18
	ds_read_b128 v[184:187], v175 offset:49152
	ds_read_b128 v[188:191], v175 offset:50176
	ds_read_b128 v[192:195], v175 offset:51200
	ds_read_b128 v[196:199], v175 offset:52224
	ds_read_b128 v[200:203], v175 offset:53248
	ds_read_b128 v[204:207], v175 offset:54272
	ds_read_b128 v[208:211], v175 offset:55296
	ds_read_b128 v[212:215], v175 offset:56320
	global_load_lds_dwordx4 v[168:169], off
	s_add_i32 m0, s18, 0x2000
	s_add_u32 s16, s16, 0xb0080
	v_lshl_add_u64 v[168:169], v[216:217], 0, s[8:9]
	s_addc_u32 s17, s17, 0
	s_add_i32 s18, s43, s23
	global_load_lds_dwordx4 v[168:169], off
	v_lshl_add_u64 v[168:169], s[16:17], 0, v[138:139]
	s_mov_b32 m0, s18
	s_nop 0
	global_load_lds_dwordx4 v[168:169], off
	v_lshl_add_u64 v[168:169], s[16:17], 0, v[142:143]
	s_add_i32 m0, s18, 0x2000
	s_nop 0
	global_load_lds_dwordx4 v[168:169], off
	v_lshl_add_u64 v[168:169], v[218:219], 0, s[8:9]
	s_mov_b32 m0, s29
	s_nop 0
	global_load_lds_dwordx4 v[168:169], off
	v_lshl_add_u64 v[168:169], v[220:221], 0, s[8:9]
	s_mov_b32 m0, s30
	s_nop 0
	global_load_lds_dwordx4 v[168:169], off
	s_waitcnt vmcnt(8)
	s_waitcnt lgkmcnt(0)
	s_barrier
	s_nop 0
	s_waitcnt lgkmcnt(0)
	v_mfma_f32_16x16x32_bf16 v[92:95], v[128:131], v[184:187], v[92:95]
	v_mfma_f32_16x16x32_bf16 v[88:91], v[152:155], v[184:187], v[88:91]
	v_mfma_f32_16x16x32_bf16 v[84:87], v[128:131], v[192:195], v[84:87]
	v_mfma_f32_16x16x32_bf16 v[80:83], v[152:155], v[192:195], v[80:83]
	v_mfma_f32_16x16x32_bf16 v[76:79], v[128:131], v[200:203], v[76:79]
	v_mfma_f32_16x16x32_bf16 v[72:75], v[152:155], v[200:203], v[72:75]
	v_mfma_f32_16x16x32_bf16 v[68:71], v[128:131], v[208:211], v[68:71]
	v_mfma_f32_16x16x32_bf16 v[64:67], v[152:155], v[208:211], v[64:67]
	v_mfma_f32_16x16x32_bf16 v[92:95], v[132:135], v[188:191], v[92:95]
	v_mfma_f32_16x16x32_bf16 v[88:91], v[156:159], v[188:191], v[88:91]
	v_mfma_f32_16x16x32_bf16 v[84:87], v[132:135], v[196:199], v[84:87]
	v_mfma_f32_16x16x32_bf16 v[80:83], v[156:159], v[196:199], v[80:83]
	v_mfma_f32_16x16x32_bf16 v[76:79], v[132:135], v[204:207], v[76:79]
	v_mfma_f32_16x16x32_bf16 v[72:75], v[156:159], v[204:207], v[72:75]
	v_mfma_f32_16x16x32_bf16 v[68:71], v[132:135], v[212:215], v[68:71]
	v_mfma_f32_16x16x32_bf16 v[64:67], v[156:159], v[212:215], v[64:67]
	s_nop 0
	s_nop 0
	v_mfma_f32_16x16x32_bf16 v[28:31], v[160:163], v[184:187], v[28:31]
	v_mfma_f32_16x16x32_bf16 v[24:27], v[176:179], v[184:187], v[24:27]
	v_mfma_f32_16x16x32_bf16 v[20:23], v[160:163], v[192:195], v[20:23]
	v_mfma_f32_16x16x32_bf16 v[16:19], v[176:179], v[192:195], v[16:19]
	v_mfma_f32_16x16x32_bf16 v[12:15], v[160:163], v[200:203], v[12:15]
	v_mfma_f32_16x16x32_bf16 v[8:11], v[176:179], v[200:203], v[8:11]
	v_mfma_f32_16x16x32_bf16 v[4:7], v[160:163], v[208:211], v[4:7]
	v_mfma_f32_16x16x32_bf16 v[0:3], v[176:179], v[208:211], v[0:3]
	v_mfma_f32_16x16x32_bf16 v[28:31], v[164:167], v[188:191], v[28:31]
	v_mfma_f32_16x16x32_bf16 v[24:27], v[180:183], v[188:191], v[24:27]
	v_mfma_f32_16x16x32_bf16 v[20:23], v[164:167], v[196:199], v[20:23]
	v_mfma_f32_16x16x32_bf16 v[16:19], v[180:183], v[196:199], v[16:19]
	v_mfma_f32_16x16x32_bf16 v[12:15], v[164:167], v[204:207], v[12:15]
	v_mfma_f32_16x16x32_bf16 v[8:11], v[180:183], v[204:207], v[8:11]
	v_mfma_f32_16x16x32_bf16 v[4:7], v[164:167], v[212:215], v[4:7]
	v_mfma_f32_16x16x32_bf16 v[0:3], v[180:183], v[212:215], v[0:3]
	s_nop 0
	s_barrier
	s_add_i32 s41, s41, 2
	s_add_u32 s14, s14, 0x100
	s_addc_u32 s15, s15, 0
	s_add_u32 s39, s39, 0x100
	s_addc_u32 s40, s40, 0
	s_cmp_gt_u32 s41, 41
	s_cbranch_scc0 .LBB9_853
	s_and_b64 vcc, exec, s[10:11]
	s_cbranch_vccz .LBB9_856
	s_barrier
